# GEMM mainloops: per-segment s_setprio toggles removed (on top of forward-substitution rewrite + reversed phase-5 dealing)
# speedup vs baseline: 1.0243x; 1.0039x over previous
.LBB0_682:
	s_add_u32 s22, s18, 0xfff80080
	s_addc_u32 s23, s19, -1
	s_add_i32 s51, 0, 0x10000
	s_cmp_eq_u32 s50, 28
	s_cselect_b32 s29, s13, s23
	s_cselect_b32 s28, s20, s22
	s_cselect_b32 s23, s26, s49
	s_cselect_b32 s22, s38, s40
	s_add_i32 s54, 0, 0x14000
	v_add_u32_e32 v82, s51, v1
	v_add_u32_e32 v154, s54, v1
	ds_read_b128 v[66:69], v82
	ds_read_b128 v[70:73], v82 offset:1024
	ds_read_b128 v[78:81], v82 offset:2048
	ds_read_b128 v[82:85], v82 offset:3072
	ds_read_b128 v[158:161], v154
	ds_read_b128 v[162:165], v154 offset:1024
	ds_read_b128 v[166:169], v154 offset:2048
	ds_read_b128 v[170:173], v154 offset:3072
	v_lshl_add_u64 v[154:155], s[18:19], 0, v[150:151]
	s_add_i32 m0, s30, 0xc000
	ds_read_b128 v[174:177], v156
	ds_read_b128 v[178:181], v156 offset:1024
	ds_read_b128 v[182:185], v156 offset:2048
	ds_read_b128 v[186:189], v156 offset:3072
	ds_read_b128 v[196:199], v156 offset:4096
	ds_read_b128 v[200:203], v156 offset:5120
	ds_read_b128 v[204:207], v156 offset:6144
	ds_read_b128 v[208:211], v156 offset:7168
	global_load_lds_dwordx4 v[154:155], off
	v_lshl_add_u64 v[154:155], s[18:19], 0, v[152:153]
	s_add_i32 m0, s30, 0xe000
	s_nop 0
	global_load_lds_dwordx4 v[154:155], off
	s_waitcnt vmcnt(8)
	s_waitcnt lgkmcnt(0)
	s_barrier
	s_waitcnt lgkmcnt(0)
	v_mfma_f32_16x16x32_bf16 v[142:145], v[66:69], v[174:177], v[142:145]
	v_mfma_f32_16x16x32_bf16 v[138:141], v[78:81], v[174:177], v[138:141]
	v_mfma_f32_16x16x32_bf16 v[126:129], v[66:69], v[182:185], v[126:129]
	v_mfma_f32_16x16x32_bf16 v[118:121], v[78:81], v[182:185], v[118:121]
	v_mfma_f32_16x16x32_bf16 v[110:113], v[66:69], v[196:199], v[110:113]
	v_mfma_f32_16x16x32_bf16 v[102:105], v[78:81], v[196:199], v[102:105]
	v_mfma_f32_16x16x32_bf16 v[94:97], v[66:69], v[204:207], v[94:97]
	v_mfma_f32_16x16x32_bf16 v[86:89], v[78:81], v[204:207], v[86:89]
	v_mfma_f32_16x16x32_bf16 v[142:145], v[70:73], v[178:181], v[142:145]
	v_mfma_f32_16x16x32_bf16 v[138:141], v[82:85], v[178:181], v[138:141]
	v_mfma_f32_16x16x32_bf16 v[126:129], v[70:73], v[186:189], v[126:129]
	v_mfma_f32_16x16x32_bf16 v[118:121], v[82:85], v[186:189], v[118:121]
	v_mfma_f32_16x16x32_bf16 v[110:113], v[70:73], v[200:203], v[110:113]
	v_mfma_f32_16x16x32_bf16 v[102:105], v[82:85], v[200:203], v[102:105]
	v_mfma_f32_16x16x32_bf16 v[94:97], v[70:73], v[208:211], v[94:97]
	v_mfma_f32_16x16x32_bf16 v[86:89], v[82:85], v[208:211], v[86:89]
	v_mfma_f32_16x16x32_bf16 v[134:137], v[158:161], v[174:177], v[134:137]
	v_mfma_f32_16x16x32_bf16 v[130:133], v[166:169], v[174:177], v[130:133]
	v_mfma_f32_16x16x32_bf16 v[122:125], v[158:161], v[182:185], v[122:125]
	v_mfma_f32_16x16x32_bf16 v[114:117], v[166:169], v[182:185], v[114:117]
	v_mfma_f32_16x16x32_bf16 v[106:109], v[158:161], v[196:199], v[106:109]
	v_mfma_f32_16x16x32_bf16 v[98:101], v[166:169], v[196:199], v[98:101]
	v_mfma_f32_16x16x32_bf16 v[90:93], v[158:161], v[204:207], v[90:93]
	v_mfma_f32_16x16x32_bf16 v[74:77], v[166:169], v[204:207], v[74:77]
	v_mfma_f32_16x16x32_bf16 v[134:137], v[162:165], v[178:181], v[134:137]
	v_mfma_f32_16x16x32_bf16 v[130:133], v[170:173], v[178:181], v[130:133]
	v_mfma_f32_16x16x32_bf16 v[122:125], v[162:165], v[186:189], v[122:125]
	v_mfma_f32_16x16x32_bf16 v[114:117], v[170:173], v[186:189], v[114:117]
	v_mfma_f32_16x16x32_bf16 v[106:109], v[162:165], v[200:203], v[106:109]
	v_mfma_f32_16x16x32_bf16 v[98:101], v[170:173], v[200:203], v[98:101]
	v_mfma_f32_16x16x32_bf16 v[90:93], v[162:165], v[208:211], v[90:93]
	v_mfma_f32_16x16x32_bf16 v[74:77], v[170:173], v[208:211], v[74:77]
	s_barrier
	s_add_i32 s51, s51, s27
	v_lshl_add_u64 v[154:155], s[22:23], 0, v[146:147]
	s_mov_b32 m0, s51
	ds_read_b128 v[174:177], v156 offset:16384
	ds_read_b128 v[178:181], v156 offset:17408
	ds_read_b128 v[182:185], v156 offset:18432
	ds_read_b128 v[186:189], v156 offset:19456
	ds_read_b128 v[196:199], v156 offset:20480
	ds_read_b128 v[200:203], v156 offset:21504
	ds_read_b128 v[204:207], v156 offset:22528
	ds_read_b128 v[208:211], v156 offset:23552
	global_load_lds_dwordx4 v[154:155], off
	s_add_i32 m0, s51, 0x2000
	s_add_u32 s52, s22, 0x80000
	v_lshl_add_u64 v[192:193], s[22:23], 0, v[148:149]
	s_addc_u32 s53, s23, 0
	s_add_i32 s51, s54, s27
	global_load_lds_dwordx4 v[192:193], off
	v_lshl_add_u64 v[194:195], s[52:53], 0, v[146:147]
	s_mov_b32 m0, s51
	v_lshl_add_u64 v[212:213], s[28:29], 0, v[148:149]
	global_load_lds_dwordx4 v[194:195], off
	v_lshl_add_u64 v[194:195], s[52:53], 0, v[148:149]
	s_add_i32 m0, s51, 0x2000
	s_nop 0
	global_load_lds_dwordx4 v[194:195], off
	v_lshl_add_u64 v[194:195], s[28:29], 0, v[146:147]
	s_mov_b32 m0, s30
	s_nop 0
	global_load_lds_dwordx4 v[194:195], off
	s_mov_b32 m0, s31
	s_nop 0
	global_load_lds_dwordx4 v[212:213], off
	s_waitcnt vmcnt(8)
	s_waitcnt lgkmcnt(0)
	s_barrier
	s_waitcnt lgkmcnt(0)
	v_mfma_f32_16x16x32_bf16 v[62:65], v[66:69], v[174:177], v[62:65]
	v_mfma_f32_16x16x32_bf16 v[54:57], v[78:81], v[174:177], v[54:57]
	v_mfma_f32_16x16x32_bf16 v[46:49], v[66:69], v[182:185], v[46:49]
	v_mfma_f32_16x16x32_bf16 v[38:41], v[78:81], v[182:185], v[38:41]
	v_mfma_f32_16x16x32_bf16 v[26:29], v[66:69], v[196:199], v[26:29]
	v_mfma_f32_16x16x32_bf16 v[18:21], v[78:81], v[196:199], v[18:21]
	v_mfma_f32_16x16x32_bf16 v[10:13], v[66:69], v[204:207], v[10:13]
	v_mfma_f32_16x16x32_bf16 v[2:5], v[78:81], v[204:207], v[2:5]
	v_mfma_f32_16x16x32_bf16 v[62:65], v[70:73], v[178:181], v[62:65]
	v_mfma_f32_16x16x32_bf16 v[54:57], v[82:85], v[178:181], v[54:57]
	v_mfma_f32_16x16x32_bf16 v[46:49], v[70:73], v[186:189], v[46:49]
	v_mfma_f32_16x16x32_bf16 v[38:41], v[82:85], v[186:189], v[38:41]
	v_mfma_f32_16x16x32_bf16 v[26:29], v[70:73], v[200:203], v[26:29]
	v_mfma_f32_16x16x32_bf16 v[18:21], v[82:85], v[200:203], v[18:21]
	v_mfma_f32_16x16x32_bf16 v[10:13], v[70:73], v[208:211], v[10:13]
	v_mfma_f32_16x16x32_bf16 v[2:5], v[82:85], v[208:211], v[2:5]
	v_mfma_f32_16x16x32_bf16 v[58:61], v[158:161], v[174:177], v[58:61]
	v_mfma_f32_16x16x32_bf16 v[50:53], v[166:169], v[174:177], v[50:53]
	v_mfma_f32_16x16x32_bf16 v[42:45], v[158:161], v[182:185], v[42:45]
	v_mfma_f32_16x16x32_bf16 v[34:37], v[166:169], v[182:185], v[34:37]
	v_mfma_f32_16x16x32_bf16 v[30:33], v[158:161], v[196:199], v[30:33]
	v_mfma_f32_16x16x32_bf16 v[22:25], v[166:169], v[196:199], v[22:25]
	v_mfma_f32_16x16x32_bf16 v[14:17], v[158:161], v[204:207], v[14:17]
	v_mfma_f32_16x16x32_bf16 v[6:9], v[166:169], v[204:207], v[6:9]
	v_mfma_f32_16x16x32_bf16 v[58:61], v[162:165], v[178:181], v[58:61]
	v_mfma_f32_16x16x32_bf16 v[50:53], v[170:173], v[178:181], v[50:53]
	v_mfma_f32_16x16x32_bf16 v[42:45], v[162:165], v[186:189], v[42:45]
	v_mfma_f32_16x16x32_bf16 v[34:37], v[170:173], v[186:189], v[34:37]
	v_mfma_f32_16x16x32_bf16 v[30:33], v[162:165], v[200:203], v[30:33]
	v_mfma_f32_16x16x32_bf16 v[22:25], v[170:173], v[200:203], v[22:25]
	v_mfma_f32_16x16x32_bf16 v[14:17], v[162:165], v[208:211], v[14:17]
	v_mfma_f32_16x16x32_bf16 v[6:9], v[170:173], v[208:211], v[6:9]
	s_barrier
	s_add_i32 s51, 0, 0x18000
	s_add_i32 s52, 0, 0x1c000
	v_add_u32_e32 v82, s51, v1
	v_add_u32_e32 v157, s52, v1
	ds_read_b128 v[66:69], v82
	ds_read_b128 v[70:73], v82 offset:1024
	ds_read_b128 v[78:81], v82 offset:2048
	ds_read_b128 v[82:85], v82 offset:3072
	ds_read_b128 v[158:161], v157
	ds_read_b128 v[162:165], v157 offset:1024
	ds_read_b128 v[166:169], v157 offset:2048
	ds_read_b128 v[170:173], v157 offset:3072
	s_add_u32 s28, s28, 0x80000
	s_addc_u32 s29, s29, 0
	s_mov_b32 m0, s39
	v_lshl_add_u64 v[214:215], s[28:29], 0, v[146:147]
	ds_read_b128 v[174:177], v156 offset:32768
	ds_read_b128 v[178:181], v156 offset:33792
	ds_read_b128 v[182:185], v156 offset:34816
	ds_read_b128 v[186:189], v156 offset:35840
	ds_read_b128 v[196:199], v156 offset:36864
	ds_read_b128 v[200:203], v156 offset:37888
	ds_read_b128 v[204:207], v156 offset:38912
	ds_read_b128 v[208:211], v156 offset:39936
	global_load_lds_dwordx4 v[214:215], off
	v_lshl_add_u64 v[214:215], s[28:29], 0, v[148:149]
	s_mov_b32 m0, s41
	s_nop 0
	global_load_lds_dwordx4 v[214:215], off
	s_waitcnt vmcnt(8)
	s_waitcnt lgkmcnt(0)
	s_barrier
	s_waitcnt lgkmcnt(0)
	v_mfma_f32_16x16x32_bf16 v[142:145], v[66:69], v[174:177], v[142:145]
	v_mfma_f32_16x16x32_bf16 v[138:141], v[78:81], v[174:177], v[138:141]
	v_mfma_f32_16x16x32_bf16 v[126:129], v[66:69], v[182:185], v[126:129]
	v_mfma_f32_16x16x32_bf16 v[118:121], v[78:81], v[182:185], v[118:121]
	v_mfma_f32_16x16x32_bf16 v[110:113], v[66:69], v[196:199], v[110:113]
	v_mfma_f32_16x16x32_bf16 v[102:105], v[78:81], v[196:199], v[102:105]
	v_mfma_f32_16x16x32_bf16 v[94:97], v[66:69], v[204:207], v[94:97]
	v_mfma_f32_16x16x32_bf16 v[86:89], v[78:81], v[204:207], v[86:89]
	v_mfma_f32_16x16x32_bf16 v[142:145], v[70:73], v[178:181], v[142:145]
	v_mfma_f32_16x16x32_bf16 v[138:141], v[82:85], v[178:181], v[138:141]
	v_mfma_f32_16x16x32_bf16 v[126:129], v[70:73], v[186:189], v[126:129]
	v_mfma_f32_16x16x32_bf16 v[118:121], v[82:85], v[186:189], v[118:121]
	v_mfma_f32_16x16x32_bf16 v[110:113], v[70:73], v[200:203], v[110:113]
	v_mfma_f32_16x16x32_bf16 v[102:105], v[82:85], v[200:203], v[102:105]
	v_mfma_f32_16x16x32_bf16 v[94:97], v[70:73], v[208:211], v[94:97]
	v_mfma_f32_16x16x32_bf16 v[86:89], v[82:85], v[208:211], v[86:89]
	v_mfma_f32_16x16x32_bf16 v[134:137], v[158:161], v[174:177], v[134:137]
	v_mfma_f32_16x16x32_bf16 v[130:133], v[166:169], v[174:177], v[130:133]
	v_mfma_f32_16x16x32_bf16 v[122:125], v[158:161], v[182:185], v[122:125]
	v_mfma_f32_16x16x32_bf16 v[114:117], v[166:169], v[182:185], v[114:117]
	v_mfma_f32_16x16x32_bf16 v[106:109], v[158:161], v[196:199], v[106:109]
	v_mfma_f32_16x16x32_bf16 v[98:101], v[166:169], v[196:199], v[98:101]
	v_mfma_f32_16x16x32_bf16 v[90:93], v[158:161], v[204:207], v[90:93]
	v_mfma_f32_16x16x32_bf16 v[74:77], v[166:169], v[204:207], v[74:77]
	v_mfma_f32_16x16x32_bf16 v[134:137], v[162:165], v[178:181], v[134:137]
	v_mfma_f32_16x16x32_bf16 v[130:133], v[170:173], v[178:181], v[130:133]
	v_mfma_f32_16x16x32_bf16 v[122:125], v[162:165], v[186:189], v[122:125]
	v_mfma_f32_16x16x32_bf16 v[114:117], v[170:173], v[186:189], v[114:117]
	v_mfma_f32_16x16x32_bf16 v[106:109], v[162:165], v[200:203], v[106:109]
	v_mfma_f32_16x16x32_bf16 v[98:101], v[170:173], v[200:203], v[98:101]
	v_mfma_f32_16x16x32_bf16 v[90:93], v[162:165], v[208:211], v[90:93]
	v_mfma_f32_16x16x32_bf16 v[74:77], v[170:173], v[208:211], v[74:77]
	s_barrier
	s_add_i32 s28, s51, s27
	v_lshl_add_u64 v[154:155], v[154:155], 0, s[36:37]
	s_mov_b32 m0, s28
	ds_read_b128 v[174:177], v156 offset:49152
	ds_read_b128 v[178:181], v156 offset:50176
	ds_read_b128 v[182:185], v156 offset:51200
	ds_read_b128 v[186:189], v156 offset:52224
	ds_read_b128 v[196:199], v156 offset:53248
	ds_read_b128 v[200:203], v156 offset:54272
	ds_read_b128 v[204:207], v156 offset:55296
	ds_read_b128 v[208:211], v156 offset:56320
	global_load_lds_dwordx4 v[154:155], off
	s_add_i32 m0, s28, 0x2000
	s_add_u32 s22, s22, 0x80080
	v_lshl_add_u64 v[154:155], v[192:193], 0, s[36:37]
	s_addc_u32 s23, s23, 0
	s_add_i32 s28, s52, s27
	global_load_lds_dwordx4 v[154:155], off
	v_lshl_add_u64 v[154:155], s[22:23], 0, v[146:147]
	s_mov_b32 m0, s28
	s_nop 0
	global_load_lds_dwordx4 v[154:155], off
	v_lshl_add_u64 v[154:155], s[22:23], 0, v[148:149]
	s_add_i32 m0, s28, 0x2000
	s_nop 0
	global_load_lds_dwordx4 v[154:155], off
	v_lshl_add_u64 v[154:155], v[194:195], 0, s[36:37]
	s_mov_b32 m0, s46
	s_nop 0
	global_load_lds_dwordx4 v[154:155], off
	v_lshl_add_u64 v[154:155], v[212:213], 0, s[36:37]
	s_mov_b32 m0, s47
	s_nop 0
	global_load_lds_dwordx4 v[154:155], off
	s_waitcnt vmcnt(8)
	s_waitcnt lgkmcnt(0)
	s_barrier
	s_waitcnt lgkmcnt(0)
	v_mfma_f32_16x16x32_bf16 v[62:65], v[66:69], v[174:177], v[62:65]
	v_mfma_f32_16x16x32_bf16 v[54:57], v[78:81], v[174:177], v[54:57]
	v_mfma_f32_16x16x32_bf16 v[46:49], v[66:69], v[182:185], v[46:49]
	v_mfma_f32_16x16x32_bf16 v[38:41], v[78:81], v[182:185], v[38:41]
	v_mfma_f32_16x16x32_bf16 v[26:29], v[66:69], v[196:199], v[26:29]
	v_mfma_f32_16x16x32_bf16 v[18:21], v[78:81], v[196:199], v[18:21]
	v_mfma_f32_16x16x32_bf16 v[10:13], v[66:69], v[204:207], v[10:13]
	v_mfma_f32_16x16x32_bf16 v[2:5], v[78:81], v[204:207], v[2:5]
	v_mfma_f32_16x16x32_bf16 v[62:65], v[70:73], v[178:181], v[62:65]
	v_mfma_f32_16x16x32_bf16 v[54:57], v[82:85], v[178:181], v[54:57]
	v_mfma_f32_16x16x32_bf16 v[46:49], v[70:73], v[186:189], v[46:49]
	v_mfma_f32_16x16x32_bf16 v[38:41], v[82:85], v[186:189], v[38:41]
	v_mfma_f32_16x16x32_bf16 v[26:29], v[70:73], v[200:203], v[26:29]
	v_mfma_f32_16x16x32_bf16 v[18:21], v[82:85], v[200:203], v[18:21]
	v_mfma_f32_16x16x32_bf16 v[10:13], v[70:73], v[208:211], v[10:13]
	v_mfma_f32_16x16x32_bf16 v[2:5], v[82:85], v[208:211], v[2:5]
	v_mfma_f32_16x16x32_bf16 v[58:61], v[158:161], v[174:177], v[58:61]
	v_mfma_f32_16x16x32_bf16 v[50:53], v[166:169], v[174:177], v[50:53]
	v_mfma_f32_16x16x32_bf16 v[42:45], v[158:161], v[182:185], v[42:45]
	v_mfma_f32_16x16x32_bf16 v[34:37], v[166:169], v[182:185], v[34:37]
	v_mfma_f32_16x16x32_bf16 v[30:33], v[158:161], v[196:199], v[30:33]
	v_mfma_f32_16x16x32_bf16 v[22:25], v[166:169], v[196:199], v[22:25]
	v_mfma_f32_16x16x32_bf16 v[14:17], v[158:161], v[204:207], v[14:17]
	v_mfma_f32_16x16x32_bf16 v[6:9], v[166:169], v[204:207], v[6:9]
	v_mfma_f32_16x16x32_bf16 v[58:61], v[162:165], v[178:181], v[58:61]
	v_mfma_f32_16x16x32_bf16 v[50:53], v[170:173], v[178:181], v[50:53]
	v_mfma_f32_16x16x32_bf16 v[42:45], v[162:165], v[186:189], v[42:45]
	v_mfma_f32_16x16x32_bf16 v[34:37], v[170:173], v[186:189], v[34:37]
	v_mfma_f32_16x16x32_bf16 v[30:33], v[162:165], v[200:203], v[30:33]
	v_mfma_f32_16x16x32_bf16 v[22:25], v[170:173], v[200:203], v[22:25]
	v_mfma_f32_16x16x32_bf16 v[14:17], v[162:165], v[208:211], v[14:17]
	v_mfma_f32_16x16x32_bf16 v[6:9], v[170:173], v[208:211], v[6:9]
	s_barrier
	s_add_i32 s50, s50, 2
	s_add_u32 s18, s18, 0x100
	s_addc_u32 s19, s19, 0
	s_add_u32 s40, s40, 0x100
	s_addc_u32 s49, s49, 0
	s_cmp_gt_u32 s50, 29
	s_cbranch_scc0 .LBB0_682
	s_and_b64 vcc, exec, s[10:11]
	s_cbranch_vccz .LBB0_685
	s_barrier

.LBB0_868:
	s_add_u32 s6, s18, 0x100
	s_addc_u32 s7, s19, 0
	s_add_i32 s40, 0, 0x10000
	s_cmpk_eq_i32 s38, 0x54
	s_cselect_b32 s29, s15, s7
	s_cselect_b32 s28, s14, s6
	s_cselect_b32 s23, s17, s26
	s_cselect_b32 s22, s16, s20
	s_add_i32 s51, 0, 0x14000
	v_add_u32_e32 v74, s40, v1
	v_add_u32_e32 v94, s51, v1
	ds_read_b128 v[58:61], v74
	ds_read_b128 v[62:65], v74 offset:1024
	ds_read_b128 v[70:73], v74 offset:2048
	ds_read_b128 v[74:77], v74 offset:3072
	ds_read_b128 v[78:81], v94
	ds_read_b128 v[86:89], v94 offset:1024
	ds_read_b128 v[90:93], v94 offset:2048
	ds_read_b128 v[94:97], v94 offset:3072
	v_lshl_add_u64 v[188:189], s[18:19], 0, v[180:181]
	s_add_i32 m0, s31, 0xc000
	ds_read_b128 v[162:165], v206
	ds_read_b128 v[166:169], v206 offset:1024
	ds_read_b128 v[170:173], v206 offset:2048
	ds_read_b128 v[174:177], v206 offset:3072
	ds_read_b128 v[184:187], v206 offset:4096
	ds_read_b128 v[196:199], v206 offset:5120
	ds_read_b128 v[200:203], v206 offset:6144
	ds_read_b128 v[208:211], v206 offset:7168
	global_load_lds_dwordx4 v[188:189], off
	v_lshl_add_u64 v[188:189], s[18:19], 0, v[182:183]
	s_add_i32 m0, s31, 0xe000
	s_nop 0
	global_load_lds_dwordx4 v[188:189], off
	s_waitcnt vmcnt(8)
	s_waitcnt lgkmcnt(0)
	s_barrier
	s_waitcnt lgkmcnt(0)
	v_mfma_f32_16x16x32_bf16 v[158:161], v[58:61], v[162:165], v[158:161]
	v_mfma_f32_16x16x32_bf16 v[154:157], v[70:73], v[162:165], v[154:157]
	v_mfma_f32_16x16x32_bf16 v[142:145], v[58:61], v[170:173], v[142:145]
	v_mfma_f32_16x16x32_bf16 v[138:141], v[70:73], v[170:173], v[138:141]
	v_mfma_f32_16x16x32_bf16 v[126:129], v[58:61], v[184:187], v[126:129]
	v_mfma_f32_16x16x32_bf16 v[122:125], v[70:73], v[184:187], v[122:125]
	v_mfma_f32_16x16x32_bf16 v[110:113], v[58:61], v[200:203], v[110:113]
	v_mfma_f32_16x16x32_bf16 v[106:109], v[70:73], v[200:203], v[106:109]
	v_mfma_f32_16x16x32_bf16 v[158:161], v[62:65], v[166:169], v[158:161]
	v_mfma_f32_16x16x32_bf16 v[154:157], v[74:77], v[166:169], v[154:157]
	v_mfma_f32_16x16x32_bf16 v[142:145], v[62:65], v[174:177], v[142:145]
	v_mfma_f32_16x16x32_bf16 v[138:141], v[74:77], v[174:177], v[138:141]
	v_mfma_f32_16x16x32_bf16 v[126:129], v[62:65], v[196:199], v[126:129]
	v_mfma_f32_16x16x32_bf16 v[122:125], v[74:77], v[196:199], v[122:125]
	v_mfma_f32_16x16x32_bf16 v[110:113], v[62:65], v[208:211], v[110:113]
	v_mfma_f32_16x16x32_bf16 v[106:109], v[74:77], v[208:211], v[106:109]
	v_mfma_f32_16x16x32_bf16 v[150:153], v[78:81], v[162:165], v[150:153]
	v_mfma_f32_16x16x32_bf16 v[146:149], v[90:93], v[162:165], v[146:149]
	v_mfma_f32_16x16x32_bf16 v[134:137], v[78:81], v[170:173], v[134:137]
	v_mfma_f32_16x16x32_bf16 v[130:133], v[90:93], v[170:173], v[130:133]
	v_mfma_f32_16x16x32_bf16 v[118:121], v[78:81], v[184:187], v[118:121]
	v_mfma_f32_16x16x32_bf16 v[114:117], v[90:93], v[184:187], v[114:117]
	v_mfma_f32_16x16x32_bf16 v[102:105], v[78:81], v[200:203], v[102:105]
	v_mfma_f32_16x16x32_bf16 v[98:101], v[90:93], v[200:203], v[98:101]
	v_mfma_f32_16x16x32_bf16 v[150:153], v[86:89], v[166:169], v[150:153]
	v_mfma_f32_16x16x32_bf16 v[146:149], v[94:97], v[166:169], v[146:149]
	v_mfma_f32_16x16x32_bf16 v[134:137], v[86:89], v[174:177], v[134:137]
	v_mfma_f32_16x16x32_bf16 v[130:133], v[94:97], v[174:177], v[130:133]
	v_mfma_f32_16x16x32_bf16 v[118:121], v[86:89], v[196:199], v[118:121]
	v_mfma_f32_16x16x32_bf16 v[114:117], v[94:97], v[196:199], v[114:117]
	v_mfma_f32_16x16x32_bf16 v[102:105], v[86:89], v[208:211], v[102:105]
	v_mfma_f32_16x16x32_bf16 v[98:101], v[94:97], v[208:211], v[98:101]
	s_barrier
	s_add_i32 s18, s40, s30
	v_lshl_add_u64 v[188:189], s[22:23], 0, v[190:191]
	s_mov_b32 m0, s18
	ds_read_b128 v[162:165], v206 offset:16384
	ds_read_b128 v[166:169], v206 offset:17408
	ds_read_b128 v[170:173], v206 offset:18432
	ds_read_b128 v[174:177], v206 offset:19456
	ds_read_b128 v[184:187], v206 offset:20480
	ds_read_b128 v[196:199], v206 offset:21504
	ds_read_b128 v[200:203], v206 offset:22528
	ds_read_b128 v[208:211], v206 offset:23552
	global_load_lds_dwordx4 v[188:189], off
	s_add_i32 m0, s18, 0x2000
	s_add_u32 s18, s22, 0x160000
	v_lshl_add_u64 v[192:193], s[22:23], 0, v[178:179]
	s_addc_u32 s19, s23, 0
	s_add_i32 s40, s51, s30
	global_load_lds_dwordx4 v[192:193], off
	v_lshl_add_u64 v[194:195], s[18:19], 0, v[190:191]
	s_mov_b32 m0, s40
	v_lshl_add_u64 v[204:205], s[28:29], 0, v[178:179]
	global_load_lds_dwordx4 v[194:195], off
	v_lshl_add_u64 v[194:195], s[18:19], 0, v[178:179]
	s_add_i32 m0, s40, 0x2000
	s_nop 0
	global_load_lds_dwordx4 v[194:195], off
	v_lshl_add_u64 v[194:195], s[28:29], 0, v[190:191]
	s_mov_b32 m0, s31
	s_nop 0
	global_load_lds_dwordx4 v[194:195], off
	s_mov_b32 m0, s39
	s_nop 0
	global_load_lds_dwordx4 v[204:205], off
	s_waitcnt vmcnt(8)
	s_waitcnt lgkmcnt(0)
	s_barrier
	s_waitcnt lgkmcnt(0)
	v_mfma_f32_16x16x32_bf16 v[82:85], v[58:61], v[162:165], v[82:85]
	v_mfma_f32_16x16x32_bf16 v[66:69], v[70:73], v[162:165], v[66:69]
	v_mfma_f32_16x16x32_bf16 v[46:49], v[58:61], v[170:173], v[46:49]
	v_mfma_f32_16x16x32_bf16 v[42:45], v[70:73], v[170:173], v[42:45]
	v_mfma_f32_16x16x32_bf16 v[26:29], v[58:61], v[184:187], v[26:29]
	v_mfma_f32_16x16x32_bf16 v[18:21], v[70:73], v[184:187], v[18:21]
	v_mfma_f32_16x16x32_bf16 v[6:9], v[58:61], v[200:203], v[6:9]
	v_mfma_f32_16x16x32_bf16 v[2:5], v[70:73], v[200:203], v[2:5]
	v_mfma_f32_16x16x32_bf16 v[82:85], v[62:65], v[166:169], v[82:85]
	v_mfma_f32_16x16x32_bf16 v[66:69], v[74:77], v[166:169], v[66:69]
	v_mfma_f32_16x16x32_bf16 v[46:49], v[62:65], v[174:177], v[46:49]
	v_mfma_f32_16x16x32_bf16 v[42:45], v[74:77], v[174:177], v[42:45]
	v_mfma_f32_16x16x32_bf16 v[26:29], v[62:65], v[196:199], v[26:29]
	v_mfma_f32_16x16x32_bf16 v[18:21], v[74:77], v[196:199], v[18:21]
	v_mfma_f32_16x16x32_bf16 v[6:9], v[62:65], v[208:211], v[6:9]
	v_mfma_f32_16x16x32_bf16 v[2:5], v[74:77], v[208:211], v[2:5]
	v_mfma_f32_16x16x32_bf16 v[54:57], v[78:81], v[162:165], v[54:57]
	v_mfma_f32_16x16x32_bf16 v[50:53], v[90:93], v[162:165], v[50:53]
	v_mfma_f32_16x16x32_bf16 v[38:41], v[78:81], v[170:173], v[38:41]
	v_mfma_f32_16x16x32_bf16 v[34:37], v[90:93], v[170:173], v[34:37]
	v_mfma_f32_16x16x32_bf16 v[30:33], v[78:81], v[184:187], v[30:33]
	v_mfma_f32_16x16x32_bf16 v[22:25], v[90:93], v[184:187], v[22:25]
	v_mfma_f32_16x16x32_bf16 v[14:17], v[78:81], v[200:203], v[14:17]
	v_mfma_f32_16x16x32_bf16 v[10:13], v[90:93], v[200:203], v[10:13]
	v_mfma_f32_16x16x32_bf16 v[54:57], v[86:89], v[166:169], v[54:57]
	v_mfma_f32_16x16x32_bf16 v[50:53], v[94:97], v[166:169], v[50:53]
	v_mfma_f32_16x16x32_bf16 v[38:41], v[86:89], v[174:177], v[38:41]
	v_mfma_f32_16x16x32_bf16 v[34:37], v[94:97], v[174:177], v[34:37]
	v_mfma_f32_16x16x32_bf16 v[30:33], v[86:89], v[196:199], v[30:33]
	v_mfma_f32_16x16x32_bf16 v[22:25], v[94:97], v[196:199], v[22:25]
	v_mfma_f32_16x16x32_bf16 v[14:17], v[86:89], v[208:211], v[14:17]
	v_mfma_f32_16x16x32_bf16 v[10:13], v[94:97], v[208:211], v[10:13]
	s_barrier
	s_add_i32 s40, 0, 0x18000
	s_add_i32 s51, 0, 0x1c000
	v_add_u32_e32 v74, s40, v1
	v_add_u32_e32 v94, s51, v1
	ds_read_b128 v[58:61], v74
	ds_read_b128 v[62:65], v74 offset:1024
	ds_read_b128 v[70:73], v74 offset:2048
	ds_read_b128 v[74:77], v74 offset:3072
	ds_read_b128 v[78:81], v94
	ds_read_b128 v[86:89], v94 offset:1024
	ds_read_b128 v[90:93], v94 offset:2048
	ds_read_b128 v[94:97], v94 offset:3072
	s_add_u32 s18, s28, 0x160000
	s_addc_u32 s19, s29, 0
	s_mov_b32 m0, s41
	v_lshl_add_u64 v[212:213], s[18:19], 0, v[190:191]
	ds_read_b128 v[162:165], v206 offset:32768
	ds_read_b128 v[166:169], v206 offset:33792
	ds_read_b128 v[170:173], v206 offset:34816
	ds_read_b128 v[174:177], v206 offset:35840
	ds_read_b128 v[184:187], v206 offset:36864
	ds_read_b128 v[196:199], v206 offset:37888
	ds_read_b128 v[200:203], v206 offset:38912
	ds_read_b128 v[208:211], v206 offset:39936
	global_load_lds_dwordx4 v[212:213], off
	v_lshl_add_u64 v[212:213], s[18:19], 0, v[178:179]
	s_mov_b32 m0, s42
	s_nop 0
	global_load_lds_dwordx4 v[212:213], off
	s_waitcnt vmcnt(8)
	s_waitcnt lgkmcnt(0)
	s_barrier
	s_waitcnt lgkmcnt(0)
	v_mfma_f32_16x16x32_bf16 v[158:161], v[58:61], v[162:165], v[158:161]
	v_mfma_f32_16x16x32_bf16 v[154:157], v[70:73], v[162:165], v[154:157]
	v_mfma_f32_16x16x32_bf16 v[142:145], v[58:61], v[170:173], v[142:145]
	v_mfma_f32_16x16x32_bf16 v[138:141], v[70:73], v[170:173], v[138:141]
	v_mfma_f32_16x16x32_bf16 v[126:129], v[58:61], v[184:187], v[126:129]
	v_mfma_f32_16x16x32_bf16 v[122:125], v[70:73], v[184:187], v[122:125]
	v_mfma_f32_16x16x32_bf16 v[110:113], v[58:61], v[200:203], v[110:113]
	v_mfma_f32_16x16x32_bf16 v[106:109], v[70:73], v[200:203], v[106:109]
	v_mfma_f32_16x16x32_bf16 v[158:161], v[62:65], v[166:169], v[158:161]
	v_mfma_f32_16x16x32_bf16 v[154:157], v[74:77], v[166:169], v[154:157]
	v_mfma_f32_16x16x32_bf16 v[142:145], v[62:65], v[174:177], v[142:145]
	v_mfma_f32_16x16x32_bf16 v[138:141], v[74:77], v[174:177], v[138:141]
	v_mfma_f32_16x16x32_bf16 v[126:129], v[62:65], v[196:199], v[126:129]
	v_mfma_f32_16x16x32_bf16 v[122:125], v[74:77], v[196:199], v[122:125]
	v_mfma_f32_16x16x32_bf16 v[110:113], v[62:65], v[208:211], v[110:113]
	v_mfma_f32_16x16x32_bf16 v[106:109], v[74:77], v[208:211], v[106:109]
	v_mfma_f32_16x16x32_bf16 v[150:153], v[78:81], v[162:165], v[150:153]
	v_mfma_f32_16x16x32_bf16 v[146:149], v[90:93], v[162:165], v[146:149]
	v_mfma_f32_16x16x32_bf16 v[134:137], v[78:81], v[170:173], v[134:137]
	v_mfma_f32_16x16x32_bf16 v[130:133], v[90:93], v[170:173], v[130:133]
	v_mfma_f32_16x16x32_bf16 v[118:121], v[78:81], v[184:187], v[118:121]
	v_mfma_f32_16x16x32_bf16 v[114:117], v[90:93], v[184:187], v[114:117]
	v_mfma_f32_16x16x32_bf16 v[102:105], v[78:81], v[200:203], v[102:105]
	v_mfma_f32_16x16x32_bf16 v[98:101], v[90:93], v[200:203], v[98:101]
	v_mfma_f32_16x16x32_bf16 v[150:153], v[86:89], v[166:169], v[150:153]
	v_mfma_f32_16x16x32_bf16 v[146:149], v[94:97], v[166:169], v[146:149]
	v_mfma_f32_16x16x32_bf16 v[134:137], v[86:89], v[174:177], v[134:137]
	v_mfma_f32_16x16x32_bf16 v[130:133], v[94:97], v[174:177], v[130:133]
	v_mfma_f32_16x16x32_bf16 v[118:121], v[86:89], v[196:199], v[118:121]
	v_mfma_f32_16x16x32_bf16 v[114:117], v[94:97], v[196:199], v[114:117]
	v_mfma_f32_16x16x32_bf16 v[102:105], v[86:89], v[208:211], v[102:105]
	v_mfma_f32_16x16x32_bf16 v[98:101], v[94:97], v[208:211], v[98:101]
	s_barrier
	s_add_i32 s18, s40, s30
	v_lshl_add_u64 v[188:189], v[188:189], 0, s[36:37]
	s_mov_b32 m0, s18
	ds_read_b128 v[162:165], v206 offset:49152
	ds_read_b128 v[166:169], v206 offset:50176
	ds_read_b128 v[170:173], v206 offset:51200
	ds_read_b128 v[174:177], v206 offset:52224
	ds_read_b128 v[184:187], v206 offset:53248
	ds_read_b128 v[196:199], v206 offset:54272
	ds_read_b128 v[200:203], v206 offset:55296
	ds_read_b128 v[208:211], v206 offset:56320
	global_load_lds_dwordx4 v[188:189], off
	s_add_i32 m0, s18, 0x2000
	s_add_u32 s18, s22, 0x160080
	v_lshl_add_u64 v[188:189], v[192:193], 0, s[36:37]
	s_addc_u32 s19, s23, 0
	s_add_i32 s22, s51, s30
	global_load_lds_dwordx4 v[188:189], off
	v_lshl_add_u64 v[188:189], s[18:19], 0, v[190:191]
	s_mov_b32 m0, s22
	s_nop 0
	global_load_lds_dwordx4 v[188:189], off
	v_lshl_add_u64 v[188:189], s[18:19], 0, v[178:179]
	s_add_i32 m0, s22, 0x2000
	s_nop 0
	global_load_lds_dwordx4 v[188:189], off
	v_lshl_add_u64 v[188:189], v[194:195], 0, s[36:37]
	s_mov_b32 m0, s47
	s_nop 0
	global_load_lds_dwordx4 v[188:189], off
	v_lshl_add_u64 v[188:189], v[204:205], 0, s[36:37]
	s_mov_b32 m0, s48
	s_nop 0
	global_load_lds_dwordx4 v[188:189], off
	s_waitcnt vmcnt(8)
	s_waitcnt lgkmcnt(0)
	s_barrier
	s_waitcnt lgkmcnt(0)
	v_mfma_f32_16x16x32_bf16 v[82:85], v[58:61], v[162:165], v[82:85]
	v_mfma_f32_16x16x32_bf16 v[66:69], v[70:73], v[162:165], v[66:69]
	v_mfma_f32_16x16x32_bf16 v[46:49], v[58:61], v[170:173], v[46:49]
	v_mfma_f32_16x16x32_bf16 v[42:45], v[70:73], v[170:173], v[42:45]
	v_mfma_f32_16x16x32_bf16 v[26:29], v[58:61], v[184:187], v[26:29]
	v_mfma_f32_16x16x32_bf16 v[18:21], v[70:73], v[184:187], v[18:21]
	v_mfma_f32_16x16x32_bf16 v[6:9], v[58:61], v[200:203], v[6:9]
	v_mfma_f32_16x16x32_bf16 v[2:5], v[70:73], v[200:203], v[2:5]
	v_mfma_f32_16x16x32_bf16 v[82:85], v[62:65], v[166:169], v[82:85]
	v_mfma_f32_16x16x32_bf16 v[66:69], v[74:77], v[166:169], v[66:69]
	v_mfma_f32_16x16x32_bf16 v[46:49], v[62:65], v[174:177], v[46:49]
	v_mfma_f32_16x16x32_bf16 v[42:45], v[74:77], v[174:177], v[42:45]
	v_mfma_f32_16x16x32_bf16 v[26:29], v[62:65], v[196:199], v[26:29]
	v_mfma_f32_16x16x32_bf16 v[18:21], v[74:77], v[196:199], v[18:21]
	v_mfma_f32_16x16x32_bf16 v[6:9], v[62:65], v[208:211], v[6:9]
	v_mfma_f32_16x16x32_bf16 v[2:5], v[74:77], v[208:211], v[2:5]
	v_mfma_f32_16x16x32_bf16 v[54:57], v[78:81], v[162:165], v[54:57]
	v_mfma_f32_16x16x32_bf16 v[50:53], v[90:93], v[162:165], v[50:53]
	v_mfma_f32_16x16x32_bf16 v[38:41], v[78:81], v[170:173], v[38:41]
	v_mfma_f32_16x16x32_bf16 v[34:37], v[90:93], v[170:173], v[34:37]
	v_mfma_f32_16x16x32_bf16 v[30:33], v[78:81], v[184:187], v[30:33]
	v_mfma_f32_16x16x32_bf16 v[22:25], v[90:93], v[184:187], v[22:25]
	v_mfma_f32_16x16x32_bf16 v[14:17], v[78:81], v[200:203], v[14:17]
	v_mfma_f32_16x16x32_bf16 v[10:13], v[90:93], v[200:203], v[10:13]
	v_mfma_f32_16x16x32_bf16 v[54:57], v[86:89], v[166:169], v[54:57]
	v_mfma_f32_16x16x32_bf16 v[50:53], v[94:97], v[166:169], v[50:53]
	v_mfma_f32_16x16x32_bf16 v[38:41], v[86:89], v[174:177], v[38:41]
	v_mfma_f32_16x16x32_bf16 v[34:37], v[94:97], v[174:177], v[34:37]
	v_mfma_f32_16x16x32_bf16 v[30:33], v[86:89], v[196:199], v[30:33]
	v_mfma_f32_16x16x32_bf16 v[22:25], v[94:97], v[196:199], v[22:25]
	v_mfma_f32_16x16x32_bf16 v[14:17], v[86:89], v[208:211], v[14:17]
	v_mfma_f32_16x16x32_bf16 v[10:13], v[94:97], v[208:211], v[10:13]
	s_barrier
	s_add_i32 s38, s38, 2
	s_add_u32 s20, s20, 0x100
	s_addc_u32 s26, s26, 0
	s_cmpk_gt_u32 s38, 0x55
	s_mov_b64 s[18:19], s[6:7]
	s_cbranch_scc0 .LBB0_868
	s_and_b64 vcc, exec, s[12:13]
	s_cbranch_vccz .LBB0_871
	s_barrier

.LBB0_905:
	s_add_u32 s16, s14, 0x100
	s_addc_u32 s17, s15, 0
	s_add_i32 s47, 0, 0x10000
	s_cmp_eq_u32 s40, 18
	s_cselect_b32 s23, s11, s17
	s_cselect_b32 s22, s10, s16
	v_add_u32_e32 v144, s47, v1
	s_cselect_b32 s19, s13, s38
	s_cselect_b32 s18, s12, s26
	s_add_i32 s48, 0, 0x14000
	ds_read_b128 v[130:133], v144
	ds_read_b128 v[140:143], v144 offset:1024
	ds_read_b128 v[148:151], v144 offset:2048
	ds_read_b128 v[152:155], v144 offset:3072
	v_add_u32_e32 v144, s48, v1
	ds_read_b128 v[156:159], v144
	ds_read_b128 v[160:163], v144 offset:1024
	ds_read_b128 v[164:167], v144 offset:2048
	ds_read_b128 v[168:171], v144 offset:3072
	v_lshl_add_u64 v[144:145], s[14:15], 0, v[136:137]
	s_add_i32 m0, s29, 0xc000
	ds_read_b128 v[172:175], v146
	ds_read_b128 v[176:179], v146 offset:1024
	ds_read_b128 v[180:183], v146 offset:2048
	ds_read_b128 v[184:187], v146 offset:3072
	ds_read_b128 v[196:199], v146 offset:4096
	ds_read_b128 v[200:203], v146 offset:5120
	ds_read_b128 v[204:207], v146 offset:6144
	ds_read_b128 v[208:211], v146 offset:7168
	global_load_lds_dwordx4 v[144:145], off
	v_lshl_add_u64 v[144:145], s[14:15], 0, v[138:139]
	s_add_i32 m0, s29, 0xe000
	s_nop 0
	global_load_lds_dwordx4 v[144:145], off
	s_waitcnt vmcnt(8)
	s_waitcnt lgkmcnt(0)
	s_barrier
	s_waitcnt lgkmcnt(0)
	v_mfma_f32_16x16x32_bf16 v[126:129], v[130:133], v[172:175], v[126:129]
	v_mfma_f32_16x16x32_bf16 v[102:105], v[148:151], v[172:175], v[102:105]
	v_mfma_f32_16x16x32_bf16 v[122:125], v[130:133], v[180:183], v[122:125]
	v_mfma_f32_16x16x32_bf16 v[94:97], v[148:151], v[180:183], v[94:97]
	v_mfma_f32_16x16x32_bf16 v[118:121], v[130:133], v[196:199], v[118:121]
	v_mfma_f32_16x16x32_bf16 v[86:89], v[148:151], v[196:199], v[86:89]
	v_mfma_f32_16x16x32_bf16 v[114:117], v[130:133], v[204:207], v[114:117]
	v_mfma_f32_16x16x32_bf16 v[82:85], v[148:151], v[204:207], v[82:85]
	v_mfma_f32_16x16x32_bf16 v[126:129], v[140:143], v[176:179], v[126:129]
	v_mfma_f32_16x16x32_bf16 v[102:105], v[152:155], v[176:179], v[102:105]
	v_mfma_f32_16x16x32_bf16 v[122:125], v[140:143], v[184:187], v[122:125]
	v_mfma_f32_16x16x32_bf16 v[94:97], v[152:155], v[184:187], v[94:97]
	v_mfma_f32_16x16x32_bf16 v[118:121], v[140:143], v[200:203], v[118:121]
	v_mfma_f32_16x16x32_bf16 v[86:89], v[152:155], v[200:203], v[86:89]
	v_mfma_f32_16x16x32_bf16 v[114:117], v[140:143], v[208:211], v[114:117]
	v_mfma_f32_16x16x32_bf16 v[82:85], v[152:155], v[208:211], v[82:85]
	v_mfma_f32_16x16x32_bf16 v[70:73], v[156:159], v[172:175], v[70:73]
	v_mfma_f32_16x16x32_bf16 v[30:33], v[164:167], v[172:175], v[30:33]
	v_mfma_f32_16x16x32_bf16 v[62:65], v[156:159], v[180:183], v[62:65]
	v_mfma_f32_16x16x32_bf16 v[26:29], v[164:167], v[180:183], v[26:29]
	v_mfma_f32_16x16x32_bf16 v[54:57], v[156:159], v[196:199], v[54:57]
	v_mfma_f32_16x16x32_bf16 v[22:25], v[164:167], v[196:199], v[22:25]
	v_mfma_f32_16x16x32_bf16 v[50:53], v[156:159], v[204:207], v[50:53]
	v_mfma_f32_16x16x32_bf16 v[18:21], v[164:167], v[204:207], v[18:21]
	v_mfma_f32_16x16x32_bf16 v[70:73], v[160:163], v[176:179], v[70:73]
	v_mfma_f32_16x16x32_bf16 v[30:33], v[168:171], v[176:179], v[30:33]
	v_mfma_f32_16x16x32_bf16 v[62:65], v[160:163], v[184:187], v[62:65]
	v_mfma_f32_16x16x32_bf16 v[26:29], v[168:171], v[184:187], v[26:29]
	v_mfma_f32_16x16x32_bf16 v[54:57], v[160:163], v[200:203], v[54:57]
	v_mfma_f32_16x16x32_bf16 v[22:25], v[168:171], v[200:203], v[22:25]
	v_mfma_f32_16x16x32_bf16 v[50:53], v[160:163], v[208:211], v[50:53]
	v_mfma_f32_16x16x32_bf16 v[18:21], v[168:171], v[208:211], v[18:21]
	s_barrier
	s_add_i32 s14, s47, s28
	v_lshl_add_u64 v[144:145], s[18:19], 0, v[190:191]
	s_mov_b32 m0, s14
	ds_read_b128 v[172:175], v146 offset:16384
	ds_read_b128 v[176:179], v146 offset:17408
	ds_read_b128 v[180:183], v146 offset:18432
	ds_read_b128 v[184:187], v146 offset:19456
	ds_read_b128 v[196:199], v146 offset:20480
	ds_read_b128 v[200:203], v146 offset:21504
	ds_read_b128 v[204:207], v146 offset:22528
	ds_read_b128 v[208:211], v146 offset:23552
	global_load_lds_dwordx4 v[144:145], off
	s_add_i32 m0, s14, 0x2000
	s_add_u32 s14, s18, 0x160000
	v_lshl_add_u64 v[188:189], s[18:19], 0, v[134:135]
	s_addc_u32 s15, s19, 0
	s_add_i32 s47, s48, s28
	global_load_lds_dwordx4 v[188:189], off
	v_lshl_add_u64 v[192:193], s[14:15], 0, v[190:191]
	s_mov_b32 m0, s47
	v_lshl_add_u64 v[194:195], s[22:23], 0, v[134:135]
	global_load_lds_dwordx4 v[192:193], off
	v_lshl_add_u64 v[192:193], s[14:15], 0, v[134:135]
	s_add_i32 m0, s47, 0x2000
	s_nop 0
	global_load_lds_dwordx4 v[192:193], off
	v_lshl_add_u64 v[192:193], s[22:23], 0, v[190:191]
	s_mov_b32 m0, s29
	s_nop 0
	global_load_lds_dwordx4 v[192:193], off
	s_mov_b32 m0, s30
	s_nop 0
	global_load_lds_dwordx4 v[194:195], off
	s_waitcnt vmcnt(8)
	s_waitcnt lgkmcnt(0)
	s_barrier
	s_waitcnt lgkmcnt(0)
	v_mfma_f32_16x16x32_bf16 v[110:113], v[130:133], v[172:175], v[110:113]
	v_mfma_f32_16x16x32_bf16 v[78:81], v[148:151], v[172:175], v[78:81]
	v_mfma_f32_16x16x32_bf16 v[106:109], v[130:133], v[180:183], v[106:109]
	v_mfma_f32_16x16x32_bf16 v[74:77], v[148:151], v[180:183], v[74:77]
	v_mfma_f32_16x16x32_bf16 v[98:101], v[130:133], v[196:199], v[98:101]
	v_mfma_f32_16x16x32_bf16 v[66:69], v[148:151], v[196:199], v[66:69]
	v_mfma_f32_16x16x32_bf16 v[90:93], v[130:133], v[204:207], v[90:93]
	v_mfma_f32_16x16x32_bf16 v[58:61], v[148:151], v[204:207], v[58:61]
	v_mfma_f32_16x16x32_bf16 v[110:113], v[140:143], v[176:179], v[110:113]
	v_mfma_f32_16x16x32_bf16 v[78:81], v[152:155], v[176:179], v[78:81]
	v_mfma_f32_16x16x32_bf16 v[106:109], v[140:143], v[184:187], v[106:109]
	v_mfma_f32_16x16x32_bf16 v[74:77], v[152:155], v[184:187], v[74:77]
	v_mfma_f32_16x16x32_bf16 v[98:101], v[140:143], v[200:203], v[98:101]
	v_mfma_f32_16x16x32_bf16 v[66:69], v[152:155], v[200:203], v[66:69]
	v_mfma_f32_16x16x32_bf16 v[90:93], v[140:143], v[208:211], v[90:93]
	v_mfma_f32_16x16x32_bf16 v[58:61], v[152:155], v[208:211], v[58:61]
	v_mfma_f32_16x16x32_bf16 v[38:41], v[156:159], v[172:175], v[38:41]
	v_mfma_f32_16x16x32_bf16 v[10:13], v[164:167], v[172:175], v[10:13]
	v_mfma_f32_16x16x32_bf16 v[34:37], v[156:159], v[180:183], v[34:37]
	v_mfma_f32_16x16x32_bf16 v[6:9], v[164:167], v[180:183], v[6:9]
	v_mfma_f32_16x16x32_bf16 v[46:49], v[156:159], v[196:199], v[46:49]
	v_mfma_f32_16x16x32_bf16 v[14:17], v[164:167], v[196:199], v[14:17]
	v_mfma_f32_16x16x32_bf16 v[42:45], v[156:159], v[204:207], v[42:45]
	v_mfma_f32_16x16x32_bf16 v[2:5], v[164:167], v[204:207], v[2:5]
	v_mfma_f32_16x16x32_bf16 v[38:41], v[160:163], v[176:179], v[38:41]
	v_mfma_f32_16x16x32_bf16 v[10:13], v[168:171], v[176:179], v[10:13]
	v_mfma_f32_16x16x32_bf16 v[34:37], v[160:163], v[184:187], v[34:37]
	v_mfma_f32_16x16x32_bf16 v[6:9], v[168:171], v[184:187], v[6:9]
	v_mfma_f32_16x16x32_bf16 v[46:49], v[160:163], v[200:203], v[46:49]
	v_mfma_f32_16x16x32_bf16 v[14:17], v[168:171], v[200:203], v[14:17]
	v_mfma_f32_16x16x32_bf16 v[42:45], v[160:163], v[208:211], v[42:45]
	v_mfma_f32_16x16x32_bf16 v[2:5], v[168:171], v[208:211], v[2:5]
	s_barrier
	s_add_i32 s47, 0, 0x18000
	v_add_u32_e32 v147, s47, v1
	s_add_i32 s48, 0, 0x1c000
	ds_read_b128 v[130:133], v147
	ds_read_b128 v[140:143], v147 offset:1024
	ds_read_b128 v[148:151], v147 offset:2048
	ds_read_b128 v[152:155], v147 offset:3072
	v_add_u32_e32 v147, s48, v1
	ds_read_b128 v[156:159], v147
	ds_read_b128 v[160:163], v147 offset:1024
	ds_read_b128 v[164:167], v147 offset:2048
	ds_read_b128 v[168:171], v147 offset:3072
	s_add_u32 s14, s22, 0x160000
	s_addc_u32 s15, s23, 0
	s_mov_b32 m0, s31
	v_lshl_add_u64 v[212:213], s[14:15], 0, v[190:191]
	ds_read_b128 v[172:175], v146 offset:32768
	ds_read_b128 v[176:179], v146 offset:33792
	ds_read_b128 v[180:183], v146 offset:34816
	ds_read_b128 v[184:187], v146 offset:35840
	ds_read_b128 v[196:199], v146 offset:36864
	ds_read_b128 v[200:203], v146 offset:37888
	ds_read_b128 v[204:207], v146 offset:38912
	ds_read_b128 v[208:211], v146 offset:39936
	global_load_lds_dwordx4 v[212:213], off
	v_lshl_add_u64 v[212:213], s[14:15], 0, v[134:135]
	s_mov_b32 m0, s39
	s_nop 0
	global_load_lds_dwordx4 v[212:213], off
	s_waitcnt vmcnt(8)
	s_waitcnt lgkmcnt(0)
	s_barrier
	s_waitcnt lgkmcnt(0)
	v_mfma_f32_16x16x32_bf16 v[126:129], v[130:133], v[172:175], v[126:129]
	v_mfma_f32_16x16x32_bf16 v[102:105], v[148:151], v[172:175], v[102:105]
	v_mfma_f32_16x16x32_bf16 v[122:125], v[130:133], v[180:183], v[122:125]
	v_mfma_f32_16x16x32_bf16 v[94:97], v[148:151], v[180:183], v[94:97]
	v_mfma_f32_16x16x32_bf16 v[118:121], v[130:133], v[196:199], v[118:121]
	v_mfma_f32_16x16x32_bf16 v[86:89], v[148:151], v[196:199], v[86:89]
	v_mfma_f32_16x16x32_bf16 v[114:117], v[130:133], v[204:207], v[114:117]
	v_mfma_f32_16x16x32_bf16 v[82:85], v[148:151], v[204:207], v[82:85]
	v_mfma_f32_16x16x32_bf16 v[126:129], v[140:143], v[176:179], v[126:129]
	v_mfma_f32_16x16x32_bf16 v[102:105], v[152:155], v[176:179], v[102:105]
	v_mfma_f32_16x16x32_bf16 v[122:125], v[140:143], v[184:187], v[122:125]
	v_mfma_f32_16x16x32_bf16 v[94:97], v[152:155], v[184:187], v[94:97]
	v_mfma_f32_16x16x32_bf16 v[118:121], v[140:143], v[200:203], v[118:121]
	v_mfma_f32_16x16x32_bf16 v[86:89], v[152:155], v[200:203], v[86:89]
	v_mfma_f32_16x16x32_bf16 v[114:117], v[140:143], v[208:211], v[114:117]
	v_mfma_f32_16x16x32_bf16 v[82:85], v[152:155], v[208:211], v[82:85]
	v_mfma_f32_16x16x32_bf16 v[70:73], v[156:159], v[172:175], v[70:73]
	v_mfma_f32_16x16x32_bf16 v[30:33], v[164:167], v[172:175], v[30:33]
	v_mfma_f32_16x16x32_bf16 v[62:65], v[156:159], v[180:183], v[62:65]
	v_mfma_f32_16x16x32_bf16 v[26:29], v[164:167], v[180:183], v[26:29]
	v_mfma_f32_16x16x32_bf16 v[54:57], v[156:159], v[196:199], v[54:57]
	v_mfma_f32_16x16x32_bf16 v[22:25], v[164:167], v[196:199], v[22:25]
	v_mfma_f32_16x16x32_bf16 v[50:53], v[156:159], v[204:207], v[50:53]
	v_mfma_f32_16x16x32_bf16 v[18:21], v[164:167], v[204:207], v[18:21]
	v_mfma_f32_16x16x32_bf16 v[70:73], v[160:163], v[176:179], v[70:73]
	v_mfma_f32_16x16x32_bf16 v[30:33], v[168:171], v[176:179], v[30:33]
	v_mfma_f32_16x16x32_bf16 v[62:65], v[160:163], v[184:187], v[62:65]
	v_mfma_f32_16x16x32_bf16 v[26:29], v[168:171], v[184:187], v[26:29]
	v_mfma_f32_16x16x32_bf16 v[54:57], v[160:163], v[200:203], v[54:57]
	v_mfma_f32_16x16x32_bf16 v[22:25], v[168:171], v[200:203], v[22:25]
	v_mfma_f32_16x16x32_bf16 v[50:53], v[160:163], v[208:211], v[50:53]
	v_mfma_f32_16x16x32_bf16 v[18:21], v[168:171], v[208:211], v[18:21]
	s_barrier
	s_add_i32 s14, s47, s28
	v_lshl_add_u64 v[144:145], v[144:145], 0, s[36:37]
	s_mov_b32 m0, s14
	ds_read_b128 v[172:175], v146 offset:49152
	ds_read_b128 v[176:179], v146 offset:50176
	ds_read_b128 v[180:183], v146 offset:51200
	ds_read_b128 v[184:187], v146 offset:52224
	ds_read_b128 v[196:199], v146 offset:53248
	ds_read_b128 v[200:203], v146 offset:54272
	ds_read_b128 v[204:207], v146 offset:55296
	ds_read_b128 v[208:211], v146 offset:56320
	global_load_lds_dwordx4 v[144:145], off
	s_add_i32 m0, s14, 0x2000
	s_add_u32 s14, s18, 0x160080
	v_lshl_add_u64 v[144:145], v[188:189], 0, s[36:37]
	s_addc_u32 s15, s19, 0
	s_add_i32 s18, s48, s28
	global_load_lds_dwordx4 v[144:145], off
	v_lshl_add_u64 v[144:145], s[14:15], 0, v[190:191]
	s_mov_b32 m0, s18
	s_nop 0
	global_load_lds_dwordx4 v[144:145], off
	v_lshl_add_u64 v[144:145], s[14:15], 0, v[134:135]
	s_add_i32 m0, s18, 0x2000
	s_nop 0
	global_load_lds_dwordx4 v[144:145], off
	v_lshl_add_u64 v[144:145], v[192:193], 0, s[36:37]
	s_mov_b32 m0, s43
	s_nop 0
	global_load_lds_dwordx4 v[144:145], off
	v_lshl_add_u64 v[144:145], v[194:195], 0, s[36:37]
	s_mov_b32 m0, s44
	s_nop 0
	global_load_lds_dwordx4 v[144:145], off
	s_waitcnt vmcnt(8)
	s_waitcnt lgkmcnt(0)
	s_barrier
	s_waitcnt lgkmcnt(0)
	v_mfma_f32_16x16x32_bf16 v[110:113], v[130:133], v[172:175], v[110:113]
	v_mfma_f32_16x16x32_bf16 v[78:81], v[148:151], v[172:175], v[78:81]
	v_mfma_f32_16x16x32_bf16 v[106:109], v[130:133], v[180:183], v[106:109]
	v_mfma_f32_16x16x32_bf16 v[74:77], v[148:151], v[180:183], v[74:77]
	v_mfma_f32_16x16x32_bf16 v[98:101], v[130:133], v[196:199], v[98:101]
	v_mfma_f32_16x16x32_bf16 v[66:69], v[148:151], v[196:199], v[66:69]
	v_mfma_f32_16x16x32_bf16 v[90:93], v[130:133], v[204:207], v[90:93]
	v_mfma_f32_16x16x32_bf16 v[58:61], v[148:151], v[204:207], v[58:61]
	v_mfma_f32_16x16x32_bf16 v[110:113], v[140:143], v[176:179], v[110:113]
	v_mfma_f32_16x16x32_bf16 v[78:81], v[152:155], v[176:179], v[78:81]
	v_mfma_f32_16x16x32_bf16 v[106:109], v[140:143], v[184:187], v[106:109]
	v_mfma_f32_16x16x32_bf16 v[74:77], v[152:155], v[184:187], v[74:77]
	v_mfma_f32_16x16x32_bf16 v[98:101], v[140:143], v[200:203], v[98:101]
	v_mfma_f32_16x16x32_bf16 v[66:69], v[152:155], v[200:203], v[66:69]
	v_mfma_f32_16x16x32_bf16 v[90:93], v[140:143], v[208:211], v[90:93]
	v_mfma_f32_16x16x32_bf16 v[58:61], v[152:155], v[208:211], v[58:61]
	v_mfma_f32_16x16x32_bf16 v[38:41], v[156:159], v[172:175], v[38:41]
	v_mfma_f32_16x16x32_bf16 v[10:13], v[164:167], v[172:175], v[10:13]
	v_mfma_f32_16x16x32_bf16 v[34:37], v[156:159], v[180:183], v[34:37]
	v_mfma_f32_16x16x32_bf16 v[6:9], v[164:167], v[180:183], v[6:9]
	v_mfma_f32_16x16x32_bf16 v[46:49], v[156:159], v[196:199], v[46:49]
	v_mfma_f32_16x16x32_bf16 v[14:17], v[164:167], v[196:199], v[14:17]
	v_mfma_f32_16x16x32_bf16 v[42:45], v[156:159], v[204:207], v[42:45]
	v_mfma_f32_16x16x32_bf16 v[2:5], v[164:167], v[204:207], v[2:5]
	v_mfma_f32_16x16x32_bf16 v[38:41], v[160:163], v[176:179], v[38:41]
	v_mfma_f32_16x16x32_bf16 v[10:13], v[168:171], v[176:179], v[10:13]
	v_mfma_f32_16x16x32_bf16 v[34:37], v[160:163], v[184:187], v[34:37]
	v_mfma_f32_16x16x32_bf16 v[6:9], v[168:171], v[184:187], v[6:9]
	v_mfma_f32_16x16x32_bf16 v[46:49], v[160:163], v[200:203], v[46:49]
	v_mfma_f32_16x16x32_bf16 v[14:17], v[168:171], v[200:203], v[14:17]
	v_mfma_f32_16x16x32_bf16 v[42:45], v[160:163], v[208:211], v[42:45]
	v_mfma_f32_16x16x32_bf16 v[2:5], v[168:171], v[208:211], v[2:5]
	s_barrier
	s_add_i32 s40, s40, 2
	s_add_u32 s26, s26, 0x100
	s_addc_u32 s38, s38, 0
	s_cmp_gt_u32 s40, 19
	s_mov_b64 s[14:15], s[16:17]
	s_cbranch_scc0 .LBB0_905
	s_and_b64 vcc, exec, s[8:9]
	s_cbranch_vccz .LBB0_908
	s_barrier

.LBB0_1339:
	s_add_u32 s28, s4, 0xfff80080
	s_addc_u32 s29, s5, -1
	s_add_i32 s40, 0, 0x10000
	s_cmp_eq_u32 s38, 28
	s_cselect_b32 s31, s0, s29
	s_cselect_b32 s30, s7, s28
	s_cselect_b32 s29, s51, s26
	s_cselect_b32 s28, s50, s20
	s_add_i32 s47, 0, 0x14000
	v_add_u32_e32 v46, s40, v1
	v_add_u32_e32 v158, s47, v1
	ds_read_b128 v[26:29], v46
	ds_read_b128 v[34:37], v46 offset:1024
	ds_read_b128 v[42:45], v46 offset:2048
	ds_read_b128 v[46:49], v46 offset:3072
	ds_read_b128 v[146:149], v158
	ds_read_b128 v[150:153], v158 offset:1024
	ds_read_b128 v[154:157], v158 offset:2048
	ds_read_b128 v[158:161], v158 offset:3072
	v_lshl_add_u64 v[188:189], s[4:5], 0, v[168:169]
	s_add_i32 m0, s27, 0xc000
	ds_read_b128 v[172:175], v204
	ds_read_b128 v[176:179], v204 offset:1024
	ds_read_b128 v[180:183], v204 offset:2048
	ds_read_b128 v[184:187], v204 offset:3072
	ds_read_b128 v[196:199], v204 offset:4096
	ds_read_b128 v[200:203], v204 offset:5120
	ds_read_b128 v[206:209], v204 offset:6144
	ds_read_b128 v[210:213], v204 offset:7168
	global_load_lds_dwordx4 v[188:189], off
	v_lshl_add_u64 v[188:189], s[4:5], 0, v[170:171]
	s_add_i32 m0, s27, 0xe000
	s_nop 0
	global_load_lds_dwordx4 v[188:189], off
	s_waitcnt vmcnt(8)
	s_waitcnt lgkmcnt(0)
	s_barrier
	s_waitcnt lgkmcnt(0)
	v_mfma_f32_16x16x32_bf16 v[142:145], v[26:29], v[172:175], v[142:145]
	v_mfma_f32_16x16x32_bf16 v[138:141], v[42:45], v[172:175], v[138:141]
	v_mfma_f32_16x16x32_bf16 v[126:129], v[26:29], v[180:183], v[126:129]
	v_mfma_f32_16x16x32_bf16 v[122:125], v[42:45], v[180:183], v[122:125]
	v_mfma_f32_16x16x32_bf16 v[110:113], v[26:29], v[196:199], v[110:113]
	v_mfma_f32_16x16x32_bf16 v[106:109], v[42:45], v[196:199], v[106:109]
	v_mfma_f32_16x16x32_bf16 v[94:97], v[26:29], v[206:209], v[94:97]
	v_mfma_f32_16x16x32_bf16 v[90:93], v[42:45], v[206:209], v[90:93]
	v_mfma_f32_16x16x32_bf16 v[142:145], v[34:37], v[176:179], v[142:145]
	v_mfma_f32_16x16x32_bf16 v[138:141], v[46:49], v[176:179], v[138:141]
	v_mfma_f32_16x16x32_bf16 v[126:129], v[34:37], v[184:187], v[126:129]
	v_mfma_f32_16x16x32_bf16 v[122:125], v[46:49], v[184:187], v[122:125]
	v_mfma_f32_16x16x32_bf16 v[110:113], v[34:37], v[200:203], v[110:113]
	v_mfma_f32_16x16x32_bf16 v[106:109], v[46:49], v[200:203], v[106:109]
	v_mfma_f32_16x16x32_bf16 v[94:97], v[34:37], v[210:213], v[94:97]
	v_mfma_f32_16x16x32_bf16 v[90:93], v[46:49], v[210:213], v[90:93]
	v_mfma_f32_16x16x32_bf16 v[134:137], v[146:149], v[172:175], v[134:137]
	v_mfma_f32_16x16x32_bf16 v[130:133], v[154:157], v[172:175], v[130:133]
	v_mfma_f32_16x16x32_bf16 v[118:121], v[146:149], v[180:183], v[118:121]
	v_mfma_f32_16x16x32_bf16 v[114:117], v[154:157], v[180:183], v[114:117]
	v_mfma_f32_16x16x32_bf16 v[102:105], v[146:149], v[196:199], v[102:105]
	v_mfma_f32_16x16x32_bf16 v[98:101], v[154:157], v[196:199], v[98:101]
	v_mfma_f32_16x16x32_bf16 v[86:89], v[146:149], v[206:209], v[86:89]
	v_mfma_f32_16x16x32_bf16 v[82:85], v[154:157], v[206:209], v[82:85]
	v_mfma_f32_16x16x32_bf16 v[134:137], v[150:153], v[176:179], v[134:137]
	v_mfma_f32_16x16x32_bf16 v[130:133], v[158:161], v[176:179], v[130:133]
	v_mfma_f32_16x16x32_bf16 v[118:121], v[150:153], v[184:187], v[118:121]
	v_mfma_f32_16x16x32_bf16 v[114:117], v[158:161], v[184:187], v[114:117]
	v_mfma_f32_16x16x32_bf16 v[102:105], v[150:153], v[200:203], v[102:105]
	v_mfma_f32_16x16x32_bf16 v[98:101], v[158:161], v[200:203], v[98:101]
	v_mfma_f32_16x16x32_bf16 v[86:89], v[150:153], v[210:213], v[86:89]
	v_mfma_f32_16x16x32_bf16 v[82:85], v[158:161], v[210:213], v[82:85]
	s_barrier
	s_add_i32 s40, s40, s21
	v_lshl_add_u64 v[188:189], s[28:29], 0, v[162:163]
	s_mov_b32 m0, s40
	ds_read_b128 v[172:175], v204 offset:16384
	ds_read_b128 v[176:179], v204 offset:17408
	ds_read_b128 v[180:183], v204 offset:18432
	ds_read_b128 v[184:187], v204 offset:19456
	ds_read_b128 v[196:199], v204 offset:20480
	ds_read_b128 v[200:203], v204 offset:21504
	ds_read_b128 v[206:209], v204 offset:22528
	ds_read_b128 v[210:213], v204 offset:23552
	global_load_lds_dwordx4 v[188:189], off
	s_add_i32 m0, s40, 0x2000
	s_add_u32 s52, s28, 0x80000
	v_lshl_add_u64 v[192:193], s[28:29], 0, v[164:165]
	s_addc_u32 s53, s29, 0
	s_add_i32 s40, s47, s21
	global_load_lds_dwordx4 v[192:193], off
	v_lshl_add_u64 v[194:195], s[52:53], 0, v[162:163]
	s_mov_b32 m0, s40
	v_lshl_add_u64 v[214:215], s[30:31], 0, v[164:165]
	global_load_lds_dwordx4 v[194:195], off
	v_lshl_add_u64 v[194:195], s[52:53], 0, v[164:165]
	s_add_i32 m0, s40, 0x2000
	s_nop 0
	global_load_lds_dwordx4 v[194:195], off
	v_lshl_add_u64 v[194:195], s[30:31], 0, v[162:163]
	s_mov_b32 m0, s27
	s_nop 0
	global_load_lds_dwordx4 v[194:195], off
	s_mov_b32 m0, s39
	s_nop 0
	global_load_lds_dwordx4 v[214:215], off
	s_waitcnt vmcnt(8)
	s_waitcnt lgkmcnt(0)
	s_barrier
	s_waitcnt lgkmcnt(0)
	v_mfma_f32_16x16x32_bf16 v[78:81], v[26:29], v[172:175], v[78:81]
	v_mfma_f32_16x16x32_bf16 v[74:77], v[42:45], v[172:175], v[74:77]
	v_mfma_f32_16x16x32_bf16 v[62:65], v[26:29], v[180:183], v[62:65]
	v_mfma_f32_16x16x32_bf16 v[58:61], v[42:45], v[180:183], v[58:61]
	v_mfma_f32_16x16x32_bf16 v[22:25], v[26:29], v[196:199], v[22:25]
	v_mfma_f32_16x16x32_bf16 v[18:21], v[42:45], v[196:199], v[18:21]
	v_mfma_f32_16x16x32_bf16 v[6:9], v[26:29], v[206:209], v[6:9]
	v_mfma_f32_16x16x32_bf16 v[2:5], v[42:45], v[206:209], v[2:5]
	v_mfma_f32_16x16x32_bf16 v[78:81], v[34:37], v[176:179], v[78:81]
	v_mfma_f32_16x16x32_bf16 v[74:77], v[46:49], v[176:179], v[74:77]
	v_mfma_f32_16x16x32_bf16 v[62:65], v[34:37], v[184:187], v[62:65]
	v_mfma_f32_16x16x32_bf16 v[58:61], v[46:49], v[184:187], v[58:61]
	v_mfma_f32_16x16x32_bf16 v[22:25], v[34:37], v[200:203], v[22:25]
	v_mfma_f32_16x16x32_bf16 v[18:21], v[46:49], v[200:203], v[18:21]
	v_mfma_f32_16x16x32_bf16 v[6:9], v[34:37], v[210:213], v[6:9]
	v_mfma_f32_16x16x32_bf16 v[2:5], v[46:49], v[210:213], v[2:5]
	v_mfma_f32_16x16x32_bf16 v[38:41], v[146:149], v[196:199], v[38:41]
	v_mfma_f32_16x16x32_bf16 v[30:33], v[154:157], v[196:199], v[30:33]
	v_mfma_f32_16x16x32_bf16 v[14:17], v[146:149], v[206:209], v[14:17]
	v_mfma_f32_16x16x32_bf16 v[10:13], v[154:157], v[206:209], v[10:13]
	v_mfma_f32_16x16x32_bf16 v[26:29], v[146:149], v[172:175], v[70:73]
	v_mfma_f32_16x16x32_bf16 v[34:37], v[154:157], v[172:175], v[66:69]
	v_mfma_f32_16x16x32_bf16 v[42:45], v[146:149], v[180:183], v[54:57]
	v_mfma_f32_16x16x32_bf16 v[46:49], v[154:157], v[180:183], v[50:53]
	v_mfma_f32_16x16x32_bf16 v[38:41], v[150:153], v[200:203], v[38:41]
	v_mfma_f32_16x16x32_bf16 v[30:33], v[158:161], v[200:203], v[30:33]
	v_mfma_f32_16x16x32_bf16 v[14:17], v[150:153], v[210:213], v[14:17]
	v_mfma_f32_16x16x32_bf16 v[10:13], v[158:161], v[210:213], v[10:13]
	v_mfma_f32_16x16x32_bf16 v[26:29], v[150:153], v[176:179], v[26:29]
	v_mfma_f32_16x16x32_bf16 v[34:37], v[158:161], v[176:179], v[34:37]
	v_mfma_f32_16x16x32_bf16 v[42:45], v[150:153], v[184:187], v[42:45]
	v_mfma_f32_16x16x32_bf16 v[46:49], v[158:161], v[184:187], v[46:49]
	s_barrier
	s_add_i32 s40, 0, 0x18000
	s_add_i32 s47, 0, 0x1c000
	v_add_u32_e32 v70, s40, v1
	v_add_u32_e32 v158, s47, v1
	ds_read_b128 v[50:53], v70
	ds_read_b128 v[54:57], v70 offset:1024
	ds_read_b128 v[66:69], v70 offset:2048
	ds_read_b128 v[70:73], v70 offset:3072
	ds_read_b128 v[146:149], v158
	ds_read_b128 v[150:153], v158 offset:1024
	ds_read_b128 v[154:157], v158 offset:2048
	ds_read_b128 v[158:161], v158 offset:3072
	s_add_u32 s30, s30, 0x80000
	s_addc_u32 s31, s31, 0
	s_mov_b32 m0, s41
	v_lshl_add_u64 v[222:223], s[30:31], 0, v[162:163]
	ds_read_b128 v[172:175], v204 offset:32768
	ds_read_b128 v[176:179], v204 offset:33792
	ds_read_b128 v[180:183], v204 offset:34816
	ds_read_b128 v[184:187], v204 offset:35840
	ds_read_b128 v[196:199], v204 offset:36864
	ds_read_b128 v[200:203], v204 offset:37888
	ds_read_b128 v[206:209], v204 offset:38912
	ds_read_b128 v[210:213], v204 offset:39936
	global_load_lds_dwordx4 v[222:223], off
	v_lshl_add_u64 v[222:223], s[30:31], 0, v[164:165]
	s_mov_b32 m0, s62
	s_nop 0
	global_load_lds_dwordx4 v[222:223], off
	s_waitcnt vmcnt(8)
	s_waitcnt lgkmcnt(0)
	s_barrier
	s_waitcnt lgkmcnt(0)
	v_mfma_f32_16x16x32_bf16 v[142:145], v[50:53], v[172:175], v[142:145]
	v_mfma_f32_16x16x32_bf16 v[138:141], v[66:69], v[172:175], v[138:141]
	v_mfma_f32_16x16x32_bf16 v[126:129], v[50:53], v[180:183], v[126:129]
	v_mfma_f32_16x16x32_bf16 v[122:125], v[66:69], v[180:183], v[122:125]
	v_mfma_f32_16x16x32_bf16 v[110:113], v[50:53], v[196:199], v[110:113]
	v_mfma_f32_16x16x32_bf16 v[106:109], v[66:69], v[196:199], v[106:109]
	v_mfma_f32_16x16x32_bf16 v[94:97], v[50:53], v[206:209], v[94:97]
	v_mfma_f32_16x16x32_bf16 v[90:93], v[66:69], v[206:209], v[90:93]
	v_mfma_f32_16x16x32_bf16 v[142:145], v[54:57], v[176:179], v[142:145]
	v_mfma_f32_16x16x32_bf16 v[138:141], v[70:73], v[176:179], v[138:141]
	v_mfma_f32_16x16x32_bf16 v[126:129], v[54:57], v[184:187], v[126:129]
	v_mfma_f32_16x16x32_bf16 v[122:125], v[70:73], v[184:187], v[122:125]
	v_mfma_f32_16x16x32_bf16 v[110:113], v[54:57], v[200:203], v[110:113]
	v_mfma_f32_16x16x32_bf16 v[106:109], v[70:73], v[200:203], v[106:109]
	v_mfma_f32_16x16x32_bf16 v[94:97], v[54:57], v[210:213], v[94:97]
	v_mfma_f32_16x16x32_bf16 v[90:93], v[70:73], v[210:213], v[90:93]
	v_mfma_f32_16x16x32_bf16 v[134:137], v[146:149], v[172:175], v[134:137]
	v_mfma_f32_16x16x32_bf16 v[130:133], v[154:157], v[172:175], v[130:133]
	v_mfma_f32_16x16x32_bf16 v[118:121], v[146:149], v[180:183], v[118:121]
	v_mfma_f32_16x16x32_bf16 v[114:117], v[154:157], v[180:183], v[114:117]
	v_mfma_f32_16x16x32_bf16 v[102:105], v[146:149], v[196:199], v[102:105]
	v_mfma_f32_16x16x32_bf16 v[98:101], v[154:157], v[196:199], v[98:101]
	v_mfma_f32_16x16x32_bf16 v[86:89], v[146:149], v[206:209], v[86:89]
	v_mfma_f32_16x16x32_bf16 v[82:85], v[154:157], v[206:209], v[82:85]
	v_mfma_f32_16x16x32_bf16 v[134:137], v[150:153], v[176:179], v[134:137]
	v_mfma_f32_16x16x32_bf16 v[130:133], v[158:161], v[176:179], v[130:133]
	v_mfma_f32_16x16x32_bf16 v[118:121], v[150:153], v[184:187], v[118:121]
	v_mfma_f32_16x16x32_bf16 v[114:117], v[158:161], v[184:187], v[114:117]
	v_mfma_f32_16x16x32_bf16 v[102:105], v[150:153], v[200:203], v[102:105]
	v_mfma_f32_16x16x32_bf16 v[98:101], v[158:161], v[200:203], v[98:101]
	v_mfma_f32_16x16x32_bf16 v[86:89], v[150:153], v[210:213], v[86:89]
	v_mfma_f32_16x16x32_bf16 v[82:85], v[158:161], v[210:213], v[82:85]
	s_barrier
	s_add_i32 s30, s40, s21
	v_lshl_add_u64 v[188:189], v[188:189], 0, s[36:37]
	s_mov_b32 m0, s30
	ds_read_b128 v[172:175], v204 offset:49152
	ds_read_b128 v[176:179], v204 offset:50176
	ds_read_b128 v[180:183], v204 offset:51200
	ds_read_b128 v[184:187], v204 offset:52224
	ds_read_b128 v[196:199], v204 offset:53248
	ds_read_b128 v[200:203], v204 offset:54272
	ds_read_b128 v[206:209], v204 offset:55296
	ds_read_b128 v[210:213], v204 offset:56320
	global_load_lds_dwordx4 v[188:189], off
	s_add_i32 m0, s30, 0x2000
	s_add_u32 s28, s28, 0x80080
	v_lshl_add_u64 v[188:189], v[192:193], 0, s[36:37]
	s_addc_u32 s29, s29, 0
	s_add_i32 s30, s47, s21
	global_load_lds_dwordx4 v[188:189], off
	v_lshl_add_u64 v[188:189], s[28:29], 0, v[162:163]
	s_mov_b32 m0, s30
	s_nop 0
	global_load_lds_dwordx4 v[188:189], off
	v_lshl_add_u64 v[188:189], s[28:29], 0, v[164:165]
	s_add_i32 m0, s30, 0x2000
	s_nop 0
	global_load_lds_dwordx4 v[188:189], off
	v_lshl_add_u64 v[188:189], v[194:195], 0, s[36:37]
	s_mov_b32 m0, s67
	s_nop 0
	global_load_lds_dwordx4 v[188:189], off
	v_lshl_add_u64 v[188:189], v[214:215], 0, s[36:37]
	s_mov_b32 m0, s68
	s_nop 0
	global_load_lds_dwordx4 v[188:189], off
	s_waitcnt vmcnt(8)
	s_waitcnt lgkmcnt(0)
	s_barrier
	s_waitcnt lgkmcnt(0)
	v_mfma_f32_16x16x32_bf16 v[78:81], v[50:53], v[172:175], v[78:81]
	v_mfma_f32_16x16x32_bf16 v[74:77], v[66:69], v[172:175], v[74:77]
	v_mfma_f32_16x16x32_bf16 v[62:65], v[50:53], v[180:183], v[62:65]
	v_mfma_f32_16x16x32_bf16 v[58:61], v[66:69], v[180:183], v[58:61]
	v_mfma_f32_16x16x32_bf16 v[22:25], v[50:53], v[196:199], v[22:25]
	v_mfma_f32_16x16x32_bf16 v[18:21], v[66:69], v[196:199], v[18:21]
	v_mfma_f32_16x16x32_bf16 v[6:9], v[50:53], v[206:209], v[6:9]
	v_mfma_f32_16x16x32_bf16 v[2:5], v[66:69], v[206:209], v[2:5]
	v_mfma_f32_16x16x32_bf16 v[78:81], v[54:57], v[176:179], v[78:81]
	v_mfma_f32_16x16x32_bf16 v[74:77], v[70:73], v[176:179], v[74:77]
	v_mfma_f32_16x16x32_bf16 v[62:65], v[54:57], v[184:187], v[62:65]
	v_mfma_f32_16x16x32_bf16 v[58:61], v[70:73], v[184:187], v[58:61]
	v_mfma_f32_16x16x32_bf16 v[22:25], v[54:57], v[200:203], v[22:25]
	v_mfma_f32_16x16x32_bf16 v[18:21], v[70:73], v[200:203], v[18:21]
	v_mfma_f32_16x16x32_bf16 v[6:9], v[54:57], v[210:213], v[6:9]
	v_mfma_f32_16x16x32_bf16 v[2:5], v[70:73], v[210:213], v[2:5]
	v_mfma_f32_16x16x32_bf16 v[26:29], v[146:149], v[172:175], v[26:29]
	v_mfma_f32_16x16x32_bf16 v[70:73], v[150:153], v[176:179], v[26:29]
	v_mfma_f32_16x16x32_bf16 v[26:29], v[154:157], v[172:175], v[34:37]
	v_mfma_f32_16x16x32_bf16 v[66:69], v[158:161], v[176:179], v[26:29]
	v_mfma_f32_16x16x32_bf16 v[26:29], v[146:149], v[180:183], v[42:45]
	v_mfma_f32_16x16x32_bf16 v[54:57], v[150:153], v[184:187], v[26:29]
	v_mfma_f32_16x16x32_bf16 v[26:29], v[154:157], v[180:183], v[46:49]
	v_mfma_f32_16x16x32_bf16 v[50:53], v[158:161], v[184:187], v[26:29]
	v_mfma_f32_16x16x32_bf16 v[26:29], v[146:149], v[196:199], v[38:41]
	v_mfma_f32_16x16x32_bf16 v[38:41], v[150:153], v[200:203], v[26:29]
	v_mfma_f32_16x16x32_bf16 v[26:29], v[154:157], v[196:199], v[30:33]
	v_mfma_f32_16x16x32_bf16 v[14:17], v[146:149], v[206:209], v[14:17]
	v_mfma_f32_16x16x32_bf16 v[10:13], v[154:157], v[206:209], v[10:13]
	v_mfma_f32_16x16x32_bf16 v[30:33], v[158:161], v[200:203], v[26:29]
	v_mfma_f32_16x16x32_bf16 v[14:17], v[150:153], v[210:213], v[14:17]
	v_mfma_f32_16x16x32_bf16 v[10:13], v[158:161], v[210:213], v[10:13]
	s_barrier
	s_add_i32 s38, s38, 2
	s_add_u32 s4, s4, 0x100
	s_addc_u32 s5, s5, 0
	s_add_u32 s20, s20, 0x100
	s_addc_u32 s26, s26, 0
	s_cmp_gt_u32 s38, 29
	s_cbranch_scc0 .LBB0_1339
	s_and_b64 vcc, exec, s[14:15]
	s_cbranch_vccz .LBB0_1342
	s_barrier

.LBB0_2185:
	s_add_u32 s22, s18, 0x100
	s_addc_u32 s23, s19, 0
	s_add_i32 s47, 0, 0x10000
	s_cmp_eq_u32 s46, 4
	s_cselect_b32 s31, s7, s23
	s_cselect_b32 s30, s6, s22
	v_add_u32_e32 v142, s47, v1
	s_cselect_b32 s29, s17, s45
	s_cselect_b32 s28, s16, s15
	s_add_i32 s48, 0, 0x14000
	ds_read_b128 v[146:149], v142
	ds_read_b128 v[150:153], v142 offset:1024
	ds_read_b128 v[154:157], v142 offset:2048
	ds_read_b128 v[158:161], v142 offset:3072
	v_add_u32_e32 v142, s48, v1
	ds_read_b128 v[162:165], v142
	ds_read_b128 v[166:169], v142 offset:1024
	ds_read_b128 v[170:173], v142 offset:2048
	ds_read_b128 v[174:177], v142 offset:3072
	v_lshl_add_u64 v[142:143], s[18:19], 0, v[138:139]
	s_add_i32 m0, s20, 0xc000
	ds_read_b128 v[178:181], v144
	ds_read_b128 v[182:185], v144 offset:1024
	ds_read_b128 v[186:189], v144 offset:2048
	ds_read_b128 v[196:199], v144 offset:3072
	ds_read_b128 v[200:203], v144 offset:4096
	ds_read_b128 v[204:207], v144 offset:5120
	ds_read_b128 v[208:211], v144 offset:6144
	ds_read_b128 v[212:215], v144 offset:7168
	global_load_lds_dwordx4 v[142:143], off
	v_lshl_add_u64 v[142:143], s[18:19], 0, v[140:141]
	s_add_i32 m0, s20, 0xe000
	s_nop 0
	global_load_lds_dwordx4 v[142:143], off
	s_waitcnt vmcnt(8)
	s_waitcnt lgkmcnt(0)
	s_barrier
	s_waitcnt lgkmcnt(0)
	v_mfma_f32_16x16x32_bf16 v[126:129], v[146:149], v[178:181], v[126:129]
	v_mfma_f32_16x16x32_bf16 v[122:125], v[154:157], v[178:181], v[122:125]
	v_mfma_f32_16x16x32_bf16 v[118:121], v[146:149], v[186:189], v[118:121]
	v_mfma_f32_16x16x32_bf16 v[110:113], v[154:157], v[186:189], v[110:113]
	v_mfma_f32_16x16x32_bf16 v[102:105], v[146:149], v[200:203], v[102:105]
	v_mfma_f32_16x16x32_bf16 v[94:97], v[154:157], v[200:203], v[94:97]
	v_mfma_f32_16x16x32_bf16 v[86:89], v[146:149], v[208:211], v[86:89]
	v_mfma_f32_16x16x32_bf16 v[78:81], v[154:157], v[208:211], v[78:81]
	v_mfma_f32_16x16x32_bf16 v[126:129], v[150:153], v[182:185], v[126:129]
	v_mfma_f32_16x16x32_bf16 v[122:125], v[158:161], v[182:185], v[122:125]
	v_mfma_f32_16x16x32_bf16 v[118:121], v[150:153], v[196:199], v[118:121]
	v_mfma_f32_16x16x32_bf16 v[110:113], v[158:161], v[196:199], v[110:113]
	v_mfma_f32_16x16x32_bf16 v[102:105], v[150:153], v[204:207], v[102:105]
	v_mfma_f32_16x16x32_bf16 v[94:97], v[158:161], v[204:207], v[94:97]
	v_mfma_f32_16x16x32_bf16 v[86:89], v[150:153], v[212:215], v[86:89]
	v_mfma_f32_16x16x32_bf16 v[78:81], v[158:161], v[212:215], v[78:81]
	v_mfma_f32_16x16x32_bf16 v[114:117], v[162:165], v[178:181], v[114:117]
	v_mfma_f32_16x16x32_bf16 v[106:109], v[170:173], v[178:181], v[106:109]
	v_mfma_f32_16x16x32_bf16 v[98:101], v[162:165], v[186:189], v[98:101]
	v_mfma_f32_16x16x32_bf16 v[90:93], v[170:173], v[186:189], v[90:93]
	v_mfma_f32_16x16x32_bf16 v[82:85], v[162:165], v[200:203], v[82:85]
	v_mfma_f32_16x16x32_bf16 v[74:77], v[170:173], v[200:203], v[74:77]
	v_mfma_f32_16x16x32_bf16 v[70:73], v[162:165], v[208:211], v[70:73]
	v_mfma_f32_16x16x32_bf16 v[66:69], v[170:173], v[208:211], v[66:69]
	v_mfma_f32_16x16x32_bf16 v[114:117], v[166:169], v[182:185], v[114:117]
	v_mfma_f32_16x16x32_bf16 v[106:109], v[174:177], v[182:185], v[106:109]
	v_mfma_f32_16x16x32_bf16 v[98:101], v[166:169], v[196:199], v[98:101]
	v_mfma_f32_16x16x32_bf16 v[90:93], v[174:177], v[196:199], v[90:93]
	v_mfma_f32_16x16x32_bf16 v[82:85], v[166:169], v[204:207], v[82:85]
	v_mfma_f32_16x16x32_bf16 v[74:77], v[174:177], v[204:207], v[74:77]
	v_mfma_f32_16x16x32_bf16 v[70:73], v[166:169], v[212:215], v[70:73]
	v_mfma_f32_16x16x32_bf16 v[66:69], v[174:177], v[212:215], v[66:69]
	s_barrier
	s_add_i32 s18, s47, s2
	v_lshl_add_u64 v[142:143], s[28:29], 0, v[132:133]
	s_mov_b32 m0, s18
	ds_read_b128 v[178:181], v144 offset:16384
	ds_read_b128 v[182:185], v144 offset:17408
	ds_read_b128 v[186:189], v144 offset:18432
	ds_read_b128 v[196:199], v144 offset:19456
	ds_read_b128 v[200:203], v144 offset:20480
	ds_read_b128 v[204:207], v144 offset:21504
	ds_read_b128 v[208:211], v144 offset:22528
	ds_read_b128 v[212:215], v144 offset:23552
	global_load_lds_dwordx4 v[142:143], off
	s_add_i32 m0, s18, 0x2000
	s_add_u32 s18, s28, 0x20000
	v_lshl_add_u64 v[192:193], s[28:29], 0, v[136:137]
	s_addc_u32 s19, s29, 0
	s_add_i32 s47, s48, s2
	global_load_lds_dwordx4 v[192:193], off
	v_lshl_add_u64 v[194:195], s[18:19], 0, v[132:133]
	s_mov_b32 m0, s47
	v_lshl_add_u64 v[222:223], s[30:31], 0, v[134:135]
	global_load_lds_dwordx4 v[194:195], off
	v_lshl_add_u64 v[194:195], s[18:19], 0, v[136:137]
	s_add_i32 m0, s47, 0x2000
	s_nop 0
	global_load_lds_dwordx4 v[194:195], off
	v_lshl_add_u64 v[194:195], s[30:31], 0, v[130:131]
	s_mov_b32 m0, s20
	s_nop 0
	global_load_lds_dwordx4 v[194:195], off
	s_mov_b32 m0, s21
	s_nop 0
	global_load_lds_dwordx4 v[222:223], off
	s_waitcnt vmcnt(8)
	s_waitcnt lgkmcnt(0)
	s_barrier
	s_waitcnt lgkmcnt(0)
	v_mfma_f32_16x16x32_bf16 v[46:49], v[146:149], v[178:181], v[46:49]
	v_mfma_f32_16x16x32_bf16 v[42:45], v[154:157], v[178:181], v[42:45]
	v_mfma_f32_16x16x32_bf16 v[38:41], v[146:149], v[186:189], v[38:41]
	v_mfma_f32_16x16x32_bf16 v[30:33], v[154:157], v[186:189], v[30:33]
	v_mfma_f32_16x16x32_bf16 v[22:25], v[146:149], v[200:203], v[22:25]
	v_mfma_f32_16x16x32_bf16 v[14:17], v[154:157], v[200:203], v[14:17]
	v_mfma_f32_16x16x32_bf16 v[6:9], v[146:149], v[208:211], v[6:9]
	v_mfma_f32_16x16x32_bf16 v[2:5], v[154:157], v[208:211], v[2:5]
	v_mfma_f32_16x16x32_bf16 v[46:49], v[150:153], v[182:185], v[46:49]
	v_mfma_f32_16x16x32_bf16 v[42:45], v[158:161], v[182:185], v[42:45]
	v_mfma_f32_16x16x32_bf16 v[38:41], v[150:153], v[196:199], v[38:41]
	v_mfma_f32_16x16x32_bf16 v[30:33], v[158:161], v[196:199], v[30:33]
	v_mfma_f32_16x16x32_bf16 v[22:25], v[150:153], v[204:207], v[22:25]
	v_mfma_f32_16x16x32_bf16 v[14:17], v[158:161], v[204:207], v[14:17]
	v_mfma_f32_16x16x32_bf16 v[6:9], v[150:153], v[212:215], v[6:9]
	v_mfma_f32_16x16x32_bf16 v[2:5], v[158:161], v[212:215], v[2:5]
	v_mfma_f32_16x16x32_bf16 v[34:37], v[162:165], v[178:181], v[34:37]
	v_mfma_f32_16x16x32_bf16 v[26:29], v[170:173], v[178:181], v[26:29]
	v_mfma_f32_16x16x32_bf16 v[18:21], v[162:165], v[186:189], v[18:21]
	v_mfma_f32_16x16x32_bf16 v[10:13], v[170:173], v[186:189], v[10:13]
	v_mfma_f32_16x16x32_bf16 v[58:61], v[162:165], v[200:203], v[58:61]
	v_mfma_f32_16x16x32_bf16 v[62:65], v[170:173], v[200:203], v[62:65]
	v_mfma_f32_16x16x32_bf16 v[50:53], v[162:165], v[208:211], v[50:53]
	v_mfma_f32_16x16x32_bf16 v[54:57], v[170:173], v[208:211], v[54:57]
	v_mfma_f32_16x16x32_bf16 v[34:37], v[166:169], v[182:185], v[34:37]
	v_mfma_f32_16x16x32_bf16 v[26:29], v[174:177], v[182:185], v[26:29]
	v_mfma_f32_16x16x32_bf16 v[18:21], v[166:169], v[196:199], v[18:21]
	v_mfma_f32_16x16x32_bf16 v[10:13], v[174:177], v[196:199], v[10:13]
	v_mfma_f32_16x16x32_bf16 v[58:61], v[166:169], v[204:207], v[58:61]
	v_mfma_f32_16x16x32_bf16 v[62:65], v[174:177], v[204:207], v[62:65]
	v_mfma_f32_16x16x32_bf16 v[50:53], v[166:169], v[212:215], v[50:53]
	v_mfma_f32_16x16x32_bf16 v[54:57], v[174:177], v[212:215], v[54:57]
	s_barrier
	s_add_i32 s47, 0, 0x18000
	v_add_u32_e32 v145, s47, v1
	s_add_i32 s48, 0, 0x1c000
	ds_read_b128 v[146:149], v145
	ds_read_b128 v[150:153], v145 offset:1024
	ds_read_b128 v[154:157], v145 offset:2048
	ds_read_b128 v[158:161], v145 offset:3072
	v_add_u32_e32 v145, s48, v1
	ds_read_b128 v[162:165], v145
	ds_read_b128 v[166:169], v145 offset:1024
	ds_read_b128 v[170:173], v145 offset:2048
	ds_read_b128 v[174:177], v145 offset:3072
	s_add_u32 s18, s30, 0x30000
	s_addc_u32 s19, s31, 0
	s_mov_b32 m0, s26
	v_lshl_add_u64 v[224:225], s[18:19], 0, v[130:131]
	ds_read_b128 v[178:181], v144 offset:32768
	ds_read_b128 v[182:185], v144 offset:33792
	ds_read_b128 v[186:189], v144 offset:34816
	ds_read_b128 v[196:199], v144 offset:35840
	ds_read_b128 v[200:203], v144 offset:36864
	ds_read_b128 v[204:207], v144 offset:37888
	ds_read_b128 v[208:211], v144 offset:38912
	ds_read_b128 v[212:215], v144 offset:39936
	global_load_lds_dwordx4 v[224:225], off
	v_lshl_add_u64 v[224:225], s[18:19], 0, v[134:135]
	s_mov_b32 m0, s27
	s_nop 0
	global_load_lds_dwordx4 v[224:225], off
	s_waitcnt vmcnt(8)
	s_waitcnt lgkmcnt(0)
	s_barrier
	s_waitcnt lgkmcnt(0)
	v_mfma_f32_16x16x32_bf16 v[126:129], v[146:149], v[178:181], v[126:129]
	v_mfma_f32_16x16x32_bf16 v[122:125], v[154:157], v[178:181], v[122:125]
	v_mfma_f32_16x16x32_bf16 v[118:121], v[146:149], v[186:189], v[118:121]
	v_mfma_f32_16x16x32_bf16 v[110:113], v[154:157], v[186:189], v[110:113]
	v_mfma_f32_16x16x32_bf16 v[102:105], v[146:149], v[200:203], v[102:105]
	v_mfma_f32_16x16x32_bf16 v[94:97], v[154:157], v[200:203], v[94:97]
	v_mfma_f32_16x16x32_bf16 v[86:89], v[146:149], v[208:211], v[86:89]
	v_mfma_f32_16x16x32_bf16 v[78:81], v[154:157], v[208:211], v[78:81]
	v_mfma_f32_16x16x32_bf16 v[126:129], v[150:153], v[182:185], v[126:129]
	v_mfma_f32_16x16x32_bf16 v[122:125], v[158:161], v[182:185], v[122:125]
	v_mfma_f32_16x16x32_bf16 v[118:121], v[150:153], v[196:199], v[118:121]
	v_mfma_f32_16x16x32_bf16 v[110:113], v[158:161], v[196:199], v[110:113]
	v_mfma_f32_16x16x32_bf16 v[102:105], v[150:153], v[204:207], v[102:105]
	v_mfma_f32_16x16x32_bf16 v[94:97], v[158:161], v[204:207], v[94:97]
	v_mfma_f32_16x16x32_bf16 v[86:89], v[150:153], v[212:215], v[86:89]
	v_mfma_f32_16x16x32_bf16 v[78:81], v[158:161], v[212:215], v[78:81]
	v_mfma_f32_16x16x32_bf16 v[114:117], v[162:165], v[178:181], v[114:117]
	v_mfma_f32_16x16x32_bf16 v[106:109], v[170:173], v[178:181], v[106:109]
	v_mfma_f32_16x16x32_bf16 v[98:101], v[162:165], v[186:189], v[98:101]
	v_mfma_f32_16x16x32_bf16 v[90:93], v[170:173], v[186:189], v[90:93]
	v_mfma_f32_16x16x32_bf16 v[82:85], v[162:165], v[200:203], v[82:85]
	v_mfma_f32_16x16x32_bf16 v[74:77], v[170:173], v[200:203], v[74:77]
	v_mfma_f32_16x16x32_bf16 v[70:73], v[162:165], v[208:211], v[70:73]
	v_mfma_f32_16x16x32_bf16 v[66:69], v[170:173], v[208:211], v[66:69]
	v_mfma_f32_16x16x32_bf16 v[114:117], v[166:169], v[182:185], v[114:117]
	v_mfma_f32_16x16x32_bf16 v[106:109], v[174:177], v[182:185], v[106:109]
	v_mfma_f32_16x16x32_bf16 v[98:101], v[166:169], v[196:199], v[98:101]
	v_mfma_f32_16x16x32_bf16 v[90:93], v[174:177], v[196:199], v[90:93]
	v_mfma_f32_16x16x32_bf16 v[82:85], v[166:169], v[204:207], v[82:85]
	v_mfma_f32_16x16x32_bf16 v[74:77], v[174:177], v[204:207], v[74:77]
	v_mfma_f32_16x16x32_bf16 v[70:73], v[166:169], v[212:215], v[70:73]
	v_mfma_f32_16x16x32_bf16 v[66:69], v[174:177], v[212:215], v[66:69]
	s_barrier
	s_add_i32 s18, s47, s2
	v_lshl_add_u64 v[142:143], v[142:143], 0, s[36:37]
	s_mov_b32 m0, s18
	ds_read_b128 v[178:181], v144 offset:49152
	ds_read_b128 v[182:185], v144 offset:50176
	ds_read_b128 v[186:189], v144 offset:51200
	ds_read_b128 v[196:199], v144 offset:52224
	ds_read_b128 v[200:203], v144 offset:53248
	ds_read_b128 v[204:207], v144 offset:54272
	ds_read_b128 v[208:211], v144 offset:55296
	ds_read_b128 v[212:215], v144 offset:56320
	global_load_lds_dwordx4 v[142:143], off
	s_add_i32 m0, s18, 0x2000
	s_add_u32 s18, s28, 0x20080
	v_lshl_add_u64 v[142:143], v[192:193], 0, s[36:37]
	s_addc_u32 s19, s29, 0
	s_add_i32 s28, s48, s2
	global_load_lds_dwordx4 v[142:143], off
	v_lshl_add_u64 v[142:143], s[18:19], 0, v[132:133]
	s_mov_b32 m0, s28
	s_nop 0
	global_load_lds_dwordx4 v[142:143], off
	v_lshl_add_u64 v[142:143], s[18:19], 0, v[136:137]
	s_add_i32 m0, s28, 0x2000
	s_nop 0
	global_load_lds_dwordx4 v[142:143], off
	v_lshl_add_u64 v[142:143], v[194:195], 0, s[36:37]
	s_mov_b32 m0, s39
	s_nop 0
	global_load_lds_dwordx4 v[142:143], off
	v_lshl_add_u64 v[142:143], v[222:223], 0, s[36:37]
	s_mov_b32 m0, s40
	s_nop 0
	global_load_lds_dwordx4 v[142:143], off
	s_waitcnt vmcnt(8)
	s_waitcnt lgkmcnt(0)
	s_barrier
	s_waitcnt lgkmcnt(0)
	v_mfma_f32_16x16x32_bf16 v[46:49], v[146:149], v[178:181], v[46:49]
	v_mfma_f32_16x16x32_bf16 v[42:45], v[154:157], v[178:181], v[42:45]
	v_mfma_f32_16x16x32_bf16 v[38:41], v[146:149], v[186:189], v[38:41]
	v_mfma_f32_16x16x32_bf16 v[30:33], v[154:157], v[186:189], v[30:33]
	v_mfma_f32_16x16x32_bf16 v[22:25], v[146:149], v[200:203], v[22:25]
	v_mfma_f32_16x16x32_bf16 v[14:17], v[154:157], v[200:203], v[14:17]
	v_mfma_f32_16x16x32_bf16 v[6:9], v[146:149], v[208:211], v[6:9]
	v_mfma_f32_16x16x32_bf16 v[2:5], v[154:157], v[208:211], v[2:5]
	v_mfma_f32_16x16x32_bf16 v[46:49], v[150:153], v[182:185], v[46:49]
	v_mfma_f32_16x16x32_bf16 v[42:45], v[158:161], v[182:185], v[42:45]
	v_mfma_f32_16x16x32_bf16 v[38:41], v[150:153], v[196:199], v[38:41]
	v_mfma_f32_16x16x32_bf16 v[30:33], v[158:161], v[196:199], v[30:33]
	v_mfma_f32_16x16x32_bf16 v[22:25], v[150:153], v[204:207], v[22:25]
	v_mfma_f32_16x16x32_bf16 v[14:17], v[158:161], v[204:207], v[14:17]
	v_mfma_f32_16x16x32_bf16 v[6:9], v[150:153], v[212:215], v[6:9]
	v_mfma_f32_16x16x32_bf16 v[2:5], v[158:161], v[212:215], v[2:5]
	v_mfma_f32_16x16x32_bf16 v[34:37], v[162:165], v[178:181], v[34:37]
	v_mfma_f32_16x16x32_bf16 v[26:29], v[170:173], v[178:181], v[26:29]
	v_mfma_f32_16x16x32_bf16 v[18:21], v[162:165], v[186:189], v[18:21]
	v_mfma_f32_16x16x32_bf16 v[10:13], v[170:173], v[186:189], v[10:13]
	v_mfma_f32_16x16x32_bf16 v[58:61], v[162:165], v[200:203], v[58:61]
	v_mfma_f32_16x16x32_bf16 v[62:65], v[170:173], v[200:203], v[62:65]
	v_mfma_f32_16x16x32_bf16 v[50:53], v[162:165], v[208:211], v[50:53]
	v_mfma_f32_16x16x32_bf16 v[54:57], v[170:173], v[208:211], v[54:57]
	v_mfma_f32_16x16x32_bf16 v[34:37], v[166:169], v[182:185], v[34:37]
	v_mfma_f32_16x16x32_bf16 v[26:29], v[174:177], v[182:185], v[26:29]
	v_mfma_f32_16x16x32_bf16 v[18:21], v[166:169], v[196:199], v[18:21]
	v_mfma_f32_16x16x32_bf16 v[10:13], v[174:177], v[196:199], v[10:13]
	v_mfma_f32_16x16x32_bf16 v[58:61], v[166:169], v[204:207], v[58:61]
	v_mfma_f32_16x16x32_bf16 v[62:65], v[174:177], v[204:207], v[62:65]
	v_mfma_f32_16x16x32_bf16 v[50:53], v[166:169], v[212:215], v[50:53]
	v_mfma_f32_16x16x32_bf16 v[54:57], v[174:177], v[212:215], v[54:57]
	s_barrier
	s_add_i32 s46, s46, 2
	s_add_u32 s15, s15, 0x100
	s_addc_u32 s45, s45, 0
	s_cmp_gt_u32 s46, 5
	s_mov_b64 s[18:19], s[22:23]
	s_cbranch_scc0 .LBB0_2185
	s_and_b64 vcc, exec, s[10:11]
	s_cbranch_vccz .LBB0_2188
	s_barrier

.LBB0_2594:
	s_add_u32 s16, s14, 0x100
	s_addc_u32 s17, s15, 0
	s_add_i32 s38, 0, 0x10000
	s_cmp_eq_u32 s29, 8
	s_cselect_b32 s23, s5, s17
	s_cselect_b32 s22, s4, s16
	v_add_u32_e32 v142, s38, v1
	s_cselect_b32 s19, s13, s28
	s_cselect_b32 s18, s12, s26
	s_add_i32 s40, 0, 0x14000
	ds_read_b128 v[138:141], v142
	ds_read_b128 v[146:149], v142 offset:1024
	ds_read_b128 v[150:153], v142 offset:2048
	ds_read_b128 v[154:157], v142 offset:3072
	v_add_u32_e32 v142, s40, v1
	ds_read_b128 v[158:161], v142
	ds_read_b128 v[162:165], v142 offset:1024
	ds_read_b128 v[166:169], v142 offset:2048
	ds_read_b128 v[170:173], v142 offset:3072
	v_lshl_add_u64 v[142:143], s[14:15], 0, v[134:135]
	s_add_i32 m0, s30, 0xc000
	ds_read_b128 v[174:177], v144
	ds_read_b128 v[178:181], v144 offset:1024
	ds_read_b128 v[182:185], v144 offset:2048
	ds_read_b128 v[186:189], v144 offset:3072
	ds_read_b128 v[192:195], v144 offset:4096
	ds_read_b128 v[196:199], v144 offset:5120
	ds_read_b128 v[200:203], v144 offset:6144
	ds_read_b128 v[204:207], v144 offset:7168
	global_load_lds_dwordx4 v[142:143], off
	v_lshl_add_u64 v[142:143], s[14:15], 0, v[136:137]
	s_add_i32 m0, s30, 0xe000
	s_nop 0
	global_load_lds_dwordx4 v[142:143], off
	s_waitcnt vmcnt(8)
	s_waitcnt lgkmcnt(0)
	s_barrier
	s_waitcnt lgkmcnt(0)
	v_mfma_f32_16x16x32_bf16 v[126:129], v[138:141], v[174:177], v[126:129]
	v_mfma_f32_16x16x32_bf16 v[122:125], v[150:153], v[174:177], v[122:125]
	v_mfma_f32_16x16x32_bf16 v[110:113], v[138:141], v[182:185], v[110:113]
	v_mfma_f32_16x16x32_bf16 v[106:109], v[150:153], v[182:185], v[106:109]
	v_mfma_f32_16x16x32_bf16 v[94:97], v[138:141], v[192:195], v[94:97]
	v_mfma_f32_16x16x32_bf16 v[90:93], v[150:153], v[192:195], v[90:93]
	v_mfma_f32_16x16x32_bf16 v[78:81], v[138:141], v[200:203], v[78:81]
	v_mfma_f32_16x16x32_bf16 v[74:77], v[150:153], v[200:203], v[74:77]
	v_mfma_f32_16x16x32_bf16 v[126:129], v[146:149], v[178:181], v[126:129]
	v_mfma_f32_16x16x32_bf16 v[122:125], v[154:157], v[178:181], v[122:125]
	v_mfma_f32_16x16x32_bf16 v[110:113], v[146:149], v[186:189], v[110:113]
	v_mfma_f32_16x16x32_bf16 v[106:109], v[154:157], v[186:189], v[106:109]
	v_mfma_f32_16x16x32_bf16 v[94:97], v[146:149], v[196:199], v[94:97]
	v_mfma_f32_16x16x32_bf16 v[90:93], v[154:157], v[196:199], v[90:93]
	v_mfma_f32_16x16x32_bf16 v[78:81], v[146:149], v[204:207], v[78:81]
	v_mfma_f32_16x16x32_bf16 v[74:77], v[154:157], v[204:207], v[74:77]
	v_mfma_f32_16x16x32_bf16 v[118:121], v[158:161], v[174:177], v[118:121]
	v_mfma_f32_16x16x32_bf16 v[114:117], v[166:169], v[174:177], v[114:117]
	v_mfma_f32_16x16x32_bf16 v[102:105], v[158:161], v[182:185], v[102:105]
	v_mfma_f32_16x16x32_bf16 v[98:101], v[166:169], v[182:185], v[98:101]
	v_mfma_f32_16x16x32_bf16 v[86:89], v[158:161], v[192:195], v[86:89]
	v_mfma_f32_16x16x32_bf16 v[82:85], v[166:169], v[192:195], v[82:85]
	v_mfma_f32_16x16x32_bf16 v[70:73], v[158:161], v[200:203], v[70:73]
	v_mfma_f32_16x16x32_bf16 v[66:69], v[166:169], v[200:203], v[66:69]
	v_mfma_f32_16x16x32_bf16 v[118:121], v[162:165], v[178:181], v[118:121]
	v_mfma_f32_16x16x32_bf16 v[114:117], v[170:173], v[178:181], v[114:117]
	v_mfma_f32_16x16x32_bf16 v[102:105], v[162:165], v[186:189], v[102:105]
	v_mfma_f32_16x16x32_bf16 v[98:101], v[170:173], v[186:189], v[98:101]
	v_mfma_f32_16x16x32_bf16 v[86:89], v[162:165], v[196:199], v[86:89]
	v_mfma_f32_16x16x32_bf16 v[82:85], v[170:173], v[196:199], v[82:85]
	v_mfma_f32_16x16x32_bf16 v[70:73], v[162:165], v[204:207], v[70:73]
	v_mfma_f32_16x16x32_bf16 v[66:69], v[170:173], v[204:207], v[66:69]
	s_barrier
	s_add_i32 s14, s38, s27
	v_lshl_add_u64 v[142:143], s[18:19], 0, v[130:131]
	s_mov_b32 m0, s14
	ds_read_b128 v[174:177], v144 offset:16384
	ds_read_b128 v[178:181], v144 offset:17408
	ds_read_b128 v[182:185], v144 offset:18432
	ds_read_b128 v[186:189], v144 offset:19456
	ds_read_b128 v[192:195], v144 offset:20480
	ds_read_b128 v[196:199], v144 offset:21504
	ds_read_b128 v[200:203], v144 offset:22528
	ds_read_b128 v[204:207], v144 offset:23552
	global_load_lds_dwordx4 v[142:143], off
	s_add_i32 m0, s14, 0x2000
	s_add_u32 s14, s18, 0x30000
	v_lshl_add_u64 v[208:209], s[18:19], 0, v[132:133]
	s_addc_u32 s15, s19, 0
	s_add_i32 s38, s40, s27
	global_load_lds_dwordx4 v[208:209], off
	v_lshl_add_u64 v[210:211], s[14:15], 0, v[130:131]
	s_mov_b32 m0, s38
	v_lshl_add_u64 v[212:213], s[22:23], 0, v[132:133]
	global_load_lds_dwordx4 v[210:211], off
	v_lshl_add_u64 v[210:211], s[14:15], 0, v[132:133]
	s_add_i32 m0, s38, 0x2000
	s_nop 0
	global_load_lds_dwordx4 v[210:211], off
	v_lshl_add_u64 v[210:211], s[22:23], 0, v[130:131]
	s_mov_b32 m0, s30
	s_nop 0
	global_load_lds_dwordx4 v[210:211], off
	s_mov_b32 m0, s31
	s_nop 0
	global_load_lds_dwordx4 v[212:213], off
	s_waitcnt vmcnt(8)
	s_waitcnt lgkmcnt(0)
	s_barrier
	s_waitcnt lgkmcnt(0)
	v_mfma_f32_16x16x32_bf16 v[62:65], v[138:141], v[174:177], v[62:65]
	v_mfma_f32_16x16x32_bf16 v[58:61], v[150:153], v[174:177], v[58:61]
	v_mfma_f32_16x16x32_bf16 v[46:49], v[138:141], v[182:185], v[46:49]
	v_mfma_f32_16x16x32_bf16 v[42:45], v[150:153], v[182:185], v[42:45]
	v_mfma_f32_16x16x32_bf16 v[30:33], v[138:141], v[192:195], v[30:33]
	v_mfma_f32_16x16x32_bf16 v[26:29], v[150:153], v[192:195], v[26:29]
	v_mfma_f32_16x16x32_bf16 v[14:17], v[138:141], v[200:203], v[14:17]
	v_mfma_f32_16x16x32_bf16 v[10:13], v[150:153], v[200:203], v[10:13]
	v_mfma_f32_16x16x32_bf16 v[62:65], v[146:149], v[178:181], v[62:65]
	v_mfma_f32_16x16x32_bf16 v[58:61], v[154:157], v[178:181], v[58:61]
	v_mfma_f32_16x16x32_bf16 v[46:49], v[146:149], v[186:189], v[46:49]
	v_mfma_f32_16x16x32_bf16 v[42:45], v[154:157], v[186:189], v[42:45]
	v_mfma_f32_16x16x32_bf16 v[30:33], v[146:149], v[196:199], v[30:33]
	v_mfma_f32_16x16x32_bf16 v[26:29], v[154:157], v[196:199], v[26:29]
	v_mfma_f32_16x16x32_bf16 v[14:17], v[146:149], v[204:207], v[14:17]
	v_mfma_f32_16x16x32_bf16 v[10:13], v[154:157], v[204:207], v[10:13]
	v_mfma_f32_16x16x32_bf16 v[54:57], v[158:161], v[174:177], v[54:57]
	v_mfma_f32_16x16x32_bf16 v[50:53], v[166:169], v[174:177], v[50:53]
	v_mfma_f32_16x16x32_bf16 v[38:41], v[158:161], v[182:185], v[38:41]
	v_mfma_f32_16x16x32_bf16 v[34:37], v[166:169], v[182:185], v[34:37]
	v_mfma_f32_16x16x32_bf16 v[22:25], v[158:161], v[192:195], v[22:25]
	v_mfma_f32_16x16x32_bf16 v[18:21], v[166:169], v[192:195], v[18:21]
	v_mfma_f32_16x16x32_bf16 v[6:9], v[158:161], v[200:203], v[6:9]
	v_mfma_f32_16x16x32_bf16 v[2:5], v[166:169], v[200:203], v[2:5]
	v_mfma_f32_16x16x32_bf16 v[54:57], v[162:165], v[178:181], v[54:57]
	v_mfma_f32_16x16x32_bf16 v[50:53], v[170:173], v[178:181], v[50:53]
	v_mfma_f32_16x16x32_bf16 v[38:41], v[162:165], v[186:189], v[38:41]
	v_mfma_f32_16x16x32_bf16 v[34:37], v[170:173], v[186:189], v[34:37]
	v_mfma_f32_16x16x32_bf16 v[22:25], v[162:165], v[196:199], v[22:25]
	v_mfma_f32_16x16x32_bf16 v[18:21], v[170:173], v[196:199], v[18:21]
	v_mfma_f32_16x16x32_bf16 v[6:9], v[162:165], v[204:207], v[6:9]
	v_mfma_f32_16x16x32_bf16 v[2:5], v[170:173], v[204:207], v[2:5]
	s_barrier
	s_add_i32 s38, 0, 0x18000
	v_add_u32_e32 v145, s38, v1
	s_add_i32 s40, 0, 0x1c000
	ds_read_b128 v[138:141], v145
	ds_read_b128 v[146:149], v145 offset:1024
	ds_read_b128 v[150:153], v145 offset:2048
	ds_read_b128 v[154:157], v145 offset:3072
	v_add_u32_e32 v145, s40, v1
	ds_read_b128 v[158:161], v145
	ds_read_b128 v[162:165], v145 offset:1024
	ds_read_b128 v[166:169], v145 offset:2048
	ds_read_b128 v[170:173], v145 offset:3072
	s_add_u32 s14, s22, 0x30000
	s_addc_u32 s15, s23, 0
	s_mov_b32 m0, s39
	v_lshl_add_u64 v[214:215], s[14:15], 0, v[130:131]
	ds_read_b128 v[174:177], v144 offset:32768
	ds_read_b128 v[178:181], v144 offset:33792
	ds_read_b128 v[182:185], v144 offset:34816
	ds_read_b128 v[186:189], v144 offset:35840
	ds_read_b128 v[192:195], v144 offset:36864
	ds_read_b128 v[196:199], v144 offset:37888
	ds_read_b128 v[200:203], v144 offset:38912
	ds_read_b128 v[204:207], v144 offset:39936
	global_load_lds_dwordx4 v[214:215], off
	v_lshl_add_u64 v[214:215], s[14:15], 0, v[132:133]
	s_mov_b32 m0, s41
	s_nop 0
	global_load_lds_dwordx4 v[214:215], off
	s_waitcnt vmcnt(8)
	s_waitcnt lgkmcnt(0)
	s_barrier
	s_waitcnt lgkmcnt(0)
	v_mfma_f32_16x16x32_bf16 v[126:129], v[138:141], v[174:177], v[126:129]
	v_mfma_f32_16x16x32_bf16 v[122:125], v[150:153], v[174:177], v[122:125]
	v_mfma_f32_16x16x32_bf16 v[110:113], v[138:141], v[182:185], v[110:113]
	v_mfma_f32_16x16x32_bf16 v[106:109], v[150:153], v[182:185], v[106:109]
	v_mfma_f32_16x16x32_bf16 v[94:97], v[138:141], v[192:195], v[94:97]
	v_mfma_f32_16x16x32_bf16 v[90:93], v[150:153], v[192:195], v[90:93]
	v_mfma_f32_16x16x32_bf16 v[78:81], v[138:141], v[200:203], v[78:81]
	v_mfma_f32_16x16x32_bf16 v[74:77], v[150:153], v[200:203], v[74:77]
	v_mfma_f32_16x16x32_bf16 v[126:129], v[146:149], v[178:181], v[126:129]
	v_mfma_f32_16x16x32_bf16 v[122:125], v[154:157], v[178:181], v[122:125]
	v_mfma_f32_16x16x32_bf16 v[110:113], v[146:149], v[186:189], v[110:113]
	v_mfma_f32_16x16x32_bf16 v[106:109], v[154:157], v[186:189], v[106:109]
	v_mfma_f32_16x16x32_bf16 v[94:97], v[146:149], v[196:199], v[94:97]
	v_mfma_f32_16x16x32_bf16 v[90:93], v[154:157], v[196:199], v[90:93]
	v_mfma_f32_16x16x32_bf16 v[78:81], v[146:149], v[204:207], v[78:81]
	v_mfma_f32_16x16x32_bf16 v[74:77], v[154:157], v[204:207], v[74:77]
	v_mfma_f32_16x16x32_bf16 v[118:121], v[158:161], v[174:177], v[118:121]
	v_mfma_f32_16x16x32_bf16 v[114:117], v[166:169], v[174:177], v[114:117]
	v_mfma_f32_16x16x32_bf16 v[102:105], v[158:161], v[182:185], v[102:105]
	v_mfma_f32_16x16x32_bf16 v[98:101], v[166:169], v[182:185], v[98:101]
	v_mfma_f32_16x16x32_bf16 v[86:89], v[158:161], v[192:195], v[86:89]
	v_mfma_f32_16x16x32_bf16 v[82:85], v[166:169], v[192:195], v[82:85]
	v_mfma_f32_16x16x32_bf16 v[70:73], v[158:161], v[200:203], v[70:73]
	v_mfma_f32_16x16x32_bf16 v[66:69], v[166:169], v[200:203], v[66:69]
	v_mfma_f32_16x16x32_bf16 v[118:121], v[162:165], v[178:181], v[118:121]
	v_mfma_f32_16x16x32_bf16 v[114:117], v[170:173], v[178:181], v[114:117]
	v_mfma_f32_16x16x32_bf16 v[102:105], v[162:165], v[186:189], v[102:105]
	v_mfma_f32_16x16x32_bf16 v[98:101], v[170:173], v[186:189], v[98:101]
	v_mfma_f32_16x16x32_bf16 v[86:89], v[162:165], v[196:199], v[86:89]
	v_mfma_f32_16x16x32_bf16 v[82:85], v[170:173], v[196:199], v[82:85]
	v_mfma_f32_16x16x32_bf16 v[70:73], v[162:165], v[204:207], v[70:73]
	v_mfma_f32_16x16x32_bf16 v[66:69], v[170:173], v[204:207], v[66:69]
	s_barrier
	s_add_i32 s14, s38, s27
	v_lshl_add_u64 v[142:143], v[142:143], 0, s[36:37]
	s_mov_b32 m0, s14
	ds_read_b128 v[174:177], v144 offset:49152
	ds_read_b128 v[178:181], v144 offset:50176
	ds_read_b128 v[182:185], v144 offset:51200
	ds_read_b128 v[186:189], v144 offset:52224
	ds_read_b128 v[192:195], v144 offset:53248
	ds_read_b128 v[196:199], v144 offset:54272
	ds_read_b128 v[200:203], v144 offset:55296
	ds_read_b128 v[204:207], v144 offset:56320
	global_load_lds_dwordx4 v[142:143], off
	s_add_i32 m0, s14, 0x2000
	s_add_u32 s14, s18, 0x30080
	v_lshl_add_u64 v[142:143], v[208:209], 0, s[36:37]
	s_addc_u32 s15, s19, 0
	s_add_i32 s18, s40, s27
	global_load_lds_dwordx4 v[142:143], off
	v_lshl_add_u64 v[142:143], s[14:15], 0, v[130:131]
	s_mov_b32 m0, s18
	s_nop 0
	global_load_lds_dwordx4 v[142:143], off
	v_lshl_add_u64 v[142:143], s[14:15], 0, v[132:133]
	s_add_i32 m0, s18, 0x2000
	s_nop 0
	global_load_lds_dwordx4 v[142:143], off
	v_lshl_add_u64 v[142:143], v[210:211], 0, s[36:37]
	s_mov_b32 m0, s50
	s_nop 0
	global_load_lds_dwordx4 v[142:143], off
	v_lshl_add_u64 v[142:143], v[212:213], 0, s[36:37]
	s_mov_b32 m0, s51
	s_nop 0
	global_load_lds_dwordx4 v[142:143], off
	s_waitcnt vmcnt(8)
	s_waitcnt lgkmcnt(0)
	s_barrier
	s_waitcnt lgkmcnt(0)
	v_mfma_f32_16x16x32_bf16 v[62:65], v[138:141], v[174:177], v[62:65]
	v_mfma_f32_16x16x32_bf16 v[58:61], v[150:153], v[174:177], v[58:61]
	v_mfma_f32_16x16x32_bf16 v[46:49], v[138:141], v[182:185], v[46:49]
	v_mfma_f32_16x16x32_bf16 v[42:45], v[150:153], v[182:185], v[42:45]
	v_mfma_f32_16x16x32_bf16 v[30:33], v[138:141], v[192:195], v[30:33]
	v_mfma_f32_16x16x32_bf16 v[26:29], v[150:153], v[192:195], v[26:29]
	v_mfma_f32_16x16x32_bf16 v[14:17], v[138:141], v[200:203], v[14:17]
	v_mfma_f32_16x16x32_bf16 v[10:13], v[150:153], v[200:203], v[10:13]
	v_mfma_f32_16x16x32_bf16 v[62:65], v[146:149], v[178:181], v[62:65]
	v_mfma_f32_16x16x32_bf16 v[58:61], v[154:157], v[178:181], v[58:61]
	v_mfma_f32_16x16x32_bf16 v[46:49], v[146:149], v[186:189], v[46:49]
	v_mfma_f32_16x16x32_bf16 v[42:45], v[154:157], v[186:189], v[42:45]
	v_mfma_f32_16x16x32_bf16 v[30:33], v[146:149], v[196:199], v[30:33]
	v_mfma_f32_16x16x32_bf16 v[26:29], v[154:157], v[196:199], v[26:29]
	v_mfma_f32_16x16x32_bf16 v[14:17], v[146:149], v[204:207], v[14:17]
	v_mfma_f32_16x16x32_bf16 v[10:13], v[154:157], v[204:207], v[10:13]
	v_mfma_f32_16x16x32_bf16 v[54:57], v[158:161], v[174:177], v[54:57]
	v_mfma_f32_16x16x32_bf16 v[50:53], v[166:169], v[174:177], v[50:53]
	v_mfma_f32_16x16x32_bf16 v[38:41], v[158:161], v[182:185], v[38:41]
	v_mfma_f32_16x16x32_bf16 v[34:37], v[166:169], v[182:185], v[34:37]
	v_mfma_f32_16x16x32_bf16 v[22:25], v[158:161], v[192:195], v[22:25]
	v_mfma_f32_16x16x32_bf16 v[18:21], v[166:169], v[192:195], v[18:21]
	v_mfma_f32_16x16x32_bf16 v[6:9], v[158:161], v[200:203], v[6:9]
	v_mfma_f32_16x16x32_bf16 v[2:5], v[166:169], v[200:203], v[2:5]
	v_mfma_f32_16x16x32_bf16 v[54:57], v[162:165], v[178:181], v[54:57]
	v_mfma_f32_16x16x32_bf16 v[50:53], v[170:173], v[178:181], v[50:53]
	v_mfma_f32_16x16x32_bf16 v[38:41], v[162:165], v[186:189], v[38:41]
	v_mfma_f32_16x16x32_bf16 v[34:37], v[170:173], v[186:189], v[34:37]
	v_mfma_f32_16x16x32_bf16 v[22:25], v[162:165], v[196:199], v[22:25]
	v_mfma_f32_16x16x32_bf16 v[18:21], v[170:173], v[196:199], v[18:21]
	v_mfma_f32_16x16x32_bf16 v[6:9], v[162:165], v[204:207], v[6:9]
	v_mfma_f32_16x16x32_bf16 v[2:5], v[170:173], v[204:207], v[2:5]
	s_barrier
	s_add_i32 s29, s29, 2
	s_add_u32 s26, s26, 0x100
	s_addc_u32 s28, s28, 0
	s_cmp_gt_u32 s29, 9
	s_mov_b64 s[14:15], s[16:17]
	s_cbranch_scc0 .LBB0_2594
	s_and_b64 vcc, exec, s[10:11]
	s_cbranch_vccz .LBB0_2597
	s_barrier

.LBB0_2717:
	s_add_u32 s30, s28, 0xfffe0080
	s_addc_u32 s31, s29, -1
	s_add_i32 s55, 0, 0x10000
	s_cmp_eq_u32 s40, 4
	s_cselect_b32 s43, s0, s31
	s_cselect_b32 s42, s13, s30
	v_add_u32_e32 v140, s55, v1
	s_cselect_b32 s31, s19, s38
	s_cselect_b32 s30, s20, s26
	s_add_i32 s58, 0, 0x14000
	ds_read_b128 v[136:139], v140
	ds_read_b128 v[144:147], v140 offset:1024
	ds_read_b128 v[148:151], v140 offset:2048
	ds_read_b128 v[152:155], v140 offset:3072
	v_add_u32_e32 v140, s58, v1
	ds_read_b128 v[156:159], v140
	ds_read_b128 v[160:163], v140 offset:1024
	ds_read_b128 v[164:167], v140 offset:2048
	ds_read_b128 v[168:171], v140 offset:3072
	v_lshl_add_u64 v[140:141], s[28:29], 0, v[132:133]
	s_add_i32 m0, s23, 0xc000
	ds_read_b128 v[172:175], v142
	ds_read_b128 v[176:179], v142 offset:1024
	ds_read_b128 v[180:183], v142 offset:2048
	ds_read_b128 v[184:187], v142 offset:3072
	ds_read_b128 v[192:195], v142 offset:4096
	ds_read_b128 v[196:199], v142 offset:5120
	ds_read_b128 v[200:203], v142 offset:6144
	ds_read_b128 v[204:207], v142 offset:7168
	global_load_lds_dwordx4 v[140:141], off
	v_lshl_add_u64 v[140:141], s[28:29], 0, v[134:135]
	s_add_i32 m0, s23, 0xe000
	s_nop 0
	global_load_lds_dwordx4 v[140:141], off
	s_waitcnt vmcnt(8)
	s_waitcnt lgkmcnt(0)
	s_barrier
	s_waitcnt lgkmcnt(0)
	v_mfma_f32_16x16x32_bf16 v[126:129], v[136:139], v[172:175], v[126:129]
	v_mfma_f32_16x16x32_bf16 v[122:125], v[148:151], v[172:175], v[122:125]
	v_mfma_f32_16x16x32_bf16 v[110:113], v[136:139], v[180:183], v[110:113]
	v_mfma_f32_16x16x32_bf16 v[106:109], v[148:151], v[180:183], v[106:109]
	v_mfma_f32_16x16x32_bf16 v[94:97], v[136:139], v[192:195], v[94:97]
	v_mfma_f32_16x16x32_bf16 v[90:93], v[148:151], v[192:195], v[90:93]
	v_mfma_f32_16x16x32_bf16 v[78:81], v[136:139], v[200:203], v[78:81]
	v_mfma_f32_16x16x32_bf16 v[74:77], v[148:151], v[200:203], v[74:77]
	v_mfma_f32_16x16x32_bf16 v[126:129], v[144:147], v[176:179], v[126:129]
	v_mfma_f32_16x16x32_bf16 v[122:125], v[152:155], v[176:179], v[122:125]
	v_mfma_f32_16x16x32_bf16 v[110:113], v[144:147], v[184:187], v[110:113]
	v_mfma_f32_16x16x32_bf16 v[106:109], v[152:155], v[184:187], v[106:109]
	v_mfma_f32_16x16x32_bf16 v[94:97], v[144:147], v[196:199], v[94:97]
	v_mfma_f32_16x16x32_bf16 v[90:93], v[152:155], v[196:199], v[90:93]
	v_mfma_f32_16x16x32_bf16 v[78:81], v[144:147], v[204:207], v[78:81]
	v_mfma_f32_16x16x32_bf16 v[74:77], v[152:155], v[204:207], v[74:77]
	v_mfma_f32_16x16x32_bf16 v[118:121], v[156:159], v[172:175], v[118:121]
	v_mfma_f32_16x16x32_bf16 v[114:117], v[164:167], v[172:175], v[114:117]
	v_mfma_f32_16x16x32_bf16 v[102:105], v[156:159], v[180:183], v[102:105]
	v_mfma_f32_16x16x32_bf16 v[98:101], v[164:167], v[180:183], v[98:101]
	v_mfma_f32_16x16x32_bf16 v[86:89], v[156:159], v[192:195], v[86:89]
	v_mfma_f32_16x16x32_bf16 v[82:85], v[164:167], v[192:195], v[82:85]
	v_mfma_f32_16x16x32_bf16 v[70:73], v[156:159], v[200:203], v[70:73]
	v_mfma_f32_16x16x32_bf16 v[66:69], v[164:167], v[200:203], v[66:69]
	v_mfma_f32_16x16x32_bf16 v[118:121], v[160:163], v[176:179], v[118:121]
	v_mfma_f32_16x16x32_bf16 v[114:117], v[168:171], v[176:179], v[114:117]
	v_mfma_f32_16x16x32_bf16 v[102:105], v[160:163], v[184:187], v[102:105]
	v_mfma_f32_16x16x32_bf16 v[98:101], v[168:171], v[184:187], v[98:101]
	v_mfma_f32_16x16x32_bf16 v[86:89], v[160:163], v[196:199], v[86:89]
	v_mfma_f32_16x16x32_bf16 v[82:85], v[168:171], v[196:199], v[82:85]
	v_mfma_f32_16x16x32_bf16 v[70:73], v[160:163], v[204:207], v[70:73]
	v_mfma_f32_16x16x32_bf16 v[66:69], v[168:171], v[204:207], v[66:69]
	s_barrier
	s_add_i32 s55, s55, s46
	v_lshl_add_u64 v[140:141], s[30:31], 0, v[190:191]
	s_mov_b32 m0, s55
	ds_read_b128 v[172:175], v142 offset:16384
	ds_read_b128 v[176:179], v142 offset:17408
	ds_read_b128 v[180:183], v142 offset:18432
	ds_read_b128 v[184:187], v142 offset:19456
	ds_read_b128 v[192:195], v142 offset:20480
	ds_read_b128 v[196:199], v142 offset:21504
	ds_read_b128 v[200:203], v142 offset:22528
	ds_read_b128 v[204:207], v142 offset:23552
	global_load_lds_dwordx4 v[140:141], off
	s_add_i32 m0, s55, 0x2000
	s_add_u32 s56, s30, 0x20000
	v_lshl_add_u64 v[188:189], s[30:31], 0, v[130:131]
	s_addc_u32 s57, s31, 0
	s_add_i32 s55, s58, s46
	global_load_lds_dwordx4 v[188:189], off
	v_lshl_add_u64 v[208:209], s[56:57], 0, v[190:191]
	s_mov_b32 m0, s55
	v_lshl_add_u64 v[210:211], s[42:43], 0, v[130:131]
	global_load_lds_dwordx4 v[208:209], off
	v_lshl_add_u64 v[208:209], s[56:57], 0, v[130:131]
	s_add_i32 m0, s55, 0x2000
	s_nop 0
	global_load_lds_dwordx4 v[208:209], off
	v_lshl_add_u64 v[208:209], s[42:43], 0, v[190:191]
	s_mov_b32 m0, s23
	s_nop 0
	global_load_lds_dwordx4 v[208:209], off
	s_mov_b32 m0, s47
	s_nop 0
	global_load_lds_dwordx4 v[210:211], off
	s_waitcnt vmcnt(8)
	s_waitcnt lgkmcnt(0)
	s_barrier
	s_waitcnt lgkmcnt(0)
	v_mfma_f32_16x16x32_bf16 v[62:65], v[136:139], v[172:175], v[62:65]
	v_mfma_f32_16x16x32_bf16 v[58:61], v[148:151], v[172:175], v[58:61]
	v_mfma_f32_16x16x32_bf16 v[46:49], v[136:139], v[180:183], v[46:49]
	v_mfma_f32_16x16x32_bf16 v[42:45], v[148:151], v[180:183], v[42:45]
	v_mfma_f32_16x16x32_bf16 v[30:33], v[136:139], v[192:195], v[30:33]
	v_mfma_f32_16x16x32_bf16 v[22:25], v[148:151], v[192:195], v[22:25]
	v_mfma_f32_16x16x32_bf16 v[14:17], v[136:139], v[200:203], v[14:17]
	v_mfma_f32_16x16x32_bf16 v[6:9], v[148:151], v[200:203], v[6:9]
	v_mfma_f32_16x16x32_bf16 v[62:65], v[144:147], v[176:179], v[62:65]
	v_mfma_f32_16x16x32_bf16 v[58:61], v[152:155], v[176:179], v[58:61]
	v_mfma_f32_16x16x32_bf16 v[46:49], v[144:147], v[184:187], v[46:49]
	v_mfma_f32_16x16x32_bf16 v[42:45], v[152:155], v[184:187], v[42:45]
	v_mfma_f32_16x16x32_bf16 v[30:33], v[144:147], v[196:199], v[30:33]
	v_mfma_f32_16x16x32_bf16 v[22:25], v[152:155], v[196:199], v[22:25]
	v_mfma_f32_16x16x32_bf16 v[14:17], v[144:147], v[204:207], v[14:17]
	v_mfma_f32_16x16x32_bf16 v[6:9], v[152:155], v[204:207], v[6:9]
	v_mfma_f32_16x16x32_bf16 v[54:57], v[156:159], v[172:175], v[54:57]
	v_mfma_f32_16x16x32_bf16 v[50:53], v[164:167], v[172:175], v[50:53]
	v_mfma_f32_16x16x32_bf16 v[38:41], v[156:159], v[180:183], v[38:41]
	v_mfma_f32_16x16x32_bf16 v[34:37], v[164:167], v[180:183], v[34:37]
	v_mfma_f32_16x16x32_bf16 v[26:29], v[156:159], v[192:195], v[26:29]
	v_mfma_f32_16x16x32_bf16 v[18:21], v[164:167], v[192:195], v[18:21]
	v_mfma_f32_16x16x32_bf16 v[10:13], v[156:159], v[200:203], v[10:13]
	v_mfma_f32_16x16x32_bf16 v[2:5], v[164:167], v[200:203], v[2:5]
	v_mfma_f32_16x16x32_bf16 v[54:57], v[160:163], v[176:179], v[54:57]
	v_mfma_f32_16x16x32_bf16 v[50:53], v[168:171], v[176:179], v[50:53]
	v_mfma_f32_16x16x32_bf16 v[38:41], v[160:163], v[184:187], v[38:41]
	v_mfma_f32_16x16x32_bf16 v[34:37], v[168:171], v[184:187], v[34:37]
	v_mfma_f32_16x16x32_bf16 v[26:29], v[160:163], v[196:199], v[26:29]
	v_mfma_f32_16x16x32_bf16 v[18:21], v[168:171], v[196:199], v[18:21]
	v_mfma_f32_16x16x32_bf16 v[10:13], v[160:163], v[204:207], v[10:13]
	v_mfma_f32_16x16x32_bf16 v[2:5], v[168:171], v[204:207], v[2:5]
	s_barrier
	s_add_i32 s55, 0, 0x18000
	v_add_u32_e32 v143, s55, v1
	s_add_i32 s56, 0, 0x1c000
	ds_read_b128 v[136:139], v143
	ds_read_b128 v[144:147], v143 offset:1024
	ds_read_b128 v[148:151], v143 offset:2048
	ds_read_b128 v[152:155], v143 offset:3072
	v_add_u32_e32 v143, s56, v1
	ds_read_b128 v[156:159], v143
	ds_read_b128 v[160:163], v143 offset:1024
	ds_read_b128 v[164:167], v143 offset:2048
	ds_read_b128 v[168:171], v143 offset:3072
	s_add_u32 s42, s42, 0x20000
	s_addc_u32 s43, s43, 0
	s_mov_b32 m0, s48
	v_lshl_add_u64 v[212:213], s[42:43], 0, v[190:191]
	ds_read_b128 v[172:175], v142 offset:32768
	ds_read_b128 v[176:179], v142 offset:33792
	ds_read_b128 v[180:183], v142 offset:34816
	ds_read_b128 v[184:187], v142 offset:35840
	ds_read_b128 v[192:195], v142 offset:36864
	ds_read_b128 v[196:199], v142 offset:37888
	ds_read_b128 v[200:203], v142 offset:38912
	ds_read_b128 v[204:207], v142 offset:39936
	global_load_lds_dwordx4 v[212:213], off
	v_lshl_add_u64 v[212:213], s[42:43], 0, v[130:131]
	s_mov_b32 m0, s49
	s_nop 0
	global_load_lds_dwordx4 v[212:213], off
	s_waitcnt vmcnt(8)
	s_waitcnt lgkmcnt(0)
	s_barrier
	s_waitcnt lgkmcnt(0)
	v_mfma_f32_16x16x32_bf16 v[126:129], v[136:139], v[172:175], v[126:129]
	v_mfma_f32_16x16x32_bf16 v[122:125], v[148:151], v[172:175], v[122:125]
	v_mfma_f32_16x16x32_bf16 v[110:113], v[136:139], v[180:183], v[110:113]
	v_mfma_f32_16x16x32_bf16 v[106:109], v[148:151], v[180:183], v[106:109]
	v_mfma_f32_16x16x32_bf16 v[94:97], v[136:139], v[192:195], v[94:97]
	v_mfma_f32_16x16x32_bf16 v[90:93], v[148:151], v[192:195], v[90:93]
	v_mfma_f32_16x16x32_bf16 v[78:81], v[136:139], v[200:203], v[78:81]
	v_mfma_f32_16x16x32_bf16 v[74:77], v[148:151], v[200:203], v[74:77]
	v_mfma_f32_16x16x32_bf16 v[126:129], v[144:147], v[176:179], v[126:129]
	v_mfma_f32_16x16x32_bf16 v[122:125], v[152:155], v[176:179], v[122:125]
	v_mfma_f32_16x16x32_bf16 v[110:113], v[144:147], v[184:187], v[110:113]
	v_mfma_f32_16x16x32_bf16 v[106:109], v[152:155], v[184:187], v[106:109]
	v_mfma_f32_16x16x32_bf16 v[94:97], v[144:147], v[196:199], v[94:97]
	v_mfma_f32_16x16x32_bf16 v[90:93], v[152:155], v[196:199], v[90:93]
	v_mfma_f32_16x16x32_bf16 v[78:81], v[144:147], v[204:207], v[78:81]
	v_mfma_f32_16x16x32_bf16 v[74:77], v[152:155], v[204:207], v[74:77]
	v_mfma_f32_16x16x32_bf16 v[118:121], v[156:159], v[172:175], v[118:121]
	v_mfma_f32_16x16x32_bf16 v[114:117], v[164:167], v[172:175], v[114:117]
	v_mfma_f32_16x16x32_bf16 v[102:105], v[156:159], v[180:183], v[102:105]
	v_mfma_f32_16x16x32_bf16 v[98:101], v[164:167], v[180:183], v[98:101]
	v_mfma_f32_16x16x32_bf16 v[86:89], v[156:159], v[192:195], v[86:89]
	v_mfma_f32_16x16x32_bf16 v[82:85], v[164:167], v[192:195], v[82:85]
	v_mfma_f32_16x16x32_bf16 v[70:73], v[156:159], v[200:203], v[70:73]
	v_mfma_f32_16x16x32_bf16 v[66:69], v[164:167], v[200:203], v[66:69]
	v_mfma_f32_16x16x32_bf16 v[118:121], v[160:163], v[176:179], v[118:121]
	v_mfma_f32_16x16x32_bf16 v[114:117], v[168:171], v[176:179], v[114:117]
	v_mfma_f32_16x16x32_bf16 v[102:105], v[160:163], v[184:187], v[102:105]
	v_mfma_f32_16x16x32_bf16 v[98:101], v[168:171], v[184:187], v[98:101]
	v_mfma_f32_16x16x32_bf16 v[86:89], v[160:163], v[196:199], v[86:89]
	v_mfma_f32_16x16x32_bf16 v[82:85], v[168:171], v[196:199], v[82:85]
	v_mfma_f32_16x16x32_bf16 v[70:73], v[160:163], v[204:207], v[70:73]
	v_mfma_f32_16x16x32_bf16 v[66:69], v[168:171], v[204:207], v[66:69]
	s_barrier
	s_add_i32 s42, s55, s46
	v_lshl_add_u64 v[140:141], v[140:141], 0, s[36:37]
	s_mov_b32 m0, s42
	ds_read_b128 v[172:175], v142 offset:49152
	ds_read_b128 v[176:179], v142 offset:50176
	ds_read_b128 v[180:183], v142 offset:51200
	ds_read_b128 v[184:187], v142 offset:52224
	ds_read_b128 v[192:195], v142 offset:53248
	ds_read_b128 v[196:199], v142 offset:54272
	ds_read_b128 v[200:203], v142 offset:55296
	ds_read_b128 v[204:207], v142 offset:56320
	global_load_lds_dwordx4 v[140:141], off
	s_add_i32 m0, s42, 0x2000
	s_add_u32 s30, s30, 0x20080
	v_lshl_add_u64 v[140:141], v[188:189], 0, s[36:37]
	s_addc_u32 s31, s31, 0
	s_add_i32 s42, s56, s46
	global_load_lds_dwordx4 v[140:141], off
	v_lshl_add_u64 v[140:141], s[30:31], 0, v[190:191]
	s_mov_b32 m0, s42
	s_nop 0
	global_load_lds_dwordx4 v[140:141], off
	v_lshl_add_u64 v[140:141], s[30:31], 0, v[130:131]
	s_add_i32 m0, s42, 0x2000
	s_nop 0
	global_load_lds_dwordx4 v[140:141], off
	v_lshl_add_u64 v[140:141], v[208:209], 0, s[36:37]
	s_mov_b32 m0, s52
	s_nop 0
	global_load_lds_dwordx4 v[140:141], off
	v_lshl_add_u64 v[140:141], v[210:211], 0, s[36:37]
	s_mov_b32 m0, s53
	s_nop 0
	global_load_lds_dwordx4 v[140:141], off
	s_waitcnt vmcnt(8)
	s_waitcnt lgkmcnt(0)
	s_barrier
	s_waitcnt lgkmcnt(0)
	v_mfma_f32_16x16x32_bf16 v[62:65], v[136:139], v[172:175], v[62:65]
	v_mfma_f32_16x16x32_bf16 v[58:61], v[148:151], v[172:175], v[58:61]
	v_mfma_f32_16x16x32_bf16 v[46:49], v[136:139], v[180:183], v[46:49]
	v_mfma_f32_16x16x32_bf16 v[42:45], v[148:151], v[180:183], v[42:45]
	v_mfma_f32_16x16x32_bf16 v[30:33], v[136:139], v[192:195], v[30:33]
	v_mfma_f32_16x16x32_bf16 v[22:25], v[148:151], v[192:195], v[22:25]
	v_mfma_f32_16x16x32_bf16 v[14:17], v[136:139], v[200:203], v[14:17]
	v_mfma_f32_16x16x32_bf16 v[6:9], v[148:151], v[200:203], v[6:9]
	v_mfma_f32_16x16x32_bf16 v[62:65], v[144:147], v[176:179], v[62:65]
	v_mfma_f32_16x16x32_bf16 v[58:61], v[152:155], v[176:179], v[58:61]
	v_mfma_f32_16x16x32_bf16 v[46:49], v[144:147], v[184:187], v[46:49]
	v_mfma_f32_16x16x32_bf16 v[42:45], v[152:155], v[184:187], v[42:45]
	v_mfma_f32_16x16x32_bf16 v[30:33], v[144:147], v[196:199], v[30:33]
	v_mfma_f32_16x16x32_bf16 v[22:25], v[152:155], v[196:199], v[22:25]
	v_mfma_f32_16x16x32_bf16 v[14:17], v[144:147], v[204:207], v[14:17]
	v_mfma_f32_16x16x32_bf16 v[6:9], v[152:155], v[204:207], v[6:9]
	v_mfma_f32_16x16x32_bf16 v[54:57], v[156:159], v[172:175], v[54:57]
	v_mfma_f32_16x16x32_bf16 v[50:53], v[164:167], v[172:175], v[50:53]
	v_mfma_f32_16x16x32_bf16 v[38:41], v[156:159], v[180:183], v[38:41]
	v_mfma_f32_16x16x32_bf16 v[34:37], v[164:167], v[180:183], v[34:37]
	v_mfma_f32_16x16x32_bf16 v[26:29], v[156:159], v[192:195], v[26:29]
	v_mfma_f32_16x16x32_bf16 v[18:21], v[164:167], v[192:195], v[18:21]
	v_mfma_f32_16x16x32_bf16 v[10:13], v[156:159], v[200:203], v[10:13]
	v_mfma_f32_16x16x32_bf16 v[2:5], v[164:167], v[200:203], v[2:5]
	v_mfma_f32_16x16x32_bf16 v[54:57], v[160:163], v[176:179], v[54:57]
	v_mfma_f32_16x16x32_bf16 v[50:53], v[168:171], v[176:179], v[50:53]
	v_mfma_f32_16x16x32_bf16 v[38:41], v[160:163], v[184:187], v[38:41]
	v_mfma_f32_16x16x32_bf16 v[34:37], v[168:171], v[184:187], v[34:37]
	v_mfma_f32_16x16x32_bf16 v[26:29], v[160:163], v[196:199], v[26:29]
	v_mfma_f32_16x16x32_bf16 v[18:21], v[168:171], v[196:199], v[18:21]
	v_mfma_f32_16x16x32_bf16 v[10:13], v[160:163], v[204:207], v[10:13]
	v_mfma_f32_16x16x32_bf16 v[2:5], v[168:171], v[204:207], v[2:5]
	s_barrier
	s_add_i32 s40, s40, 2
	s_add_u32 s28, s28, 0x100
	s_addc_u32 s29, s29, 0
	s_add_u32 s26, s26, 0x100
	s_addc_u32 s38, s38, 0
	s_cmp_gt_u32 s40, 5
	s_cbranch_scc0 .LBB0_2717
	s_and_b64 vcc, exec, s[10:11]
	s_cbranch_vccz .LBB0_2720
	s_barrier

.LBB0_2792:
	s_add_u32 s22, s6, 0xfff80080
	s_addc_u32 s23, s7, -1
	s_add_i32 s38, 0, 0x10000
	s_cmp_eq_u32 s26, 28
	s_cselect_b32 s29, s17, s23
	s_cselect_b32 s28, s16, s22
	s_cselect_b32 s23, s19, s20
	s_cselect_b32 s22, s18, s15
	s_add_i32 s40, 0, 0x14000
	v_add_u32_e32 v74, s38, v1
	v_add_u32_e32 v94, s40, v1
	ds_read_b128 v[58:61], v74
	ds_read_b128 v[62:65], v74 offset:1024
	ds_read_b128 v[70:73], v74 offset:2048
	ds_read_b128 v[74:77], v74 offset:3072
	ds_read_b128 v[78:81], v94
	ds_read_b128 v[86:89], v94 offset:1024
	ds_read_b128 v[90:93], v94 offset:2048
	ds_read_b128 v[94:97], v94 offset:3072
	v_lshl_add_u64 v[188:189], s[6:7], 0, v[180:181]
	s_add_i32 m0, s39, 0xc000
	ds_read_b128 v[162:165], v206
	ds_read_b128 v[166:169], v206 offset:1024
	ds_read_b128 v[170:173], v206 offset:2048
	ds_read_b128 v[174:177], v206 offset:3072
	ds_read_b128 v[184:187], v206 offset:4096
	ds_read_b128 v[192:195], v206 offset:5120
	ds_read_b128 v[196:199], v206 offset:6144
	ds_read_b128 v[200:203], v206 offset:7168
	global_load_lds_dwordx4 v[188:189], off
	v_lshl_add_u64 v[188:189], s[6:7], 0, v[182:183]
	s_add_i32 m0, s39, 0xe000
	s_nop 0
	global_load_lds_dwordx4 v[188:189], off
	s_waitcnt vmcnt(8)
	s_waitcnt lgkmcnt(0)
	s_barrier
	s_waitcnt lgkmcnt(0)
	v_mfma_f32_16x16x32_bf16 v[158:161], v[58:61], v[162:165], v[158:161]
	v_mfma_f32_16x16x32_bf16 v[154:157], v[70:73], v[162:165], v[154:157]
	v_mfma_f32_16x16x32_bf16 v[142:145], v[58:61], v[170:173], v[142:145]
	v_mfma_f32_16x16x32_bf16 v[138:141], v[70:73], v[170:173], v[138:141]
	v_mfma_f32_16x16x32_bf16 v[126:129], v[58:61], v[184:187], v[126:129]
	v_mfma_f32_16x16x32_bf16 v[122:125], v[70:73], v[184:187], v[122:125]
	v_mfma_f32_16x16x32_bf16 v[110:113], v[58:61], v[196:199], v[110:113]
	v_mfma_f32_16x16x32_bf16 v[106:109], v[70:73], v[196:199], v[106:109]
	v_mfma_f32_16x16x32_bf16 v[158:161], v[62:65], v[166:169], v[158:161]
	v_mfma_f32_16x16x32_bf16 v[154:157], v[74:77], v[166:169], v[154:157]
	v_mfma_f32_16x16x32_bf16 v[142:145], v[62:65], v[174:177], v[142:145]
	v_mfma_f32_16x16x32_bf16 v[138:141], v[74:77], v[174:177], v[138:141]
	v_mfma_f32_16x16x32_bf16 v[126:129], v[62:65], v[192:195], v[126:129]
	v_mfma_f32_16x16x32_bf16 v[122:125], v[74:77], v[192:195], v[122:125]
	v_mfma_f32_16x16x32_bf16 v[110:113], v[62:65], v[200:203], v[110:113]
	v_mfma_f32_16x16x32_bf16 v[106:109], v[74:77], v[200:203], v[106:109]
	v_mfma_f32_16x16x32_bf16 v[150:153], v[78:81], v[162:165], v[150:153]
	v_mfma_f32_16x16x32_bf16 v[146:149], v[90:93], v[162:165], v[146:149]
	v_mfma_f32_16x16x32_bf16 v[134:137], v[78:81], v[170:173], v[134:137]
	v_mfma_f32_16x16x32_bf16 v[130:133], v[90:93], v[170:173], v[130:133]
	v_mfma_f32_16x16x32_bf16 v[118:121], v[78:81], v[184:187], v[118:121]
	v_mfma_f32_16x16x32_bf16 v[114:117], v[90:93], v[184:187], v[114:117]
	v_mfma_f32_16x16x32_bf16 v[102:105], v[78:81], v[196:199], v[102:105]
	v_mfma_f32_16x16x32_bf16 v[98:101], v[90:93], v[196:199], v[98:101]
	v_mfma_f32_16x16x32_bf16 v[150:153], v[86:89], v[166:169], v[150:153]
	v_mfma_f32_16x16x32_bf16 v[146:149], v[94:97], v[166:169], v[146:149]
	v_mfma_f32_16x16x32_bf16 v[134:137], v[86:89], v[174:177], v[134:137]
	v_mfma_f32_16x16x32_bf16 v[130:133], v[94:97], v[174:177], v[130:133]
	v_mfma_f32_16x16x32_bf16 v[118:121], v[86:89], v[192:195], v[118:121]
	v_mfma_f32_16x16x32_bf16 v[114:117], v[94:97], v[192:195], v[114:117]
	v_mfma_f32_16x16x32_bf16 v[102:105], v[86:89], v[200:203], v[102:105]
	v_mfma_f32_16x16x32_bf16 v[98:101], v[94:97], v[200:203], v[98:101]
	s_barrier
	s_add_i32 s38, s38, s31
	v_lshl_add_u64 v[188:189], s[22:23], 0, v[190:191]
	s_mov_b32 m0, s38
	ds_read_b128 v[162:165], v206 offset:16384
	ds_read_b128 v[166:169], v206 offset:17408
	ds_read_b128 v[170:173], v206 offset:18432
	ds_read_b128 v[174:177], v206 offset:19456
	ds_read_b128 v[184:187], v206 offset:20480
	ds_read_b128 v[192:195], v206 offset:21504
	ds_read_b128 v[196:199], v206 offset:22528
	ds_read_b128 v[200:203], v206 offset:23552
	global_load_lds_dwordx4 v[188:189], off
	s_add_i32 m0, s38, 0x2000
	s_add_u32 s52, s22, 0x80000
	v_lshl_add_u64 v[204:205], s[22:23], 0, v[178:179]
	s_addc_u32 s53, s23, 0
	s_add_i32 s38, s40, s31
	global_load_lds_dwordx4 v[204:205], off
	v_lshl_add_u64 v[208:209], s[52:53], 0, v[190:191]
	s_mov_b32 m0, s38
	v_lshl_add_u64 v[210:211], s[28:29], 0, v[178:179]
	global_load_lds_dwordx4 v[208:209], off
	v_lshl_add_u64 v[208:209], s[52:53], 0, v[178:179]
	s_add_i32 m0, s38, 0x2000
	s_nop 0
	global_load_lds_dwordx4 v[208:209], off
	v_lshl_add_u64 v[208:209], s[28:29], 0, v[190:191]
	s_mov_b32 m0, s39
	s_nop 0
	global_load_lds_dwordx4 v[208:209], off
	s_mov_b32 m0, s41
	s_nop 0
	global_load_lds_dwordx4 v[210:211], off
	s_waitcnt vmcnt(8)
	s_waitcnt lgkmcnt(0)
	s_barrier
	s_waitcnt lgkmcnt(0)
	v_mfma_f32_16x16x32_bf16 v[82:85], v[58:61], v[162:165], v[82:85]
	v_mfma_f32_16x16x32_bf16 v[66:69], v[70:73], v[162:165], v[66:69]
	v_mfma_f32_16x16x32_bf16 v[46:49], v[58:61], v[170:173], v[46:49]
	v_mfma_f32_16x16x32_bf16 v[42:45], v[70:73], v[170:173], v[42:45]
	v_mfma_f32_16x16x32_bf16 v[26:29], v[58:61], v[184:187], v[26:29]
	v_mfma_f32_16x16x32_bf16 v[18:21], v[70:73], v[184:187], v[18:21]
	v_mfma_f32_16x16x32_bf16 v[6:9], v[58:61], v[196:199], v[6:9]
	v_mfma_f32_16x16x32_bf16 v[2:5], v[70:73], v[196:199], v[2:5]
	v_mfma_f32_16x16x32_bf16 v[82:85], v[62:65], v[166:169], v[82:85]
	v_mfma_f32_16x16x32_bf16 v[66:69], v[74:77], v[166:169], v[66:69]
	v_mfma_f32_16x16x32_bf16 v[46:49], v[62:65], v[174:177], v[46:49]
	v_mfma_f32_16x16x32_bf16 v[42:45], v[74:77], v[174:177], v[42:45]
	v_mfma_f32_16x16x32_bf16 v[26:29], v[62:65], v[192:195], v[26:29]
	v_mfma_f32_16x16x32_bf16 v[18:21], v[74:77], v[192:195], v[18:21]
	v_mfma_f32_16x16x32_bf16 v[6:9], v[62:65], v[200:203], v[6:9]
	v_mfma_f32_16x16x32_bf16 v[2:5], v[74:77], v[200:203], v[2:5]
	v_mfma_f32_16x16x32_bf16 v[54:57], v[78:81], v[162:165], v[54:57]
	v_mfma_f32_16x16x32_bf16 v[50:53], v[90:93], v[162:165], v[50:53]
	v_mfma_f32_16x16x32_bf16 v[38:41], v[78:81], v[170:173], v[38:41]
	v_mfma_f32_16x16x32_bf16 v[34:37], v[90:93], v[170:173], v[34:37]
	v_mfma_f32_16x16x32_bf16 v[30:33], v[78:81], v[184:187], v[30:33]
	v_mfma_f32_16x16x32_bf16 v[22:25], v[90:93], v[184:187], v[22:25]
	v_mfma_f32_16x16x32_bf16 v[14:17], v[78:81], v[196:199], v[14:17]
	v_mfma_f32_16x16x32_bf16 v[10:13], v[90:93], v[196:199], v[10:13]
	v_mfma_f32_16x16x32_bf16 v[54:57], v[86:89], v[166:169], v[54:57]
	v_mfma_f32_16x16x32_bf16 v[50:53], v[94:97], v[166:169], v[50:53]
	v_mfma_f32_16x16x32_bf16 v[38:41], v[86:89], v[174:177], v[38:41]
	v_mfma_f32_16x16x32_bf16 v[34:37], v[94:97], v[174:177], v[34:37]
	v_mfma_f32_16x16x32_bf16 v[30:33], v[86:89], v[192:195], v[30:33]
	v_mfma_f32_16x16x32_bf16 v[22:25], v[94:97], v[192:195], v[22:25]
	v_mfma_f32_16x16x32_bf16 v[14:17], v[86:89], v[200:203], v[14:17]
	v_mfma_f32_16x16x32_bf16 v[10:13], v[94:97], v[200:203], v[10:13]
	s_barrier
	s_add_i32 s38, 0, 0x18000
	s_add_i32 s40, 0, 0x1c000
	v_add_u32_e32 v74, s38, v1
	v_add_u32_e32 v94, s40, v1
	ds_read_b128 v[58:61], v74
	ds_read_b128 v[62:65], v74 offset:1024
	ds_read_b128 v[70:73], v74 offset:2048
	ds_read_b128 v[74:77], v74 offset:3072
	ds_read_b128 v[78:81], v94
	ds_read_b128 v[86:89], v94 offset:1024
	ds_read_b128 v[90:93], v94 offset:2048
	ds_read_b128 v[94:97], v94 offset:3072
	s_add_u32 s28, s28, 0x80000
	s_addc_u32 s29, s29, 0
	s_mov_b32 m0, s42
	v_lshl_add_u64 v[212:213], s[28:29], 0, v[190:191]
	ds_read_b128 v[162:165], v206 offset:32768
	ds_read_b128 v[166:169], v206 offset:33792
	ds_read_b128 v[170:173], v206 offset:34816
	ds_read_b128 v[174:177], v206 offset:35840
	ds_read_b128 v[184:187], v206 offset:36864
	ds_read_b128 v[192:195], v206 offset:37888
	ds_read_b128 v[196:199], v206 offset:38912
	ds_read_b128 v[200:203], v206 offset:39936
	global_load_lds_dwordx4 v[212:213], off
	v_lshl_add_u64 v[212:213], s[28:29], 0, v[178:179]
	s_mov_b32 m0, s43
	s_nop 0
	global_load_lds_dwordx4 v[212:213], off
	s_waitcnt vmcnt(8)
	s_waitcnt lgkmcnt(0)
	s_barrier
	s_waitcnt lgkmcnt(0)
	v_mfma_f32_16x16x32_bf16 v[158:161], v[58:61], v[162:165], v[158:161]
	v_mfma_f32_16x16x32_bf16 v[154:157], v[70:73], v[162:165], v[154:157]
	v_mfma_f32_16x16x32_bf16 v[142:145], v[58:61], v[170:173], v[142:145]
	v_mfma_f32_16x16x32_bf16 v[138:141], v[70:73], v[170:173], v[138:141]
	v_mfma_f32_16x16x32_bf16 v[126:129], v[58:61], v[184:187], v[126:129]
	v_mfma_f32_16x16x32_bf16 v[122:125], v[70:73], v[184:187], v[122:125]
	v_mfma_f32_16x16x32_bf16 v[110:113], v[58:61], v[196:199], v[110:113]
	v_mfma_f32_16x16x32_bf16 v[106:109], v[70:73], v[196:199], v[106:109]
	v_mfma_f32_16x16x32_bf16 v[158:161], v[62:65], v[166:169], v[158:161]
	v_mfma_f32_16x16x32_bf16 v[154:157], v[74:77], v[166:169], v[154:157]
	v_mfma_f32_16x16x32_bf16 v[142:145], v[62:65], v[174:177], v[142:145]
	v_mfma_f32_16x16x32_bf16 v[138:141], v[74:77], v[174:177], v[138:141]
	v_mfma_f32_16x16x32_bf16 v[126:129], v[62:65], v[192:195], v[126:129]
	v_mfma_f32_16x16x32_bf16 v[122:125], v[74:77], v[192:195], v[122:125]
	v_mfma_f32_16x16x32_bf16 v[110:113], v[62:65], v[200:203], v[110:113]
	v_mfma_f32_16x16x32_bf16 v[106:109], v[74:77], v[200:203], v[106:109]
	v_mfma_f32_16x16x32_bf16 v[150:153], v[78:81], v[162:165], v[150:153]
	v_mfma_f32_16x16x32_bf16 v[146:149], v[90:93], v[162:165], v[146:149]
	v_mfma_f32_16x16x32_bf16 v[134:137], v[78:81], v[170:173], v[134:137]
	v_mfma_f32_16x16x32_bf16 v[130:133], v[90:93], v[170:173], v[130:133]
	v_mfma_f32_16x16x32_bf16 v[118:121], v[78:81], v[184:187], v[118:121]
	v_mfma_f32_16x16x32_bf16 v[114:117], v[90:93], v[184:187], v[114:117]
	v_mfma_f32_16x16x32_bf16 v[102:105], v[78:81], v[196:199], v[102:105]
	v_mfma_f32_16x16x32_bf16 v[98:101], v[90:93], v[196:199], v[98:101]
	v_mfma_f32_16x16x32_bf16 v[150:153], v[86:89], v[166:169], v[150:153]
	v_mfma_f32_16x16x32_bf16 v[146:149], v[94:97], v[166:169], v[146:149]
	v_mfma_f32_16x16x32_bf16 v[134:137], v[86:89], v[174:177], v[134:137]
	v_mfma_f32_16x16x32_bf16 v[130:133], v[94:97], v[174:177], v[130:133]
	v_mfma_f32_16x16x32_bf16 v[118:121], v[86:89], v[192:195], v[118:121]
	v_mfma_f32_16x16x32_bf16 v[114:117], v[94:97], v[192:195], v[114:117]
	v_mfma_f32_16x16x32_bf16 v[102:105], v[86:89], v[200:203], v[102:105]
	v_mfma_f32_16x16x32_bf16 v[98:101], v[94:97], v[200:203], v[98:101]
	s_barrier
	s_add_i32 s28, s38, s31
	v_lshl_add_u64 v[188:189], v[188:189], 0, s[36:37]
	s_mov_b32 m0, s28
	ds_read_b128 v[162:165], v206 offset:49152
	ds_read_b128 v[166:169], v206 offset:50176
	ds_read_b128 v[170:173], v206 offset:51200
	ds_read_b128 v[174:177], v206 offset:52224
	ds_read_b128 v[184:187], v206 offset:53248
	ds_read_b128 v[192:195], v206 offset:54272
	ds_read_b128 v[196:199], v206 offset:55296
	ds_read_b128 v[200:203], v206 offset:56320
	global_load_lds_dwordx4 v[188:189], off
	s_add_i32 m0, s28, 0x2000
	s_add_u32 s22, s22, 0x80080
	v_lshl_add_u64 v[188:189], v[204:205], 0, s[36:37]
	s_addc_u32 s23, s23, 0
	s_add_i32 s28, s40, s31
	global_load_lds_dwordx4 v[188:189], off
	v_lshl_add_u64 v[188:189], s[22:23], 0, v[190:191]
	s_mov_b32 m0, s28
	s_nop 0
	global_load_lds_dwordx4 v[188:189], off
	v_lshl_add_u64 v[188:189], s[22:23], 0, v[178:179]
	s_add_i32 m0, s28, 0x2000
	s_nop 0
	global_load_lds_dwordx4 v[188:189], off
	v_lshl_add_u64 v[188:189], v[208:209], 0, s[36:37]
	s_mov_b32 m0, s48
	s_nop 0
	global_load_lds_dwordx4 v[188:189], off
	v_lshl_add_u64 v[188:189], v[210:211], 0, s[36:37]
	s_mov_b32 m0, s49
	s_nop 0
	global_load_lds_dwordx4 v[188:189], off
	s_waitcnt vmcnt(8)
	s_waitcnt lgkmcnt(0)
	s_barrier
	s_waitcnt lgkmcnt(0)
	v_mfma_f32_16x16x32_bf16 v[82:85], v[58:61], v[162:165], v[82:85]
	v_mfma_f32_16x16x32_bf16 v[66:69], v[70:73], v[162:165], v[66:69]
	v_mfma_f32_16x16x32_bf16 v[46:49], v[58:61], v[170:173], v[46:49]
	v_mfma_f32_16x16x32_bf16 v[42:45], v[70:73], v[170:173], v[42:45]
	v_mfma_f32_16x16x32_bf16 v[26:29], v[58:61], v[184:187], v[26:29]
	v_mfma_f32_16x16x32_bf16 v[18:21], v[70:73], v[184:187], v[18:21]
	v_mfma_f32_16x16x32_bf16 v[6:9], v[58:61], v[196:199], v[6:9]
	v_mfma_f32_16x16x32_bf16 v[2:5], v[70:73], v[196:199], v[2:5]
	v_mfma_f32_16x16x32_bf16 v[82:85], v[62:65], v[166:169], v[82:85]
	v_mfma_f32_16x16x32_bf16 v[66:69], v[74:77], v[166:169], v[66:69]
	v_mfma_f32_16x16x32_bf16 v[46:49], v[62:65], v[174:177], v[46:49]
	v_mfma_f32_16x16x32_bf16 v[42:45], v[74:77], v[174:177], v[42:45]
	v_mfma_f32_16x16x32_bf16 v[26:29], v[62:65], v[192:195], v[26:29]
	v_mfma_f32_16x16x32_bf16 v[18:21], v[74:77], v[192:195], v[18:21]
	v_mfma_f32_16x16x32_bf16 v[6:9], v[62:65], v[200:203], v[6:9]
	v_mfma_f32_16x16x32_bf16 v[2:5], v[74:77], v[200:203], v[2:5]
	v_mfma_f32_16x16x32_bf16 v[54:57], v[78:81], v[162:165], v[54:57]
	v_mfma_f32_16x16x32_bf16 v[50:53], v[90:93], v[162:165], v[50:53]
	v_mfma_f32_16x16x32_bf16 v[38:41], v[78:81], v[170:173], v[38:41]
	v_mfma_f32_16x16x32_bf16 v[34:37], v[90:93], v[170:173], v[34:37]
	v_mfma_f32_16x16x32_bf16 v[30:33], v[78:81], v[184:187], v[30:33]
	v_mfma_f32_16x16x32_bf16 v[22:25], v[90:93], v[184:187], v[22:25]
	v_mfma_f32_16x16x32_bf16 v[14:17], v[78:81], v[196:199], v[14:17]
	v_mfma_f32_16x16x32_bf16 v[10:13], v[90:93], v[196:199], v[10:13]
	v_mfma_f32_16x16x32_bf16 v[54:57], v[86:89], v[166:169], v[54:57]
	v_mfma_f32_16x16x32_bf16 v[50:53], v[94:97], v[166:169], v[50:53]
	v_mfma_f32_16x16x32_bf16 v[38:41], v[86:89], v[174:177], v[38:41]
	v_mfma_f32_16x16x32_bf16 v[34:37], v[94:97], v[174:177], v[34:37]
	v_mfma_f32_16x16x32_bf16 v[30:33], v[86:89], v[192:195], v[30:33]
	v_mfma_f32_16x16x32_bf16 v[22:25], v[94:97], v[192:195], v[22:25]
	v_mfma_f32_16x16x32_bf16 v[14:17], v[86:89], v[200:203], v[14:17]
	v_mfma_f32_16x16x32_bf16 v[10:13], v[94:97], v[200:203], v[10:13]
	s_barrier
	s_add_i32 s26, s26, 2
	s_add_u32 s6, s6, 0x100
	s_addc_u32 s7, s7, 0
	s_add_u32 s15, s15, 0x100
	s_addc_u32 s20, s20, 0
	s_cmp_gt_u32 s26, 29
	s_cbranch_scc0 .LBB0_2792
	s_and_b64 vcc, exec, s[12:13]
	s_cbranch_vccz .LBB0_2795
	s_barrier

.LBB0_2831:
	s_add_u32 s18, s16, 0xfff80080
	s_addc_u32 s19, s17, -1
	s_add_i32 s40, 0, 0x10000
	s_cmp_eq_u32 s38, 4
	s_cselect_b32 s23, s13, s19
	s_cselect_b32 s22, s12, s18
	v_add_u32_e32 v144, s40, v1
	s_cselect_b32 s19, s15, s26
	s_cselect_b32 s18, s14, s11
	s_add_i32 s47, 0, 0x14000
	ds_read_b128 v[130:133], v144
	ds_read_b128 v[140:143], v144 offset:1024
	ds_read_b128 v[148:151], v144 offset:2048
	ds_read_b128 v[152:155], v144 offset:3072
	v_add_u32_e32 v144, s47, v1
	ds_read_b128 v[156:159], v144
	ds_read_b128 v[160:163], v144 offset:1024
	ds_read_b128 v[164:167], v144 offset:2048
	ds_read_b128 v[168:171], v144 offset:3072
	v_lshl_add_u64 v[144:145], s[16:17], 0, v[136:137]
	s_add_i32 m0, s29, 0xc000
	ds_read_b128 v[172:175], v146
	ds_read_b128 v[176:179], v146 offset:1024
	ds_read_b128 v[180:183], v146 offset:2048
	ds_read_b128 v[184:187], v146 offset:3072
	ds_read_b128 v[192:195], v146 offset:4096
	ds_read_b128 v[196:199], v146 offset:5120
	ds_read_b128 v[200:203], v146 offset:6144
	ds_read_b128 v[204:207], v146 offset:7168
	global_load_lds_dwordx4 v[144:145], off
	v_lshl_add_u64 v[144:145], s[16:17], 0, v[138:139]
	s_add_i32 m0, s29, 0xe000
	s_nop 0
	global_load_lds_dwordx4 v[144:145], off
	s_waitcnt vmcnt(8)
	s_waitcnt lgkmcnt(0)
	s_barrier
	s_waitcnt lgkmcnt(0)
	v_mfma_f32_16x16x32_bf16 v[126:129], v[130:133], v[172:175], v[126:129]
	v_mfma_f32_16x16x32_bf16 v[102:105], v[148:151], v[172:175], v[102:105]
	v_mfma_f32_16x16x32_bf16 v[122:125], v[130:133], v[180:183], v[122:125]
	v_mfma_f32_16x16x32_bf16 v[94:97], v[148:151], v[180:183], v[94:97]
	v_mfma_f32_16x16x32_bf16 v[118:121], v[130:133], v[192:195], v[118:121]
	v_mfma_f32_16x16x32_bf16 v[86:89], v[148:151], v[192:195], v[86:89]
	v_mfma_f32_16x16x32_bf16 v[114:117], v[130:133], v[200:203], v[114:117]
	v_mfma_f32_16x16x32_bf16 v[82:85], v[148:151], v[200:203], v[82:85]
	v_mfma_f32_16x16x32_bf16 v[126:129], v[140:143], v[176:179], v[126:129]
	v_mfma_f32_16x16x32_bf16 v[102:105], v[152:155], v[176:179], v[102:105]
	v_mfma_f32_16x16x32_bf16 v[122:125], v[140:143], v[184:187], v[122:125]
	v_mfma_f32_16x16x32_bf16 v[94:97], v[152:155], v[184:187], v[94:97]
	v_mfma_f32_16x16x32_bf16 v[118:121], v[140:143], v[196:199], v[118:121]
	v_mfma_f32_16x16x32_bf16 v[86:89], v[152:155], v[196:199], v[86:89]
	v_mfma_f32_16x16x32_bf16 v[114:117], v[140:143], v[204:207], v[114:117]
	v_mfma_f32_16x16x32_bf16 v[82:85], v[152:155], v[204:207], v[82:85]
	v_mfma_f32_16x16x32_bf16 v[70:73], v[156:159], v[172:175], v[70:73]
	v_mfma_f32_16x16x32_bf16 v[30:33], v[164:167], v[172:175], v[30:33]
	v_mfma_f32_16x16x32_bf16 v[62:65], v[156:159], v[180:183], v[62:65]
	v_mfma_f32_16x16x32_bf16 v[26:29], v[164:167], v[180:183], v[26:29]
	v_mfma_f32_16x16x32_bf16 v[54:57], v[156:159], v[192:195], v[54:57]
	v_mfma_f32_16x16x32_bf16 v[22:25], v[164:167], v[192:195], v[22:25]
	v_mfma_f32_16x16x32_bf16 v[50:53], v[156:159], v[200:203], v[50:53]
	v_mfma_f32_16x16x32_bf16 v[18:21], v[164:167], v[200:203], v[18:21]
	v_mfma_f32_16x16x32_bf16 v[70:73], v[160:163], v[176:179], v[70:73]
	v_mfma_f32_16x16x32_bf16 v[30:33], v[168:171], v[176:179], v[30:33]
	v_mfma_f32_16x16x32_bf16 v[62:65], v[160:163], v[184:187], v[62:65]
	v_mfma_f32_16x16x32_bf16 v[26:29], v[168:171], v[184:187], v[26:29]
	v_mfma_f32_16x16x32_bf16 v[54:57], v[160:163], v[196:199], v[54:57]
	v_mfma_f32_16x16x32_bf16 v[22:25], v[168:171], v[196:199], v[22:25]
	v_mfma_f32_16x16x32_bf16 v[50:53], v[160:163], v[204:207], v[50:53]
	v_mfma_f32_16x16x32_bf16 v[18:21], v[168:171], v[204:207], v[18:21]
	s_barrier
	s_add_i32 s40, s40, s28
	v_lshl_add_u64 v[144:145], s[18:19], 0, v[190:191]
	s_mov_b32 m0, s40
	ds_read_b128 v[172:175], v146 offset:16384
	ds_read_b128 v[176:179], v146 offset:17408
	ds_read_b128 v[180:183], v146 offset:18432
	ds_read_b128 v[184:187], v146 offset:19456
	ds_read_b128 v[192:195], v146 offset:20480
	ds_read_b128 v[196:199], v146 offset:21504
	ds_read_b128 v[200:203], v146 offset:22528
	ds_read_b128 v[204:207], v146 offset:23552
	global_load_lds_dwordx4 v[144:145], off
	s_add_i32 m0, s40, 0x2000
	s_add_u32 s48, s18, 0x80000
	v_lshl_add_u64 v[188:189], s[18:19], 0, v[134:135]
	s_addc_u32 s49, s19, 0
	s_add_i32 s40, s47, s28
	global_load_lds_dwordx4 v[188:189], off
	v_lshl_add_u64 v[208:209], s[48:49], 0, v[190:191]
	s_mov_b32 m0, s40
	v_lshl_add_u64 v[210:211], s[22:23], 0, v[134:135]
	global_load_lds_dwordx4 v[208:209], off
	v_lshl_add_u64 v[208:209], s[48:49], 0, v[134:135]
	s_add_i32 m0, s40, 0x2000
	s_nop 0
	global_load_lds_dwordx4 v[208:209], off
	v_lshl_add_u64 v[208:209], s[22:23], 0, v[190:191]
	s_mov_b32 m0, s29
	s_nop 0
	global_load_lds_dwordx4 v[208:209], off
	s_mov_b32 m0, s31
	s_nop 0
	global_load_lds_dwordx4 v[210:211], off
	s_waitcnt vmcnt(8)
	s_waitcnt lgkmcnt(0)
	s_barrier
	s_waitcnt lgkmcnt(0)
	v_mfma_f32_16x16x32_bf16 v[110:113], v[130:133], v[172:175], v[110:113]
	v_mfma_f32_16x16x32_bf16 v[78:81], v[148:151], v[172:175], v[78:81]
	v_mfma_f32_16x16x32_bf16 v[106:109], v[130:133], v[180:183], v[106:109]
	v_mfma_f32_16x16x32_bf16 v[74:77], v[148:151], v[180:183], v[74:77]
	v_mfma_f32_16x16x32_bf16 v[98:101], v[130:133], v[192:195], v[98:101]
	v_mfma_f32_16x16x32_bf16 v[66:69], v[148:151], v[192:195], v[66:69]
	v_mfma_f32_16x16x32_bf16 v[90:93], v[130:133], v[200:203], v[90:93]
	v_mfma_f32_16x16x32_bf16 v[58:61], v[148:151], v[200:203], v[58:61]
	v_mfma_f32_16x16x32_bf16 v[110:113], v[140:143], v[176:179], v[110:113]
	v_mfma_f32_16x16x32_bf16 v[78:81], v[152:155], v[176:179], v[78:81]
	v_mfma_f32_16x16x32_bf16 v[106:109], v[140:143], v[184:187], v[106:109]
	v_mfma_f32_16x16x32_bf16 v[74:77], v[152:155], v[184:187], v[74:77]
	v_mfma_f32_16x16x32_bf16 v[98:101], v[140:143], v[196:199], v[98:101]
	v_mfma_f32_16x16x32_bf16 v[66:69], v[152:155], v[196:199], v[66:69]
	v_mfma_f32_16x16x32_bf16 v[90:93], v[140:143], v[204:207], v[90:93]
	v_mfma_f32_16x16x32_bf16 v[58:61], v[152:155], v[204:207], v[58:61]
	v_mfma_f32_16x16x32_bf16 v[38:41], v[156:159], v[172:175], v[38:41]
	v_mfma_f32_16x16x32_bf16 v[10:13], v[164:167], v[172:175], v[10:13]
	v_mfma_f32_16x16x32_bf16 v[34:37], v[156:159], v[180:183], v[34:37]
	v_mfma_f32_16x16x32_bf16 v[6:9], v[164:167], v[180:183], v[6:9]
	v_mfma_f32_16x16x32_bf16 v[46:49], v[156:159], v[192:195], v[46:49]
	v_mfma_f32_16x16x32_bf16 v[14:17], v[164:167], v[192:195], v[14:17]
	v_mfma_f32_16x16x32_bf16 v[42:45], v[156:159], v[200:203], v[42:45]
	v_mfma_f32_16x16x32_bf16 v[2:5], v[164:167], v[200:203], v[2:5]
	v_mfma_f32_16x16x32_bf16 v[38:41], v[160:163], v[176:179], v[38:41]
	v_mfma_f32_16x16x32_bf16 v[10:13], v[168:171], v[176:179], v[10:13]
	v_mfma_f32_16x16x32_bf16 v[34:37], v[160:163], v[184:187], v[34:37]
	v_mfma_f32_16x16x32_bf16 v[6:9], v[168:171], v[184:187], v[6:9]
	v_mfma_f32_16x16x32_bf16 v[46:49], v[160:163], v[196:199], v[46:49]
	v_mfma_f32_16x16x32_bf16 v[14:17], v[168:171], v[196:199], v[14:17]
	v_mfma_f32_16x16x32_bf16 v[42:45], v[160:163], v[204:207], v[42:45]
	v_mfma_f32_16x16x32_bf16 v[2:5], v[168:171], v[204:207], v[2:5]
	s_barrier
	s_add_i32 s40, 0, 0x18000
	v_add_u32_e32 v147, s40, v1
	s_add_i32 s47, 0, 0x1c000
	ds_read_b128 v[130:133], v147
	ds_read_b128 v[140:143], v147 offset:1024
	ds_read_b128 v[148:151], v147 offset:2048
	ds_read_b128 v[152:155], v147 offset:3072
	v_add_u32_e32 v147, s47, v1
	ds_read_b128 v[156:159], v147
	ds_read_b128 v[160:163], v147 offset:1024
	ds_read_b128 v[164:167], v147 offset:2048
	ds_read_b128 v[168:171], v147 offset:3072
	s_add_u32 s22, s22, 0x80000
	s_addc_u32 s23, s23, 0
	s_mov_b32 m0, s39
	v_lshl_add_u64 v[212:213], s[22:23], 0, v[190:191]
	ds_read_b128 v[172:175], v146 offset:32768
	ds_read_b128 v[176:179], v146 offset:33792
	ds_read_b128 v[180:183], v146 offset:34816
	ds_read_b128 v[184:187], v146 offset:35840
	ds_read_b128 v[192:195], v146 offset:36864
	ds_read_b128 v[196:199], v146 offset:37888
	ds_read_b128 v[200:203], v146 offset:38912
	ds_read_b128 v[204:207], v146 offset:39936
	global_load_lds_dwordx4 v[212:213], off
	v_lshl_add_u64 v[212:213], s[22:23], 0, v[134:135]
	s_mov_b32 m0, s41
	s_nop 0
	global_load_lds_dwordx4 v[212:213], off
	s_waitcnt vmcnt(8)
	s_waitcnt lgkmcnt(0)
	s_barrier
	s_waitcnt lgkmcnt(0)
	v_mfma_f32_16x16x32_bf16 v[126:129], v[130:133], v[172:175], v[126:129]
	v_mfma_f32_16x16x32_bf16 v[102:105], v[148:151], v[172:175], v[102:105]
	v_mfma_f32_16x16x32_bf16 v[122:125], v[130:133], v[180:183], v[122:125]
	v_mfma_f32_16x16x32_bf16 v[94:97], v[148:151], v[180:183], v[94:97]
	v_mfma_f32_16x16x32_bf16 v[118:121], v[130:133], v[192:195], v[118:121]
	v_mfma_f32_16x16x32_bf16 v[86:89], v[148:151], v[192:195], v[86:89]
	v_mfma_f32_16x16x32_bf16 v[114:117], v[130:133], v[200:203], v[114:117]
	v_mfma_f32_16x16x32_bf16 v[82:85], v[148:151], v[200:203], v[82:85]
	v_mfma_f32_16x16x32_bf16 v[126:129], v[140:143], v[176:179], v[126:129]
	v_mfma_f32_16x16x32_bf16 v[102:105], v[152:155], v[176:179], v[102:105]
	v_mfma_f32_16x16x32_bf16 v[122:125], v[140:143], v[184:187], v[122:125]
	v_mfma_f32_16x16x32_bf16 v[94:97], v[152:155], v[184:187], v[94:97]
	v_mfma_f32_16x16x32_bf16 v[118:121], v[140:143], v[196:199], v[118:121]
	v_mfma_f32_16x16x32_bf16 v[86:89], v[152:155], v[196:199], v[86:89]
	v_mfma_f32_16x16x32_bf16 v[114:117], v[140:143], v[204:207], v[114:117]
	v_mfma_f32_16x16x32_bf16 v[82:85], v[152:155], v[204:207], v[82:85]
	v_mfma_f32_16x16x32_bf16 v[70:73], v[156:159], v[172:175], v[70:73]
	v_mfma_f32_16x16x32_bf16 v[30:33], v[164:167], v[172:175], v[30:33]
	v_mfma_f32_16x16x32_bf16 v[62:65], v[156:159], v[180:183], v[62:65]
	v_mfma_f32_16x16x32_bf16 v[26:29], v[164:167], v[180:183], v[26:29]
	v_mfma_f32_16x16x32_bf16 v[54:57], v[156:159], v[192:195], v[54:57]
	v_mfma_f32_16x16x32_bf16 v[22:25], v[164:167], v[192:195], v[22:25]
	v_mfma_f32_16x16x32_bf16 v[50:53], v[156:159], v[200:203], v[50:53]
	v_mfma_f32_16x16x32_bf16 v[18:21], v[164:167], v[200:203], v[18:21]
	v_mfma_f32_16x16x32_bf16 v[70:73], v[160:163], v[176:179], v[70:73]
	v_mfma_f32_16x16x32_bf16 v[30:33], v[168:171], v[176:179], v[30:33]
	v_mfma_f32_16x16x32_bf16 v[62:65], v[160:163], v[184:187], v[62:65]
	v_mfma_f32_16x16x32_bf16 v[26:29], v[168:171], v[184:187], v[26:29]
	v_mfma_f32_16x16x32_bf16 v[54:57], v[160:163], v[196:199], v[54:57]
	v_mfma_f32_16x16x32_bf16 v[22:25], v[168:171], v[196:199], v[22:25]
	v_mfma_f32_16x16x32_bf16 v[50:53], v[160:163], v[204:207], v[50:53]
	v_mfma_f32_16x16x32_bf16 v[18:21], v[168:171], v[204:207], v[18:21]
	s_barrier
	s_add_i32 s22, s40, s28
	v_lshl_add_u64 v[144:145], v[144:145], 0, s[36:37]
	s_mov_b32 m0, s22
	ds_read_b128 v[172:175], v146 offset:49152
	ds_read_b128 v[176:179], v146 offset:50176
	ds_read_b128 v[180:183], v146 offset:51200
	ds_read_b128 v[184:187], v146 offset:52224
	ds_read_b128 v[192:195], v146 offset:53248
	ds_read_b128 v[196:199], v146 offset:54272
	ds_read_b128 v[200:203], v146 offset:55296
	ds_read_b128 v[204:207], v146 offset:56320
	global_load_lds_dwordx4 v[144:145], off
	s_add_i32 m0, s22, 0x2000
	s_add_u32 s18, s18, 0x80080
	v_lshl_add_u64 v[144:145], v[188:189], 0, s[36:37]
	s_addc_u32 s19, s19, 0
	s_add_i32 s22, s47, s28
	global_load_lds_dwordx4 v[144:145], off
	v_lshl_add_u64 v[144:145], s[18:19], 0, v[190:191]
	s_mov_b32 m0, s22
	s_nop 0
	global_load_lds_dwordx4 v[144:145], off
	v_lshl_add_u64 v[144:145], s[18:19], 0, v[134:135]
	s_add_i32 m0, s22, 0x2000
	s_nop 0
	global_load_lds_dwordx4 v[144:145], off
	v_lshl_add_u64 v[144:145], v[208:209], 0, s[36:37]
	s_mov_b32 m0, s44
	s_nop 0
	global_load_lds_dwordx4 v[144:145], off
	v_lshl_add_u64 v[144:145], v[210:211], 0, s[36:37]
	s_mov_b32 m0, s45
	s_nop 0
	global_load_lds_dwordx4 v[144:145], off
	s_waitcnt vmcnt(8)
	s_waitcnt lgkmcnt(0)
	s_barrier
	s_waitcnt lgkmcnt(0)
	v_mfma_f32_16x16x32_bf16 v[110:113], v[130:133], v[172:175], v[110:113]
	v_mfma_f32_16x16x32_bf16 v[78:81], v[148:151], v[172:175], v[78:81]
	v_mfma_f32_16x16x32_bf16 v[106:109], v[130:133], v[180:183], v[106:109]
	v_mfma_f32_16x16x32_bf16 v[74:77], v[148:151], v[180:183], v[74:77]
	v_mfma_f32_16x16x32_bf16 v[98:101], v[130:133], v[192:195], v[98:101]
	v_mfma_f32_16x16x32_bf16 v[66:69], v[148:151], v[192:195], v[66:69]
	v_mfma_f32_16x16x32_bf16 v[90:93], v[130:133], v[200:203], v[90:93]
	v_mfma_f32_16x16x32_bf16 v[58:61], v[148:151], v[200:203], v[58:61]
	v_mfma_f32_16x16x32_bf16 v[110:113], v[140:143], v[176:179], v[110:113]
	v_mfma_f32_16x16x32_bf16 v[78:81], v[152:155], v[176:179], v[78:81]
	v_mfma_f32_16x16x32_bf16 v[106:109], v[140:143], v[184:187], v[106:109]
	v_mfma_f32_16x16x32_bf16 v[74:77], v[152:155], v[184:187], v[74:77]
	v_mfma_f32_16x16x32_bf16 v[98:101], v[140:143], v[196:199], v[98:101]
	v_mfma_f32_16x16x32_bf16 v[66:69], v[152:155], v[196:199], v[66:69]
	v_mfma_f32_16x16x32_bf16 v[90:93], v[140:143], v[204:207], v[90:93]
	v_mfma_f32_16x16x32_bf16 v[58:61], v[152:155], v[204:207], v[58:61]
	v_mfma_f32_16x16x32_bf16 v[38:41], v[156:159], v[172:175], v[38:41]
	v_mfma_f32_16x16x32_bf16 v[10:13], v[164:167], v[172:175], v[10:13]
	v_mfma_f32_16x16x32_bf16 v[34:37], v[156:159], v[180:183], v[34:37]
	v_mfma_f32_16x16x32_bf16 v[6:9], v[164:167], v[180:183], v[6:9]
	v_mfma_f32_16x16x32_bf16 v[46:49], v[156:159], v[192:195], v[46:49]
	v_mfma_f32_16x16x32_bf16 v[14:17], v[164:167], v[192:195], v[14:17]
	v_mfma_f32_16x16x32_bf16 v[42:45], v[156:159], v[200:203], v[42:45]
	v_mfma_f32_16x16x32_bf16 v[2:5], v[164:167], v[200:203], v[2:5]
	v_mfma_f32_16x16x32_bf16 v[38:41], v[160:163], v[176:179], v[38:41]
	v_mfma_f32_16x16x32_bf16 v[10:13], v[168:171], v[176:179], v[10:13]
	v_mfma_f32_16x16x32_bf16 v[34:37], v[160:163], v[184:187], v[34:37]
	v_mfma_f32_16x16x32_bf16 v[6:9], v[168:171], v[184:187], v[6:9]
	v_mfma_f32_16x16x32_bf16 v[46:49], v[160:163], v[196:199], v[46:49]
	v_mfma_f32_16x16x32_bf16 v[14:17], v[168:171], v[196:199], v[14:17]
	v_mfma_f32_16x16x32_bf16 v[42:45], v[160:163], v[204:207], v[42:45]
	v_mfma_f32_16x16x32_bf16 v[2:5], v[168:171], v[204:207], v[2:5]
	s_barrier
	s_add_i32 s38, s38, 2
	s_add_u32 s16, s16, 0x100
	s_addc_u32 s17, s17, 0
	s_add_u32 s11, s11, 0x100
	s_addc_u32 s26, s26, 0
	s_cmp_gt_u32 s38, 5
	s_cbranch_scc0 .LBB0_2831
	s_and_b64 vcc, exec, s[8:9]
	s_cbranch_vccz .LBB0_2834
	s_barrier

.LBB0_2960:
	s_add_u32 s40, s30, 0xfff80080
	s_addc_u32 s42, s31, -1
	s_add_i32 s56, 0, 0x10000
	s_cmp_eq_u32 s38, 28
	s_cselect_b32 s45, s0, s42
	s_cselect_b32 s44, s2, s40
	s_cselect_b32 s43, s15, s26
	s_cselect_b32 s42, s20, s23
	s_add_i32 s40, 0, 0x14000
	v_add_u32_e32 v82, s56, v1
	v_add_u32_e32 v154, s40, v1
	ds_read_b128 v[66:69], v82
	ds_read_b128 v[70:73], v82 offset:1024
	ds_read_b128 v[78:81], v82 offset:2048
	ds_read_b128 v[82:85], v82 offset:3072
	ds_read_b128 v[158:161], v154
	ds_read_b128 v[162:165], v154 offset:1024
	ds_read_b128 v[166:169], v154 offset:2048
	ds_read_b128 v[170:173], v154 offset:3072
	v_lshl_add_u64 v[154:155], s[30:31], 0, v[150:151]
	s_add_i32 m0, s29, 0xc000
	ds_read_b128 v[174:177], v156
	ds_read_b128 v[178:181], v156 offset:1024
	ds_read_b128 v[182:185], v156 offset:2048
	ds_read_b128 v[186:189], v156 offset:3072
	ds_read_b128 v[192:195], v156 offset:4096
	ds_read_b128 v[196:199], v156 offset:5120
	ds_read_b128 v[200:203], v156 offset:6144
	ds_read_b128 v[204:207], v156 offset:7168
	global_load_lds_dwordx4 v[154:155], off
	v_lshl_add_u64 v[154:155], s[30:31], 0, v[152:153]
	s_add_i32 m0, s29, 0xe000
	s_nop 0
	global_load_lds_dwordx4 v[154:155], off
	s_waitcnt vmcnt(8)
	s_waitcnt lgkmcnt(0)
	s_barrier
	s_waitcnt lgkmcnt(0)
	v_mfma_f32_16x16x32_bf16 v[142:145], v[66:69], v[174:177], v[142:145]
	v_mfma_f32_16x16x32_bf16 v[138:141], v[78:81], v[174:177], v[138:141]
	v_mfma_f32_16x16x32_bf16 v[126:129], v[66:69], v[182:185], v[126:129]
	v_mfma_f32_16x16x32_bf16 v[118:121], v[78:81], v[182:185], v[118:121]
	v_mfma_f32_16x16x32_bf16 v[110:113], v[66:69], v[192:195], v[110:113]
	v_mfma_f32_16x16x32_bf16 v[102:105], v[78:81], v[192:195], v[102:105]
	v_mfma_f32_16x16x32_bf16 v[94:97], v[66:69], v[200:203], v[94:97]
	v_mfma_f32_16x16x32_bf16 v[86:89], v[78:81], v[200:203], v[86:89]
	v_mfma_f32_16x16x32_bf16 v[142:145], v[70:73], v[178:181], v[142:145]
	v_mfma_f32_16x16x32_bf16 v[138:141], v[82:85], v[178:181], v[138:141]
	v_mfma_f32_16x16x32_bf16 v[126:129], v[70:73], v[186:189], v[126:129]
	v_mfma_f32_16x16x32_bf16 v[118:121], v[82:85], v[186:189], v[118:121]
	v_mfma_f32_16x16x32_bf16 v[110:113], v[70:73], v[196:199], v[110:113]
	v_mfma_f32_16x16x32_bf16 v[102:105], v[82:85], v[196:199], v[102:105]
	v_mfma_f32_16x16x32_bf16 v[94:97], v[70:73], v[204:207], v[94:97]
	v_mfma_f32_16x16x32_bf16 v[86:89], v[82:85], v[204:207], v[86:89]
	v_mfma_f32_16x16x32_bf16 v[134:137], v[158:161], v[174:177], v[134:137]
	v_mfma_f32_16x16x32_bf16 v[130:133], v[166:169], v[174:177], v[130:133]
	v_mfma_f32_16x16x32_bf16 v[122:125], v[158:161], v[182:185], v[122:125]
	v_mfma_f32_16x16x32_bf16 v[114:117], v[166:169], v[182:185], v[114:117]
	v_mfma_f32_16x16x32_bf16 v[106:109], v[158:161], v[192:195], v[106:109]
	v_mfma_f32_16x16x32_bf16 v[98:101], v[166:169], v[192:195], v[98:101]
	v_mfma_f32_16x16x32_bf16 v[90:93], v[158:161], v[200:203], v[90:93]
	v_mfma_f32_16x16x32_bf16 v[74:77], v[166:169], v[200:203], v[74:77]
	v_mfma_f32_16x16x32_bf16 v[134:137], v[162:165], v[178:181], v[134:137]
	v_mfma_f32_16x16x32_bf16 v[130:133], v[170:173], v[178:181], v[130:133]
	v_mfma_f32_16x16x32_bf16 v[122:125], v[162:165], v[186:189], v[122:125]
	v_mfma_f32_16x16x32_bf16 v[114:117], v[170:173], v[186:189], v[114:117]
	v_mfma_f32_16x16x32_bf16 v[106:109], v[162:165], v[196:199], v[106:109]
	v_mfma_f32_16x16x32_bf16 v[98:101], v[170:173], v[196:199], v[98:101]
	v_mfma_f32_16x16x32_bf16 v[90:93], v[162:165], v[204:207], v[90:93]
	v_mfma_f32_16x16x32_bf16 v[74:77], v[170:173], v[204:207], v[74:77]
	s_barrier
	s_add_i32 s56, s56, s41
	v_lshl_add_u64 v[154:155], s[42:43], 0, v[146:147]
	s_mov_b32 m0, s56
	ds_read_b128 v[174:177], v156 offset:16384
	ds_read_b128 v[178:181], v156 offset:17408
	ds_read_b128 v[182:185], v156 offset:18432
	ds_read_b128 v[186:189], v156 offset:19456
	ds_read_b128 v[192:195], v156 offset:20480
	ds_read_b128 v[196:199], v156 offset:21504
	ds_read_b128 v[200:203], v156 offset:22528
	ds_read_b128 v[204:207], v156 offset:23552
	global_load_lds_dwordx4 v[154:155], off
	s_add_i32 m0, s56, 0x2000
	s_add_u32 s56, s42, 0x80000
	v_lshl_add_u64 v[208:209], s[42:43], 0, v[148:149]
	s_addc_u32 s57, s43, 0
	s_add_i32 s40, s40, s41
	global_load_lds_dwordx4 v[208:209], off
	v_lshl_add_u64 v[210:211], s[56:57], 0, v[146:147]
	s_mov_b32 m0, s40
	v_lshl_add_u64 v[212:213], s[44:45], 0, v[148:149]
	global_load_lds_dwordx4 v[210:211], off
	v_lshl_add_u64 v[210:211], s[56:57], 0, v[148:149]
	s_add_i32 m0, s40, 0x2000
	s_nop 0
	global_load_lds_dwordx4 v[210:211], off
	v_lshl_add_u64 v[210:211], s[44:45], 0, v[146:147]
	s_mov_b32 m0, s29
	s_nop 0
	global_load_lds_dwordx4 v[210:211], off
	s_mov_b32 m0, s46
	s_nop 0
	global_load_lds_dwordx4 v[212:213], off
	s_waitcnt vmcnt(8)
	s_waitcnt lgkmcnt(0)
	s_barrier
	s_waitcnt lgkmcnt(0)
	v_mfma_f32_16x16x32_bf16 v[62:65], v[66:69], v[174:177], v[62:65]
	v_mfma_f32_16x16x32_bf16 v[54:57], v[78:81], v[174:177], v[54:57]
	v_mfma_f32_16x16x32_bf16 v[46:49], v[66:69], v[182:185], v[46:49]
	v_mfma_f32_16x16x32_bf16 v[38:41], v[78:81], v[182:185], v[38:41]
	v_mfma_f32_16x16x32_bf16 v[26:29], v[66:69], v[192:195], v[26:29]
	v_mfma_f32_16x16x32_bf16 v[18:21], v[78:81], v[192:195], v[18:21]
	v_mfma_f32_16x16x32_bf16 v[10:13], v[66:69], v[200:203], v[10:13]
	v_mfma_f32_16x16x32_bf16 v[2:5], v[78:81], v[200:203], v[2:5]
	v_mfma_f32_16x16x32_bf16 v[62:65], v[70:73], v[178:181], v[62:65]
	v_mfma_f32_16x16x32_bf16 v[54:57], v[82:85], v[178:181], v[54:57]
	v_mfma_f32_16x16x32_bf16 v[46:49], v[70:73], v[186:189], v[46:49]
	v_mfma_f32_16x16x32_bf16 v[38:41], v[82:85], v[186:189], v[38:41]
	v_mfma_f32_16x16x32_bf16 v[26:29], v[70:73], v[196:199], v[26:29]
	v_mfma_f32_16x16x32_bf16 v[18:21], v[82:85], v[196:199], v[18:21]
	v_mfma_f32_16x16x32_bf16 v[10:13], v[70:73], v[204:207], v[10:13]
	v_mfma_f32_16x16x32_bf16 v[2:5], v[82:85], v[204:207], v[2:5]
	v_mfma_f32_16x16x32_bf16 v[58:61], v[158:161], v[174:177], v[58:61]
	v_mfma_f32_16x16x32_bf16 v[50:53], v[166:169], v[174:177], v[50:53]
	v_mfma_f32_16x16x32_bf16 v[42:45], v[158:161], v[182:185], v[42:45]
	v_mfma_f32_16x16x32_bf16 v[34:37], v[166:169], v[182:185], v[34:37]
	v_mfma_f32_16x16x32_bf16 v[30:33], v[158:161], v[192:195], v[30:33]
	v_mfma_f32_16x16x32_bf16 v[22:25], v[166:169], v[192:195], v[22:25]
	v_mfma_f32_16x16x32_bf16 v[14:17], v[158:161], v[200:203], v[14:17]
	v_mfma_f32_16x16x32_bf16 v[6:9], v[166:169], v[200:203], v[6:9]
	v_mfma_f32_16x16x32_bf16 v[58:61], v[162:165], v[178:181], v[58:61]
	v_mfma_f32_16x16x32_bf16 v[50:53], v[170:173], v[178:181], v[50:53]
	v_mfma_f32_16x16x32_bf16 v[42:45], v[162:165], v[186:189], v[42:45]
	v_mfma_f32_16x16x32_bf16 v[34:37], v[170:173], v[186:189], v[34:37]
	v_mfma_f32_16x16x32_bf16 v[30:33], v[162:165], v[196:199], v[30:33]
	v_mfma_f32_16x16x32_bf16 v[22:25], v[170:173], v[196:199], v[22:25]
	v_mfma_f32_16x16x32_bf16 v[14:17], v[162:165], v[204:207], v[14:17]
	v_mfma_f32_16x16x32_bf16 v[6:9], v[170:173], v[204:207], v[6:9]
	s_barrier
	s_add_i32 s40, 0, 0x18000
	s_add_i32 s56, 0, 0x1c000
	v_add_u32_e32 v82, s40, v1
	v_add_u32_e32 v157, s56, v1
	ds_read_b128 v[66:69], v82
	ds_read_b128 v[70:73], v82 offset:1024
	ds_read_b128 v[78:81], v82 offset:2048
	ds_read_b128 v[82:85], v82 offset:3072
	ds_read_b128 v[158:161], v157
	ds_read_b128 v[162:165], v157 offset:1024
	ds_read_b128 v[166:169], v157 offset:2048
	ds_read_b128 v[170:173], v157 offset:3072
	s_add_u32 s44, s44, 0x80000
	s_addc_u32 s45, s45, 0
	s_mov_b32 m0, s47
	v_lshl_add_u64 v[214:215], s[44:45], 0, v[146:147]
	ds_read_b128 v[174:177], v156 offset:32768
	ds_read_b128 v[178:181], v156 offset:33792
	ds_read_b128 v[182:185], v156 offset:34816
	ds_read_b128 v[186:189], v156 offset:35840
	ds_read_b128 v[192:195], v156 offset:36864
	ds_read_b128 v[196:199], v156 offset:37888
	ds_read_b128 v[200:203], v156 offset:38912
	ds_read_b128 v[204:207], v156 offset:39936
	global_load_lds_dwordx4 v[214:215], off
	v_lshl_add_u64 v[214:215], s[44:45], 0, v[148:149]
	s_mov_b32 m0, s48
	s_nop 0
	global_load_lds_dwordx4 v[214:215], off
	s_waitcnt vmcnt(8)
	s_waitcnt lgkmcnt(0)
	s_barrier
	s_waitcnt lgkmcnt(0)
	v_mfma_f32_16x16x32_bf16 v[142:145], v[66:69], v[174:177], v[142:145]
	v_mfma_f32_16x16x32_bf16 v[138:141], v[78:81], v[174:177], v[138:141]
	v_mfma_f32_16x16x32_bf16 v[126:129], v[66:69], v[182:185], v[126:129]
	v_mfma_f32_16x16x32_bf16 v[118:121], v[78:81], v[182:185], v[118:121]
	v_mfma_f32_16x16x32_bf16 v[110:113], v[66:69], v[192:195], v[110:113]
	v_mfma_f32_16x16x32_bf16 v[102:105], v[78:81], v[192:195], v[102:105]
	v_mfma_f32_16x16x32_bf16 v[94:97], v[66:69], v[200:203], v[94:97]
	v_mfma_f32_16x16x32_bf16 v[86:89], v[78:81], v[200:203], v[86:89]
	v_mfma_f32_16x16x32_bf16 v[142:145], v[70:73], v[178:181], v[142:145]
	v_mfma_f32_16x16x32_bf16 v[138:141], v[82:85], v[178:181], v[138:141]
	v_mfma_f32_16x16x32_bf16 v[126:129], v[70:73], v[186:189], v[126:129]
	v_mfma_f32_16x16x32_bf16 v[118:121], v[82:85], v[186:189], v[118:121]
	v_mfma_f32_16x16x32_bf16 v[110:113], v[70:73], v[196:199], v[110:113]
	v_mfma_f32_16x16x32_bf16 v[102:105], v[82:85], v[196:199], v[102:105]
	v_mfma_f32_16x16x32_bf16 v[94:97], v[70:73], v[204:207], v[94:97]
	v_mfma_f32_16x16x32_bf16 v[86:89], v[82:85], v[204:207], v[86:89]
	v_mfma_f32_16x16x32_bf16 v[134:137], v[158:161], v[174:177], v[134:137]
	v_mfma_f32_16x16x32_bf16 v[130:133], v[166:169], v[174:177], v[130:133]
	v_mfma_f32_16x16x32_bf16 v[122:125], v[158:161], v[182:185], v[122:125]
	v_mfma_f32_16x16x32_bf16 v[114:117], v[166:169], v[182:185], v[114:117]
	v_mfma_f32_16x16x32_bf16 v[106:109], v[158:161], v[192:195], v[106:109]
	v_mfma_f32_16x16x32_bf16 v[98:101], v[166:169], v[192:195], v[98:101]
	v_mfma_f32_16x16x32_bf16 v[90:93], v[158:161], v[200:203], v[90:93]
	v_mfma_f32_16x16x32_bf16 v[74:77], v[166:169], v[200:203], v[74:77]
	v_mfma_f32_16x16x32_bf16 v[134:137], v[162:165], v[178:181], v[134:137]
	v_mfma_f32_16x16x32_bf16 v[130:133], v[170:173], v[178:181], v[130:133]
	v_mfma_f32_16x16x32_bf16 v[122:125], v[162:165], v[186:189], v[122:125]
	v_mfma_f32_16x16x32_bf16 v[114:117], v[170:173], v[186:189], v[114:117]
	v_mfma_f32_16x16x32_bf16 v[106:109], v[162:165], v[196:199], v[106:109]
	v_mfma_f32_16x16x32_bf16 v[98:101], v[170:173], v[196:199], v[98:101]
	v_mfma_f32_16x16x32_bf16 v[90:93], v[162:165], v[204:207], v[90:93]
	v_mfma_f32_16x16x32_bf16 v[74:77], v[170:173], v[204:207], v[74:77]
	s_barrier
	s_add_i32 s40, s40, s41
	v_lshl_add_u64 v[154:155], v[154:155], 0, s[36:37]
	s_mov_b32 m0, s40
	ds_read_b128 v[174:177], v156 offset:49152
	ds_read_b128 v[178:181], v156 offset:50176
	ds_read_b128 v[182:185], v156 offset:51200
	ds_read_b128 v[186:189], v156 offset:52224
	ds_read_b128 v[192:195], v156 offset:53248
	ds_read_b128 v[196:199], v156 offset:54272
	ds_read_b128 v[200:203], v156 offset:55296
	ds_read_b128 v[204:207], v156 offset:56320
	global_load_lds_dwordx4 v[154:155], off
	s_add_i32 m0, s40, 0x2000
	s_add_u32 s42, s42, 0x80080
	v_lshl_add_u64 v[154:155], v[208:209], 0, s[36:37]
	s_addc_u32 s43, s43, 0
	s_add_i32 s40, s56, s41
	global_load_lds_dwordx4 v[154:155], off
	v_lshl_add_u64 v[154:155], s[42:43], 0, v[146:147]
	s_mov_b32 m0, s40
	s_nop 0
	global_load_lds_dwordx4 v[154:155], off
	v_lshl_add_u64 v[154:155], s[42:43], 0, v[148:149]
	s_add_i32 m0, s40, 0x2000
	s_nop 0
	global_load_lds_dwordx4 v[154:155], off
	v_lshl_add_u64 v[154:155], v[210:211], 0, s[36:37]
	s_mov_b32 m0, s53
	s_nop 0
	global_load_lds_dwordx4 v[154:155], off
	v_lshl_add_u64 v[154:155], v[212:213], 0, s[36:37]
	s_mov_b32 m0, s54
	s_nop 0
	global_load_lds_dwordx4 v[154:155], off
	s_waitcnt vmcnt(8)
	s_waitcnt lgkmcnt(0)
	s_barrier
	s_waitcnt lgkmcnt(0)
	v_mfma_f32_16x16x32_bf16 v[62:65], v[66:69], v[174:177], v[62:65]
	v_mfma_f32_16x16x32_bf16 v[54:57], v[78:81], v[174:177], v[54:57]
	v_mfma_f32_16x16x32_bf16 v[46:49], v[66:69], v[182:185], v[46:49]
	v_mfma_f32_16x16x32_bf16 v[38:41], v[78:81], v[182:185], v[38:41]
	v_mfma_f32_16x16x32_bf16 v[26:29], v[66:69], v[192:195], v[26:29]
	v_mfma_f32_16x16x32_bf16 v[18:21], v[78:81], v[192:195], v[18:21]
	v_mfma_f32_16x16x32_bf16 v[10:13], v[66:69], v[200:203], v[10:13]
	v_mfma_f32_16x16x32_bf16 v[2:5], v[78:81], v[200:203], v[2:5]
	v_mfma_f32_16x16x32_bf16 v[62:65], v[70:73], v[178:181], v[62:65]
	v_mfma_f32_16x16x32_bf16 v[54:57], v[82:85], v[178:181], v[54:57]
	v_mfma_f32_16x16x32_bf16 v[46:49], v[70:73], v[186:189], v[46:49]
	v_mfma_f32_16x16x32_bf16 v[38:41], v[82:85], v[186:189], v[38:41]
	v_mfma_f32_16x16x32_bf16 v[26:29], v[70:73], v[196:199], v[26:29]
	v_mfma_f32_16x16x32_bf16 v[18:21], v[82:85], v[196:199], v[18:21]
	v_mfma_f32_16x16x32_bf16 v[10:13], v[70:73], v[204:207], v[10:13]
	v_mfma_f32_16x16x32_bf16 v[2:5], v[82:85], v[204:207], v[2:5]
	v_mfma_f32_16x16x32_bf16 v[58:61], v[158:161], v[174:177], v[58:61]
	v_mfma_f32_16x16x32_bf16 v[50:53], v[166:169], v[174:177], v[50:53]
	v_mfma_f32_16x16x32_bf16 v[42:45], v[158:161], v[182:185], v[42:45]
	v_mfma_f32_16x16x32_bf16 v[34:37], v[166:169], v[182:185], v[34:37]
	v_mfma_f32_16x16x32_bf16 v[30:33], v[158:161], v[192:195], v[30:33]
	v_mfma_f32_16x16x32_bf16 v[22:25], v[166:169], v[192:195], v[22:25]
	v_mfma_f32_16x16x32_bf16 v[14:17], v[158:161], v[200:203], v[14:17]
	v_mfma_f32_16x16x32_bf16 v[6:9], v[166:169], v[200:203], v[6:9]
	v_mfma_f32_16x16x32_bf16 v[58:61], v[162:165], v[178:181], v[58:61]
	v_mfma_f32_16x16x32_bf16 v[50:53], v[170:173], v[178:181], v[50:53]
	v_mfma_f32_16x16x32_bf16 v[42:45], v[162:165], v[186:189], v[42:45]
	v_mfma_f32_16x16x32_bf16 v[34:37], v[170:173], v[186:189], v[34:37]
	v_mfma_f32_16x16x32_bf16 v[30:33], v[162:165], v[196:199], v[30:33]
	v_mfma_f32_16x16x32_bf16 v[22:25], v[170:173], v[196:199], v[22:25]
	v_mfma_f32_16x16x32_bf16 v[14:17], v[162:165], v[204:207], v[14:17]
	v_mfma_f32_16x16x32_bf16 v[6:9], v[170:173], v[204:207], v[6:9]
	s_barrier
	s_add_i32 s38, s38, 2
	s_add_u32 s30, s30, 0x100
	s_addc_u32 s31, s31, 0
	s_add_u32 s23, s23, 0x100
	s_addc_u32 s26, s26, 0
	s_cmp_gt_u32 s38, 29
	s_cbranch_scc0 .LBB0_2960
	s_and_b64 vcc, exec, s[12:13]
	s_cbranch_vccz .LBB0_2963
	s_barrier

.LBB0_3450:
	s_add_u32 s6, s8, 0x100
	s_addc_u32 s7, s9, 0
	s_add_i32 s40, 0, 0x10000
	s_cmpk_eq_i32 s38, 0x54
	s_cselect_b32 s43, s23, s7
	s_cselect_b32 s42, s22, s6
	s_cselect_b32 s31, s29, s26
	s_cselect_b32 s30, s28, s20
	s_add_i32 s54, 0, 0x14000
	v_add_u32_e32 v62, s40, v1
	v_add_u32_e32 v78, s54, v1
	ds_read_b128 v[46:49], v62
	ds_read_b128 v[50:53], v62 offset:1024
	ds_read_b128 v[54:57], v62 offset:2048
	ds_read_b128 v[62:65], v62 offset:3072
	ds_read_b128 v[66:69], v78
	ds_read_b128 v[70:73], v78 offset:1024
	ds_read_b128 v[74:77], v78 offset:2048
	ds_read_b128 v[78:81], v78 offset:3072
	v_lshl_add_u64 v[202:203], s[8:9], 0, v[198:199]
	s_add_i32 m0, s44, 0xc000
	ds_read_b128 v[162:165], v242
	ds_read_b128 v[166:169], v242 offset:1024
	ds_read_b128 v[170:173], v242 offset:2048
	ds_read_b128 v[174:177], v242 offset:3072
	ds_read_b128 v[178:181], v242 offset:4096
	ds_read_b128 v[182:185], v242 offset:5120
	ds_read_b128 v[186:189], v242 offset:6144
	ds_read_b128 v[192:195], v242 offset:7168
	global_load_lds_dwordx4 v[202:203], off
	v_lshl_add_u64 v[202:203], s[8:9], 0, v[200:201]
	s_add_i32 m0, s44, 0xe000
	s_nop 0
	global_load_lds_dwordx4 v[202:203], off
	s_waitcnt vmcnt(8)
	s_waitcnt lgkmcnt(0)
	s_barrier
	s_waitcnt lgkmcnt(0)
	v_mfma_f32_16x16x32_bf16 v[158:161], v[46:49], v[162:165], v[158:161]
	v_mfma_f32_16x16x32_bf16 v[154:157], v[54:57], v[162:165], v[154:157]
	v_mfma_f32_16x16x32_bf16 v[142:145], v[46:49], v[170:173], v[142:145]
	v_mfma_f32_16x16x32_bf16 v[138:141], v[54:57], v[170:173], v[138:141]
	v_mfma_f32_16x16x32_bf16 v[126:129], v[46:49], v[178:181], v[126:129]
	v_mfma_f32_16x16x32_bf16 v[122:125], v[54:57], v[178:181], v[122:125]
	v_mfma_f32_16x16x32_bf16 v[110:113], v[46:49], v[186:189], v[110:113]
	v_mfma_f32_16x16x32_bf16 v[106:109], v[54:57], v[186:189], v[106:109]
	v_mfma_f32_16x16x32_bf16 v[158:161], v[50:53], v[166:169], v[158:161]
	v_mfma_f32_16x16x32_bf16 v[154:157], v[62:65], v[166:169], v[154:157]
	v_mfma_f32_16x16x32_bf16 v[142:145], v[50:53], v[174:177], v[142:145]
	v_mfma_f32_16x16x32_bf16 v[138:141], v[62:65], v[174:177], v[138:141]
	v_mfma_f32_16x16x32_bf16 v[126:129], v[50:53], v[182:185], v[126:129]
	v_mfma_f32_16x16x32_bf16 v[122:125], v[62:65], v[182:185], v[122:125]
	v_mfma_f32_16x16x32_bf16 v[110:113], v[50:53], v[192:195], v[110:113]
	v_mfma_f32_16x16x32_bf16 v[106:109], v[62:65], v[192:195], v[106:109]
	v_mfma_f32_16x16x32_bf16 v[150:153], v[66:69], v[162:165], v[150:153]
	v_mfma_f32_16x16x32_bf16 v[146:149], v[74:77], v[162:165], v[146:149]
	v_mfma_f32_16x16x32_bf16 v[134:137], v[66:69], v[170:173], v[134:137]
	v_mfma_f32_16x16x32_bf16 v[130:133], v[74:77], v[170:173], v[130:133]
	v_mfma_f32_16x16x32_bf16 v[118:121], v[66:69], v[178:181], v[118:121]
	v_mfma_f32_16x16x32_bf16 v[114:117], v[74:77], v[178:181], v[114:117]
	v_mfma_f32_16x16x32_bf16 v[102:105], v[66:69], v[186:189], v[102:105]
	v_mfma_f32_16x16x32_bf16 v[98:101], v[74:77], v[186:189], v[98:101]
	v_mfma_f32_16x16x32_bf16 v[150:153], v[70:73], v[166:169], v[150:153]
	v_mfma_f32_16x16x32_bf16 v[146:149], v[78:81], v[166:169], v[146:149]
	v_mfma_f32_16x16x32_bf16 v[134:137], v[70:73], v[174:177], v[134:137]
	v_mfma_f32_16x16x32_bf16 v[130:133], v[78:81], v[174:177], v[130:133]
	v_mfma_f32_16x16x32_bf16 v[118:121], v[70:73], v[182:185], v[118:121]
	v_mfma_f32_16x16x32_bf16 v[114:117], v[78:81], v[182:185], v[114:117]
	v_mfma_f32_16x16x32_bf16 v[102:105], v[70:73], v[192:195], v[102:105]
	v_mfma_f32_16x16x32_bf16 v[98:101], v[78:81], v[192:195], v[98:101]
	s_barrier
	s_add_i32 s8, s40, s41
	v_lshl_add_u64 v[206:207], s[30:31], 0, v[190:191]
	s_mov_b32 m0, s8
	ds_read_b128 v[162:165], v242 offset:16384
	ds_read_b128 v[166:169], v242 offset:17408
	ds_read_b128 v[170:173], v242 offset:18432
	ds_read_b128 v[174:177], v242 offset:19456
	ds_read_b128 v[178:181], v242 offset:20480
	ds_read_b128 v[182:185], v242 offset:21504
	ds_read_b128 v[186:189], v242 offset:22528
	ds_read_b128 v[192:195], v242 offset:23552
	global_load_lds_dwordx4 v[206:207], off
	s_add_i32 m0, s8, 0x2000
	s_add_u32 s8, s30, 0x160000
	v_lshl_add_u64 v[208:209], s[30:31], 0, v[196:197]
	s_addc_u32 s9, s31, 0
	s_add_i32 s40, s54, s41
	global_load_lds_dwordx4 v[208:209], off
	v_lshl_add_u64 v[202:203], s[8:9], 0, v[190:191]
	s_mov_b32 m0, s40
	v_lshl_add_u64 v[210:211], s[42:43], 0, v[190:191]
	global_load_lds_dwordx4 v[202:203], off
	v_lshl_add_u64 v[202:203], s[8:9], 0, v[196:197]
	s_add_i32 m0, s40, 0x2000
	v_lshl_add_u64 v[212:213], s[42:43], 0, v[196:197]
	global_load_lds_dwordx4 v[202:203], off
	s_mov_b32 m0, s44
	s_nop 0
	global_load_lds_dwordx4 v[210:211], off
	s_mov_b32 m0, s45
	s_nop 0
	global_load_lds_dwordx4 v[212:213], off
	s_waitcnt vmcnt(8)
	s_waitcnt lgkmcnt(0)
	s_barrier
	s_waitcnt lgkmcnt(0)
	v_mfma_f32_16x16x32_bf16 v[94:97], v[46:49], v[162:165], v[94:97]
	v_mfma_f32_16x16x32_bf16 v[90:93], v[54:57], v[162:165], v[90:93]
	v_mfma_f32_16x16x32_bf16 v[58:61], v[46:49], v[170:173], v[58:61]
	v_mfma_f32_16x16x32_bf16 v[42:45], v[54:57], v[170:173], v[42:45]
	v_mfma_f32_16x16x32_bf16 v[30:33], v[46:49], v[178:181], v[30:33]
	v_mfma_f32_16x16x32_bf16 v[18:21], v[54:57], v[178:181], v[18:21]
	v_mfma_f32_16x16x32_bf16 v[14:17], v[46:49], v[186:189], v[14:17]
	v_mfma_f32_16x16x32_bf16 v[2:5], v[54:57], v[186:189], v[2:5]
	v_mfma_f32_16x16x32_bf16 v[94:97], v[50:53], v[166:169], v[94:97]
	v_mfma_f32_16x16x32_bf16 v[90:93], v[62:65], v[166:169], v[90:93]
	v_mfma_f32_16x16x32_bf16 v[58:61], v[50:53], v[174:177], v[58:61]
	v_mfma_f32_16x16x32_bf16 v[42:45], v[62:65], v[174:177], v[42:45]
	v_mfma_f32_16x16x32_bf16 v[30:33], v[50:53], v[182:185], v[30:33]
	v_mfma_f32_16x16x32_bf16 v[18:21], v[62:65], v[182:185], v[18:21]
	v_mfma_f32_16x16x32_bf16 v[14:17], v[50:53], v[192:195], v[14:17]
	v_mfma_f32_16x16x32_bf16 v[2:5], v[62:65], v[192:195], v[2:5]
	v_mfma_f32_16x16x32_bf16 v[38:41], v[66:69], v[170:173], v[38:41]
	v_mfma_f32_16x16x32_bf16 v[34:37], v[74:77], v[170:173], v[34:37]
	v_mfma_f32_16x16x32_bf16 v[26:29], v[66:69], v[178:181], v[26:29]
	v_mfma_f32_16x16x32_bf16 v[22:25], v[74:77], v[178:181], v[22:25]
	v_mfma_f32_16x16x32_bf16 v[10:13], v[66:69], v[186:189], v[10:13]
	v_mfma_f32_16x16x32_bf16 v[6:9], v[74:77], v[186:189], v[6:9]
	v_mfma_f32_16x16x32_bf16 v[46:49], v[66:69], v[162:165], v[86:89]
	v_mfma_f32_16x16x32_bf16 v[50:53], v[74:77], v[162:165], v[82:85]
	v_mfma_f32_16x16x32_bf16 v[38:41], v[70:73], v[174:177], v[38:41]
	v_mfma_f32_16x16x32_bf16 v[34:37], v[78:81], v[174:177], v[34:37]
	v_mfma_f32_16x16x32_bf16 v[26:29], v[70:73], v[182:185], v[26:29]
	v_mfma_f32_16x16x32_bf16 v[22:25], v[78:81], v[182:185], v[22:25]
	v_mfma_f32_16x16x32_bf16 v[10:13], v[70:73], v[192:195], v[10:13]
	v_mfma_f32_16x16x32_bf16 v[6:9], v[78:81], v[192:195], v[6:9]
	v_mfma_f32_16x16x32_bf16 v[46:49], v[70:73], v[166:169], v[46:49]
	v_mfma_f32_16x16x32_bf16 v[50:53], v[78:81], v[166:169], v[50:53]
	s_barrier
	s_add_i32 s40, 0, 0x18000
	s_add_i32 s54, 0, 0x1c000
	v_add_u32_e32 v70, s40, v1
	v_add_u32_e32 v82, s54, v1
	ds_read_b128 v[54:57], v70
	ds_read_b128 v[62:65], v70 offset:1024
	ds_read_b128 v[66:69], v70 offset:2048
	ds_read_b128 v[70:73], v70 offset:3072
	ds_read_b128 v[74:77], v82
	ds_read_b128 v[78:81], v82 offset:1024
	ds_read_b128 v[162:165], v82 offset:2048
	ds_read_b128 v[166:169], v82 offset:3072
	s_add_u32 s8, s42, 0x160000
	s_addc_u32 s9, s43, 0
	s_mov_b32 m0, s46
	v_lshl_add_u64 v[202:203], s[8:9], 0, v[190:191]
	ds_read_b128 v[82:85], v242 offset:32768
	ds_read_b128 v[86:89], v242 offset:33792
	ds_read_b128 v[170:173], v242 offset:34816
	ds_read_b128 v[174:177], v242 offset:35840
	ds_read_b128 v[178:181], v242 offset:36864
	ds_read_b128 v[182:185], v242 offset:37888
	ds_read_b128 v[186:189], v242 offset:38912
	ds_read_b128 v[192:195], v242 offset:39936
	global_load_lds_dwordx4 v[202:203], off
	v_lshl_add_u64 v[202:203], s[8:9], 0, v[196:197]
	s_mov_b32 m0, s47
	s_nop 0
	global_load_lds_dwordx4 v[202:203], off
	s_waitcnt vmcnt(8)
	s_waitcnt lgkmcnt(0)
	s_barrier
	s_waitcnt lgkmcnt(0)
	v_mfma_f32_16x16x32_bf16 v[158:161], v[54:57], v[82:85], v[158:161]
	v_mfma_f32_16x16x32_bf16 v[154:157], v[66:69], v[82:85], v[154:157]
	v_mfma_f32_16x16x32_bf16 v[142:145], v[54:57], v[170:173], v[142:145]
	v_mfma_f32_16x16x32_bf16 v[138:141], v[66:69], v[170:173], v[138:141]
	v_mfma_f32_16x16x32_bf16 v[126:129], v[54:57], v[178:181], v[126:129]
	v_mfma_f32_16x16x32_bf16 v[122:125], v[66:69], v[178:181], v[122:125]
	v_mfma_f32_16x16x32_bf16 v[110:113], v[54:57], v[186:189], v[110:113]
	v_mfma_f32_16x16x32_bf16 v[106:109], v[66:69], v[186:189], v[106:109]
	v_mfma_f32_16x16x32_bf16 v[158:161], v[62:65], v[86:89], v[158:161]
	v_mfma_f32_16x16x32_bf16 v[154:157], v[70:73], v[86:89], v[154:157]
	v_mfma_f32_16x16x32_bf16 v[142:145], v[62:65], v[174:177], v[142:145]
	v_mfma_f32_16x16x32_bf16 v[138:141], v[70:73], v[174:177], v[138:141]
	v_mfma_f32_16x16x32_bf16 v[126:129], v[62:65], v[182:185], v[126:129]
	v_mfma_f32_16x16x32_bf16 v[122:125], v[70:73], v[182:185], v[122:125]
	v_mfma_f32_16x16x32_bf16 v[110:113], v[62:65], v[192:195], v[110:113]
	v_mfma_f32_16x16x32_bf16 v[106:109], v[70:73], v[192:195], v[106:109]
	v_mfma_f32_16x16x32_bf16 v[150:153], v[74:77], v[82:85], v[150:153]
	v_mfma_f32_16x16x32_bf16 v[82:85], v[162:165], v[82:85], v[146:149]
	v_mfma_f32_16x16x32_bf16 v[146:149], v[166:169], v[86:89], v[82:85]
	v_mfma_f32_16x16x32_bf16 v[82:85], v[74:77], v[170:173], v[134:137]
	v_mfma_f32_16x16x32_bf16 v[134:137], v[78:81], v[174:177], v[82:85]
	v_mfma_f32_16x16x32_bf16 v[82:85], v[162:165], v[170:173], v[130:133]
	v_mfma_f32_16x16x32_bf16 v[130:133], v[166:169], v[174:177], v[82:85]
	v_mfma_f32_16x16x32_bf16 v[82:85], v[74:77], v[178:181], v[118:121]
	v_mfma_f32_16x16x32_bf16 v[118:121], v[78:81], v[182:185], v[82:85]
	v_mfma_f32_16x16x32_bf16 v[82:85], v[162:165], v[178:181], v[114:117]
	v_mfma_f32_16x16x32_bf16 v[114:117], v[166:169], v[182:185], v[82:85]
	v_mfma_f32_16x16x32_bf16 v[82:85], v[74:77], v[186:189], v[102:105]
	v_mfma_f32_16x16x32_bf16 v[102:105], v[78:81], v[192:195], v[82:85]
	v_mfma_f32_16x16x32_bf16 v[82:85], v[162:165], v[186:189], v[98:101]
	v_mfma_f32_16x16x32_bf16 v[150:153], v[78:81], v[86:89], v[150:153]
	v_mfma_f32_16x16x32_bf16 v[98:101], v[166:169], v[192:195], v[82:85]
	s_barrier
	s_add_i32 s8, s40, s41
	v_lshl_add_u64 v[86:87], v[206:207], 0, s[36:37]
	s_mov_b32 m0, s8
	s_nop 0
	ds_read_b128 v[82:85], v242 offset:49152
	ds_read_b128 v[170:173], v242 offset:50176
	ds_read_b128 v[174:177], v242 offset:51200
	ds_read_b128 v[178:181], v242 offset:52224
	ds_read_b128 v[182:185], v242 offset:53248
	ds_read_b128 v[186:189], v242 offset:54272
	ds_read_b128 v[192:195], v242 offset:55296
	ds_read_b128 v[202:205], v242 offset:56320
	global_load_lds_dwordx4 v[86:87], off
	s_add_i32 m0, s8, 0x2000
	s_add_u32 s8, s30, 0x160080
	v_lshl_add_u64 v[86:87], v[208:209], 0, s[36:37]
	s_addc_u32 s9, s31, 0
	s_add_i32 s30, s54, s41
	global_load_lds_dwordx4 v[86:87], off
	v_lshl_add_u64 v[86:87], s[8:9], 0, v[190:191]
	s_mov_b32 m0, s30
	s_nop 0
	global_load_lds_dwordx4 v[86:87], off
	v_lshl_add_u64 v[86:87], s[8:9], 0, v[196:197]
	s_add_i32 m0, s30, 0x2000
	s_nop 0
	global_load_lds_dwordx4 v[86:87], off
	v_lshl_add_u64 v[86:87], v[210:211], 0, s[36:37]
	s_mov_b32 m0, s50
	s_nop 0
	global_load_lds_dwordx4 v[86:87], off
	v_lshl_add_u64 v[86:87], v[212:213], 0, s[36:37]
	s_mov_b32 m0, s51
	s_nop 0
	global_load_lds_dwordx4 v[86:87], off
	s_waitcnt vmcnt(8)
	s_waitcnt lgkmcnt(0)
	s_barrier
	s_waitcnt lgkmcnt(0)
	v_mfma_f32_16x16x32_bf16 v[86:89], v[54:57], v[82:85], v[94:97]
	v_mfma_f32_16x16x32_bf16 v[94:97], v[62:65], v[170:173], v[86:89]
	v_mfma_f32_16x16x32_bf16 v[86:89], v[66:69], v[82:85], v[90:93]
	v_mfma_f32_16x16x32_bf16 v[58:61], v[54:57], v[174:177], v[58:61]
	v_mfma_f32_16x16x32_bf16 v[42:45], v[66:69], v[174:177], v[42:45]
	v_mfma_f32_16x16x32_bf16 v[30:33], v[54:57], v[182:185], v[30:33]
	v_mfma_f32_16x16x32_bf16 v[18:21], v[66:69], v[182:185], v[18:21]
	v_mfma_f32_16x16x32_bf16 v[14:17], v[54:57], v[192:195], v[14:17]
	v_mfma_f32_16x16x32_bf16 v[2:5], v[66:69], v[192:195], v[2:5]
	v_mfma_f32_16x16x32_bf16 v[90:93], v[70:73], v[170:173], v[86:89]
	v_mfma_f32_16x16x32_bf16 v[58:61], v[62:65], v[178:181], v[58:61]
	v_mfma_f32_16x16x32_bf16 v[42:45], v[70:73], v[178:181], v[42:45]
	v_mfma_f32_16x16x32_bf16 v[30:33], v[62:65], v[186:189], v[30:33]
	v_mfma_f32_16x16x32_bf16 v[18:21], v[70:73], v[186:189], v[18:21]
	v_mfma_f32_16x16x32_bf16 v[14:17], v[62:65], v[202:205], v[14:17]
	v_mfma_f32_16x16x32_bf16 v[2:5], v[70:73], v[202:205], v[2:5]
	v_mfma_f32_16x16x32_bf16 v[46:49], v[74:77], v[82:85], v[46:49]
	v_mfma_f32_16x16x32_bf16 v[86:89], v[78:81], v[170:173], v[46:49]
	v_mfma_f32_16x16x32_bf16 v[46:49], v[162:165], v[82:85], v[50:53]
	v_mfma_f32_16x16x32_bf16 v[38:41], v[74:77], v[174:177], v[38:41]
	v_mfma_f32_16x16x32_bf16 v[34:37], v[162:165], v[174:177], v[34:37]
	v_mfma_f32_16x16x32_bf16 v[26:29], v[74:77], v[182:185], v[26:29]
	v_mfma_f32_16x16x32_bf16 v[22:25], v[162:165], v[182:185], v[22:25]
	v_mfma_f32_16x16x32_bf16 v[10:13], v[74:77], v[192:195], v[10:13]
	v_mfma_f32_16x16x32_bf16 v[6:9], v[162:165], v[192:195], v[6:9]
	v_mfma_f32_16x16x32_bf16 v[82:85], v[166:169], v[170:173], v[46:49]
	v_mfma_f32_16x16x32_bf16 v[38:41], v[78:81], v[178:181], v[38:41]
	v_mfma_f32_16x16x32_bf16 v[34:37], v[166:169], v[178:181], v[34:37]
	v_mfma_f32_16x16x32_bf16 v[26:29], v[78:81], v[186:189], v[26:29]
	v_mfma_f32_16x16x32_bf16 v[22:25], v[166:169], v[186:189], v[22:25]
	v_mfma_f32_16x16x32_bf16 v[10:13], v[78:81], v[202:205], v[10:13]
	v_mfma_f32_16x16x32_bf16 v[6:9], v[166:169], v[202:205], v[6:9]
	s_barrier
	s_add_i32 s38, s38, 2
	s_add_u32 s20, s20, 0x100
	s_addc_u32 s26, s26, 0
	s_cmpk_gt_u32 s38, 0x55
	s_mov_b64 s[8:9], s[6:7]
	s_cbranch_scc0 .LBB0_3450
	s_and_b64 vcc, exec, s[16:17]
	s_cbranch_vccz .LBB0_3453
	s_barrier

.LBB0_3533:
	s_add_u32 s16, s14, 0x100
	s_addc_u32 s17, s15, 0
	s_add_i32 s48, 0, 0x10000
	s_cmp_eq_u32 s40, 18
	s_cselect_b32 s23, s11, s17
	s_cselect_b32 s22, s10, s16
	v_add_u32_e32 v144, s48, v1
	s_cselect_b32 s19, s13, s38
	s_cselect_b32 s18, s12, s26
	s_add_i32 s49, 0, 0x14000
	ds_read_b128 v[130:133], v144
	ds_read_b128 v[140:143], v144 offset:1024
	ds_read_b128 v[148:151], v144 offset:2048
	ds_read_b128 v[152:155], v144 offset:3072
	v_add_u32_e32 v144, s49, v1
	ds_read_b128 v[156:159], v144
	ds_read_b128 v[160:163], v144 offset:1024
	ds_read_b128 v[164:167], v144 offset:2048
	ds_read_b128 v[168:171], v144 offset:3072
	v_lshl_add_u64 v[144:145], s[14:15], 0, v[136:137]
	s_add_i32 m0, s29, 0xc000
	ds_read_b128 v[172:175], v146
	ds_read_b128 v[176:179], v146 offset:1024
	ds_read_b128 v[180:183], v146 offset:2048
	ds_read_b128 v[184:187], v146 offset:3072
	ds_read_b128 v[192:195], v146 offset:4096
	ds_read_b128 v[196:199], v146 offset:5120
	ds_read_b128 v[200:203], v146 offset:6144
	ds_read_b128 v[204:207], v146 offset:7168
	global_load_lds_dwordx4 v[144:145], off
	v_lshl_add_u64 v[144:145], s[14:15], 0, v[138:139]
	s_add_i32 m0, s29, 0xe000
	s_nop 0
	global_load_lds_dwordx4 v[144:145], off
	s_waitcnt vmcnt(8)
	s_waitcnt lgkmcnt(0)
	s_barrier
	s_waitcnt lgkmcnt(0)
	v_mfma_f32_16x16x32_bf16 v[126:129], v[130:133], v[172:175], v[126:129]
	v_mfma_f32_16x16x32_bf16 v[102:105], v[148:151], v[172:175], v[102:105]
	v_mfma_f32_16x16x32_bf16 v[122:125], v[130:133], v[180:183], v[122:125]
	v_mfma_f32_16x16x32_bf16 v[94:97], v[148:151], v[180:183], v[94:97]
	v_mfma_f32_16x16x32_bf16 v[118:121], v[130:133], v[192:195], v[118:121]
	v_mfma_f32_16x16x32_bf16 v[86:89], v[148:151], v[192:195], v[86:89]
	v_mfma_f32_16x16x32_bf16 v[114:117], v[130:133], v[200:203], v[114:117]
	v_mfma_f32_16x16x32_bf16 v[82:85], v[148:151], v[200:203], v[82:85]
	v_mfma_f32_16x16x32_bf16 v[126:129], v[140:143], v[176:179], v[126:129]
	v_mfma_f32_16x16x32_bf16 v[102:105], v[152:155], v[176:179], v[102:105]
	v_mfma_f32_16x16x32_bf16 v[122:125], v[140:143], v[184:187], v[122:125]
	v_mfma_f32_16x16x32_bf16 v[94:97], v[152:155], v[184:187], v[94:97]
	v_mfma_f32_16x16x32_bf16 v[118:121], v[140:143], v[196:199], v[118:121]
	v_mfma_f32_16x16x32_bf16 v[86:89], v[152:155], v[196:199], v[86:89]
	v_mfma_f32_16x16x32_bf16 v[114:117], v[140:143], v[204:207], v[114:117]
	v_mfma_f32_16x16x32_bf16 v[82:85], v[152:155], v[204:207], v[82:85]
	v_mfma_f32_16x16x32_bf16 v[70:73], v[156:159], v[172:175], v[70:73]
	v_mfma_f32_16x16x32_bf16 v[30:33], v[164:167], v[172:175], v[30:33]
	v_mfma_f32_16x16x32_bf16 v[62:65], v[156:159], v[180:183], v[62:65]
	v_mfma_f32_16x16x32_bf16 v[26:29], v[164:167], v[180:183], v[26:29]
	v_mfma_f32_16x16x32_bf16 v[54:57], v[156:159], v[192:195], v[54:57]
	v_mfma_f32_16x16x32_bf16 v[22:25], v[164:167], v[192:195], v[22:25]
	v_mfma_f32_16x16x32_bf16 v[50:53], v[156:159], v[200:203], v[50:53]
	v_mfma_f32_16x16x32_bf16 v[18:21], v[164:167], v[200:203], v[18:21]
	v_mfma_f32_16x16x32_bf16 v[70:73], v[160:163], v[176:179], v[70:73]
	v_mfma_f32_16x16x32_bf16 v[30:33], v[168:171], v[176:179], v[30:33]
	v_mfma_f32_16x16x32_bf16 v[62:65], v[160:163], v[184:187], v[62:65]
	v_mfma_f32_16x16x32_bf16 v[26:29], v[168:171], v[184:187], v[26:29]
	v_mfma_f32_16x16x32_bf16 v[54:57], v[160:163], v[196:199], v[54:57]
	v_mfma_f32_16x16x32_bf16 v[22:25], v[168:171], v[196:199], v[22:25]
	v_mfma_f32_16x16x32_bf16 v[50:53], v[160:163], v[204:207], v[50:53]
	v_mfma_f32_16x16x32_bf16 v[18:21], v[168:171], v[204:207], v[18:21]
	s_barrier
	s_add_i32 s14, s48, s28
	v_lshl_add_u64 v[144:145], s[18:19], 0, v[190:191]
	s_mov_b32 m0, s14
	ds_read_b128 v[172:175], v146 offset:16384
	ds_read_b128 v[176:179], v146 offset:17408
	ds_read_b128 v[180:183], v146 offset:18432
	ds_read_b128 v[184:187], v146 offset:19456
	ds_read_b128 v[192:195], v146 offset:20480
	ds_read_b128 v[196:199], v146 offset:21504
	ds_read_b128 v[200:203], v146 offset:22528
	ds_read_b128 v[204:207], v146 offset:23552
	global_load_lds_dwordx4 v[144:145], off
	s_add_i32 m0, s14, 0x2000
	s_add_u32 s14, s18, 0x160000
	v_lshl_add_u64 v[188:189], s[18:19], 0, v[134:135]
	s_addc_u32 s15, s19, 0
	s_add_i32 s48, s49, s28
	global_load_lds_dwordx4 v[188:189], off
	v_lshl_add_u64 v[208:209], s[14:15], 0, v[190:191]
	s_mov_b32 m0, s48
	v_lshl_add_u64 v[210:211], s[22:23], 0, v[134:135]
	global_load_lds_dwordx4 v[208:209], off
	v_lshl_add_u64 v[208:209], s[14:15], 0, v[134:135]
	s_add_i32 m0, s48, 0x2000
	s_nop 0
	global_load_lds_dwordx4 v[208:209], off
	v_lshl_add_u64 v[208:209], s[22:23], 0, v[190:191]
	s_mov_b32 m0, s29
	s_nop 0
	global_load_lds_dwordx4 v[208:209], off
	s_mov_b32 m0, s30
	s_nop 0
	global_load_lds_dwordx4 v[210:211], off
	s_waitcnt vmcnt(8)
	s_waitcnt lgkmcnt(0)
	s_barrier
	s_waitcnt lgkmcnt(0)
	v_mfma_f32_16x16x32_bf16 v[110:113], v[130:133], v[172:175], v[110:113]
	v_mfma_f32_16x16x32_bf16 v[78:81], v[148:151], v[172:175], v[78:81]
	v_mfma_f32_16x16x32_bf16 v[106:109], v[130:133], v[180:183], v[106:109]
	v_mfma_f32_16x16x32_bf16 v[74:77], v[148:151], v[180:183], v[74:77]
	v_mfma_f32_16x16x32_bf16 v[98:101], v[130:133], v[192:195], v[98:101]
	v_mfma_f32_16x16x32_bf16 v[66:69], v[148:151], v[192:195], v[66:69]
	v_mfma_f32_16x16x32_bf16 v[90:93], v[130:133], v[200:203], v[90:93]
	v_mfma_f32_16x16x32_bf16 v[58:61], v[148:151], v[200:203], v[58:61]
	v_mfma_f32_16x16x32_bf16 v[110:113], v[140:143], v[176:179], v[110:113]
	v_mfma_f32_16x16x32_bf16 v[78:81], v[152:155], v[176:179], v[78:81]
	v_mfma_f32_16x16x32_bf16 v[106:109], v[140:143], v[184:187], v[106:109]
	v_mfma_f32_16x16x32_bf16 v[74:77], v[152:155], v[184:187], v[74:77]
	v_mfma_f32_16x16x32_bf16 v[98:101], v[140:143], v[196:199], v[98:101]
	v_mfma_f32_16x16x32_bf16 v[66:69], v[152:155], v[196:199], v[66:69]
	v_mfma_f32_16x16x32_bf16 v[90:93], v[140:143], v[204:207], v[90:93]
	v_mfma_f32_16x16x32_bf16 v[58:61], v[152:155], v[204:207], v[58:61]
	v_mfma_f32_16x16x32_bf16 v[38:41], v[156:159], v[172:175], v[38:41]
	v_mfma_f32_16x16x32_bf16 v[10:13], v[164:167], v[172:175], v[10:13]
	v_mfma_f32_16x16x32_bf16 v[34:37], v[156:159], v[180:183], v[34:37]
	v_mfma_f32_16x16x32_bf16 v[6:9], v[164:167], v[180:183], v[6:9]
	v_mfma_f32_16x16x32_bf16 v[46:49], v[156:159], v[192:195], v[46:49]
	v_mfma_f32_16x16x32_bf16 v[14:17], v[164:167], v[192:195], v[14:17]
	v_mfma_f32_16x16x32_bf16 v[42:45], v[156:159], v[200:203], v[42:45]
	v_mfma_f32_16x16x32_bf16 v[2:5], v[164:167], v[200:203], v[2:5]
	v_mfma_f32_16x16x32_bf16 v[38:41], v[160:163], v[176:179], v[38:41]
	v_mfma_f32_16x16x32_bf16 v[10:13], v[168:171], v[176:179], v[10:13]
	v_mfma_f32_16x16x32_bf16 v[34:37], v[160:163], v[184:187], v[34:37]
	v_mfma_f32_16x16x32_bf16 v[6:9], v[168:171], v[184:187], v[6:9]
	v_mfma_f32_16x16x32_bf16 v[46:49], v[160:163], v[196:199], v[46:49]
	v_mfma_f32_16x16x32_bf16 v[14:17], v[168:171], v[196:199], v[14:17]
	v_mfma_f32_16x16x32_bf16 v[42:45], v[160:163], v[204:207], v[42:45]
	v_mfma_f32_16x16x32_bf16 v[2:5], v[168:171], v[204:207], v[2:5]
	s_barrier
	s_add_i32 s48, 0, 0x18000
	v_add_u32_e32 v147, s48, v1
	s_add_i32 s49, 0, 0x1c000
	ds_read_b128 v[130:133], v147
	ds_read_b128 v[140:143], v147 offset:1024
	ds_read_b128 v[148:151], v147 offset:2048
	ds_read_b128 v[152:155], v147 offset:3072
	v_add_u32_e32 v147, s49, v1
	ds_read_b128 v[156:159], v147
	ds_read_b128 v[160:163], v147 offset:1024
	ds_read_b128 v[164:167], v147 offset:2048
	ds_read_b128 v[168:171], v147 offset:3072
	s_add_u32 s14, s22, 0x160000
	s_addc_u32 s15, s23, 0
	s_mov_b32 m0, s31
	v_lshl_add_u64 v[212:213], s[14:15], 0, v[190:191]
	ds_read_b128 v[172:175], v146 offset:32768
	ds_read_b128 v[176:179], v146 offset:33792
	ds_read_b128 v[180:183], v146 offset:34816
	ds_read_b128 v[184:187], v146 offset:35840
	ds_read_b128 v[192:195], v146 offset:36864
	ds_read_b128 v[196:199], v146 offset:37888
	ds_read_b128 v[200:203], v146 offset:38912
	ds_read_b128 v[204:207], v146 offset:39936
	global_load_lds_dwordx4 v[212:213], off
	v_lshl_add_u64 v[212:213], s[14:15], 0, v[134:135]
	s_mov_b32 m0, s41
	s_nop 0
	global_load_lds_dwordx4 v[212:213], off
	s_waitcnt vmcnt(8)
	s_waitcnt lgkmcnt(0)
	s_barrier
	s_waitcnt lgkmcnt(0)
	v_mfma_f32_16x16x32_bf16 v[126:129], v[130:133], v[172:175], v[126:129]
	v_mfma_f32_16x16x32_bf16 v[102:105], v[148:151], v[172:175], v[102:105]
	v_mfma_f32_16x16x32_bf16 v[122:125], v[130:133], v[180:183], v[122:125]
	v_mfma_f32_16x16x32_bf16 v[94:97], v[148:151], v[180:183], v[94:97]
	v_mfma_f32_16x16x32_bf16 v[118:121], v[130:133], v[192:195], v[118:121]
	v_mfma_f32_16x16x32_bf16 v[86:89], v[148:151], v[192:195], v[86:89]
	v_mfma_f32_16x16x32_bf16 v[114:117], v[130:133], v[200:203], v[114:117]
	v_mfma_f32_16x16x32_bf16 v[82:85], v[148:151], v[200:203], v[82:85]
	v_mfma_f32_16x16x32_bf16 v[126:129], v[140:143], v[176:179], v[126:129]
	v_mfma_f32_16x16x32_bf16 v[102:105], v[152:155], v[176:179], v[102:105]
	v_mfma_f32_16x16x32_bf16 v[122:125], v[140:143], v[184:187], v[122:125]
	v_mfma_f32_16x16x32_bf16 v[94:97], v[152:155], v[184:187], v[94:97]
	v_mfma_f32_16x16x32_bf16 v[118:121], v[140:143], v[196:199], v[118:121]
	v_mfma_f32_16x16x32_bf16 v[86:89], v[152:155], v[196:199], v[86:89]
	v_mfma_f32_16x16x32_bf16 v[114:117], v[140:143], v[204:207], v[114:117]
	v_mfma_f32_16x16x32_bf16 v[82:85], v[152:155], v[204:207], v[82:85]
	v_mfma_f32_16x16x32_bf16 v[70:73], v[156:159], v[172:175], v[70:73]
	v_mfma_f32_16x16x32_bf16 v[30:33], v[164:167], v[172:175], v[30:33]
	v_mfma_f32_16x16x32_bf16 v[62:65], v[156:159], v[180:183], v[62:65]
	v_mfma_f32_16x16x32_bf16 v[26:29], v[164:167], v[180:183], v[26:29]
	v_mfma_f32_16x16x32_bf16 v[54:57], v[156:159], v[192:195], v[54:57]
	v_mfma_f32_16x16x32_bf16 v[22:25], v[164:167], v[192:195], v[22:25]
	v_mfma_f32_16x16x32_bf16 v[50:53], v[156:159], v[200:203], v[50:53]
	v_mfma_f32_16x16x32_bf16 v[18:21], v[164:167], v[200:203], v[18:21]
	v_mfma_f32_16x16x32_bf16 v[70:73], v[160:163], v[176:179], v[70:73]
	v_mfma_f32_16x16x32_bf16 v[30:33], v[168:171], v[176:179], v[30:33]
	v_mfma_f32_16x16x32_bf16 v[62:65], v[160:163], v[184:187], v[62:65]
	v_mfma_f32_16x16x32_bf16 v[26:29], v[168:171], v[184:187], v[26:29]
	v_mfma_f32_16x16x32_bf16 v[54:57], v[160:163], v[196:199], v[54:57]
	v_mfma_f32_16x16x32_bf16 v[22:25], v[168:171], v[196:199], v[22:25]
	v_mfma_f32_16x16x32_bf16 v[50:53], v[160:163], v[204:207], v[50:53]
	v_mfma_f32_16x16x32_bf16 v[18:21], v[168:171], v[204:207], v[18:21]
	s_barrier
	s_add_i32 s14, s48, s28
	v_lshl_add_u64 v[144:145], v[144:145], 0, s[36:37]
	s_mov_b32 m0, s14
	ds_read_b128 v[172:175], v146 offset:49152
	ds_read_b128 v[176:179], v146 offset:50176
	ds_read_b128 v[180:183], v146 offset:51200
	ds_read_b128 v[184:187], v146 offset:52224
	ds_read_b128 v[192:195], v146 offset:53248
	ds_read_b128 v[196:199], v146 offset:54272
	ds_read_b128 v[200:203], v146 offset:55296
	ds_read_b128 v[204:207], v146 offset:56320
	global_load_lds_dwordx4 v[144:145], off
	s_add_i32 m0, s14, 0x2000
	s_add_u32 s14, s18, 0x160080
	v_lshl_add_u64 v[144:145], v[188:189], 0, s[36:37]
	s_addc_u32 s15, s19, 0
	s_add_i32 s18, s49, s28
	global_load_lds_dwordx4 v[144:145], off
	v_lshl_add_u64 v[144:145], s[14:15], 0, v[190:191]
	s_mov_b32 m0, s18
	s_nop 0
	global_load_lds_dwordx4 v[144:145], off
	v_lshl_add_u64 v[144:145], s[14:15], 0, v[134:135]
	s_add_i32 m0, s18, 0x2000
	s_nop 0
	global_load_lds_dwordx4 v[144:145], off
	v_lshl_add_u64 v[144:145], v[208:209], 0, s[36:37]
	s_mov_b32 m0, s44
	s_nop 0
	global_load_lds_dwordx4 v[144:145], off
	v_lshl_add_u64 v[144:145], v[210:211], 0, s[36:37]
	s_mov_b32 m0, s45
	s_nop 0
	global_load_lds_dwordx4 v[144:145], off
	s_waitcnt vmcnt(8)
	s_waitcnt lgkmcnt(0)
	s_barrier
	s_waitcnt lgkmcnt(0)
	v_mfma_f32_16x16x32_bf16 v[110:113], v[130:133], v[172:175], v[110:113]
	v_mfma_f32_16x16x32_bf16 v[78:81], v[148:151], v[172:175], v[78:81]
	v_mfma_f32_16x16x32_bf16 v[106:109], v[130:133], v[180:183], v[106:109]
	v_mfma_f32_16x16x32_bf16 v[74:77], v[148:151], v[180:183], v[74:77]
	v_mfma_f32_16x16x32_bf16 v[98:101], v[130:133], v[192:195], v[98:101]
	v_mfma_f32_16x16x32_bf16 v[66:69], v[148:151], v[192:195], v[66:69]
	v_mfma_f32_16x16x32_bf16 v[90:93], v[130:133], v[200:203], v[90:93]
	v_mfma_f32_16x16x32_bf16 v[58:61], v[148:151], v[200:203], v[58:61]
	v_mfma_f32_16x16x32_bf16 v[110:113], v[140:143], v[176:179], v[110:113]
	v_mfma_f32_16x16x32_bf16 v[78:81], v[152:155], v[176:179], v[78:81]
	v_mfma_f32_16x16x32_bf16 v[106:109], v[140:143], v[184:187], v[106:109]
	v_mfma_f32_16x16x32_bf16 v[74:77], v[152:155], v[184:187], v[74:77]
	v_mfma_f32_16x16x32_bf16 v[98:101], v[140:143], v[196:199], v[98:101]
	v_mfma_f32_16x16x32_bf16 v[66:69], v[152:155], v[196:199], v[66:69]
	v_mfma_f32_16x16x32_bf16 v[90:93], v[140:143], v[204:207], v[90:93]
	v_mfma_f32_16x16x32_bf16 v[58:61], v[152:155], v[204:207], v[58:61]
	v_mfma_f32_16x16x32_bf16 v[38:41], v[156:159], v[172:175], v[38:41]
	v_mfma_f32_16x16x32_bf16 v[10:13], v[164:167], v[172:175], v[10:13]
	v_mfma_f32_16x16x32_bf16 v[34:37], v[156:159], v[180:183], v[34:37]
	v_mfma_f32_16x16x32_bf16 v[6:9], v[164:167], v[180:183], v[6:9]
	v_mfma_f32_16x16x32_bf16 v[46:49], v[156:159], v[192:195], v[46:49]
	v_mfma_f32_16x16x32_bf16 v[14:17], v[164:167], v[192:195], v[14:17]
	v_mfma_f32_16x16x32_bf16 v[42:45], v[156:159], v[200:203], v[42:45]
	v_mfma_f32_16x16x32_bf16 v[2:5], v[164:167], v[200:203], v[2:5]
	v_mfma_f32_16x16x32_bf16 v[38:41], v[160:163], v[176:179], v[38:41]
	v_mfma_f32_16x16x32_bf16 v[10:13], v[168:171], v[176:179], v[10:13]
	v_mfma_f32_16x16x32_bf16 v[34:37], v[160:163], v[184:187], v[34:37]
	v_mfma_f32_16x16x32_bf16 v[6:9], v[168:171], v[184:187], v[6:9]
	v_mfma_f32_16x16x32_bf16 v[46:49], v[160:163], v[196:199], v[46:49]
	v_mfma_f32_16x16x32_bf16 v[14:17], v[168:171], v[196:199], v[14:17]
	v_mfma_f32_16x16x32_bf16 v[42:45], v[160:163], v[204:207], v[42:45]
	v_mfma_f32_16x16x32_bf16 v[2:5], v[168:171], v[204:207], v[2:5]
	s_barrier
	s_add_i32 s40, s40, 2
	s_add_u32 s26, s26, 0x100
	s_addc_u32 s38, s38, 0
	s_cmp_gt_u32 s40, 19
	s_mov_b64 s[14:15], s[16:17]
	s_cbranch_scc0 .LBB0_3533
	s_and_b64 vcc, exec, s[8:9]
	s_cbranch_vccz .LBB0_3536
	s_barrier
